# one s_setprio 1 for waves 4-7 at kernel entry; the per-tile raise blocks in front of the K-loops deleted
# baseline (speedup 1.0000x reference)
_Z4mega6Params:
	s_mov_b64 s[80:81], s[0:1]
	v_readfirstlane_b32 s98, v0
	s_and_b32 s98, s98, 0x3ff
	s_lshr_b32 s98, s98, 8
	s_cmp_eq_u32 s98, 0
	s_cbranch_scc1 .Lkprio_entry
	s_setprio 1
.Lkprio_entry:
	s_load_dwordx2 s[82:83], s[80:81], 0x100
	v_and_b32_e32 v188, 0x3ff, v0
	s_mov_b32 s69, s2
	v_cmp_eq_u32_e64 s[74:75], 0, v188
	s_and_saveexec_b64 s[2:3], s[74:75]
	s_cbranch_execz .LBB0_2
	s_add_i32 s4, 0, 0x20000
	v_mov_b32_e32 v1, 0
	v_mov_b32_e32 v2, s4
	s_add_i32 s4, 0, 0x20004
	ds_write_b32 v2, v1
	v_mov_b32_e32 v2, s4
	s_add_i32 s4, 0, 0x20008
	ds_write_b32 v2, v1
	v_mov_b32_e32 v2, s4
	s_add_i32 s4, 0, 0x2000c
	ds_write_b32 v2, v1
	v_mov_b32_e32 v2, s4
	ds_write_b32 v2, v1

.LBB0_56:
	s_ashr_i32 s37, s36, 31
	v_cmp_lt_i64_e32 vcc, s[40:41], v[150:151]
	s_lshl_b64 s[40:41], s[36:37], 19
	s_add_u32 s40, s52, s40
	s_addc_u32 s41, s53, s41
	s_and_b64 s[44:45], vcc, exec
	s_cselect_b32 s37, s41, s1
	s_cselect_b32 s60, s40, s0
	s_ashr_i32 s35, s34, 31
	s_lshl_b64 s[44:45], s[34:35], 19
	s_add_u32 s44, s19, s44
	s_addc_u32 s45, s24, s45
	s_and_b64 s[48:49], vcc, exec
	s_cselect_b32 s35, s45, s23
	s_cselect_b32 s61, s44, s22
	s_add_u32 s0, s0, 0x40080
	s_addc_u32 s1, s1, 0
	s_add_u32 s62, s22, 0x100
	s_addc_u32 s63, s23, 0
	s_mov_b32 s64, -2
	v_mov_b64_e32 v[82:83], 0
	v_mov_b64_e32 v[84:85], 0
	s_nop 1
	v_mfma_f32_32x32x16_bf16 v[2:17], v[82:85], v[82:85], 0
	v_mov_b64_e32 v[114:115], 0
	v_mov_b64_e32 v[116:117], 0
	v_mov_b64_e32 v[118:119], 0
	v_mov_b64_e32 v[120:121], 0
	v_mov_b64_e32 v[122:123], 0
	v_mfma_f32_32x32x16_bf16 v[18:33], v[82:85], v[82:85], 0
	v_mov_b64_e32 v[124:125], 0
	v_mov_b64_e32 v[126:127], 0
	v_mov_b64_e32 v[128:129], 0
	v_mov_b64_e32 v[98:99], 0
	v_mov_b64_e32 v[100:101], 0
	v_mfma_f32_32x32x16_bf16 v[34:49], v[82:85], v[82:85], 0
	v_mov_b64_e32 v[102:103], 0
	v_mov_b64_e32 v[104:105], 0
	v_mov_b64_e32 v[106:107], 0
	v_mov_b64_e32 v[108:109], 0
	v_mov_b64_e32 v[110:111], 0
	v_mfma_f32_32x32x16_bf16 v[50:65], v[82:85], v[82:85], 0
	v_mov_b64_e32 v[112:113], 0
	v_mov_b64_e32 v[86:87], 0
	v_mov_b64_e32 v[88:89], 0
	v_mov_b64_e32 v[90:91], 0
	v_mov_b64_e32 v[92:93], 0
	v_mfma_f32_32x32x16_bf16 v[66:81], v[82:85], v[82:85], 0
	v_mov_b64_e32 v[94:95], 0
	v_mov_b64_e32 v[96:97], 0
.LBB0_57:
	s_add_u32 s22, s0, 0xfffc0080
	s_addc_u32 s23, s1, -1
	s_add_i32 s65, 0, 0x10000
	v_add_u32_e32 v142, s65, v178
	ds_read_b128 v[130:133], v142
	ds_read_b128 v[134:137], v142 offset:1024
	ds_read_b128 v[138:141], v142 offset:2048
	ds_read_b128 v[142:145], v142 offset:3072
	s_cmp_eq_u32 s64, 12
	s_cselect_b32 s49, s37, s23
	s_cselect_b32 s48, s60, s22
	s_cselect_b32 s23, s35, s63
	s_cselect_b32 s22, s61, s62
	v_lshl_add_u64 v[186:187], s[0:1], 0, v[168:169]
	s_add_i32 m0, s47, 0xc000
	ds_read_b128 v[172:175], v180
	ds_read_b128 v[182:185], v180 offset:1024
	ds_read_b128 v[206:209], v180 offset:2048
	ds_read_b128 v[210:213], v180 offset:3072
	ds_read_b128 v[214:217], v180 offset:4096
	ds_read_b128 v[218:221], v180 offset:5120
	ds_read_b128 v[222:225], v180 offset:6144
	ds_read_b128 v[226:229], v180 offset:7168
	global_load_lds_dwordx4 v[186:187], off
	v_lshl_add_u64 v[186:187], s[0:1], 0, v[170:171]
	s_add_i32 m0, s47, 0xe000
	s_nop 0
	global_load_lds_dwordx4 v[186:187], off
	s_waitcnt lgkmcnt(8)
	s_barrier
	s_waitcnt lgkmcnt(0)
	v_mfma_f32_16x16x32_bf16 v[126:129], v[130:133], v[172:175], v[126:129]
	v_mfma_f32_16x16x32_bf16 v[122:125], v[138:141], v[172:175], v[122:125]
	v_mfma_f32_16x16x32_bf16 v[114:117], v[130:133], v[206:209], v[114:117]
	v_mfma_f32_16x16x32_bf16 v[106:109], v[138:141], v[206:209], v[106:109]
	v_mfma_f32_16x16x32_bf16 v[98:101], v[130:133], v[214:217], v[98:101]
	v_mfma_f32_16x16x32_bf16 v[90:93], v[138:141], v[214:217], v[90:93]
	v_mfma_f32_16x16x32_bf16 v[82:85], v[130:133], v[222:225], v[82:85]
	v_mfma_f32_16x16x32_bf16 v[74:77], v[138:141], v[222:225], v[74:77]
	v_mfma_f32_16x16x32_bf16 v[126:129], v[134:137], v[182:185], v[126:129]
	v_mfma_f32_16x16x32_bf16 v[122:125], v[142:145], v[182:185], v[122:125]
	v_mfma_f32_16x16x32_bf16 v[114:117], v[134:137], v[210:213], v[114:117]
	v_mfma_f32_16x16x32_bf16 v[106:109], v[142:145], v[210:213], v[106:109]
	v_mfma_f32_16x16x32_bf16 v[98:101], v[134:137], v[218:221], v[98:101]
	v_mfma_f32_16x16x32_bf16 v[90:93], v[142:145], v[218:221], v[90:93]
	v_mfma_f32_16x16x32_bf16 v[82:85], v[134:137], v[226:229], v[82:85]
	v_mfma_f32_16x16x32_bf16 v[74:77], v[142:145], v[226:229], v[74:77]
	s_barrier
	s_add_i32 s68, 0, 0x14000
	s_add_i32 s65, s65, s27
	v_add_u32_e32 v181, s68, v178
	v_lshl_add_u64 v[186:187], s[22:23], 0, v[0:1]
	s_mov_b32 m0, s65
	ds_read_b128 v[230:233], v181
	ds_read_b128 v[234:237], v181 offset:1024
	ds_read_b128 v[238:241], v181 offset:2048
	ds_read_b128 v[242:245], v181 offset:3072
	global_load_lds_dwordx4 v[186:187], off
	v_lshl_add_u64 v[246:247], s[22:23], 0, v[166:167]
	s_add_i32 m0, s65, 0x2000
	s_nop 0
	global_load_lds_dwordx4 v[246:247], off
	s_barrier
	s_waitcnt lgkmcnt(0)
	v_mfma_f32_16x16x32_bf16 v[118:121], v[230:233], v[172:175], v[118:121]
	v_mfma_f32_16x16x32_bf16 v[110:113], v[238:241], v[172:175], v[110:113]
	v_mfma_f32_16x16x32_bf16 v[102:105], v[230:233], v[206:209], v[102:105]
	v_mfma_f32_16x16x32_bf16 v[94:97], v[238:241], v[206:209], v[94:97]
	v_mfma_f32_16x16x32_bf16 v[86:89], v[230:233], v[214:217], v[86:89]
	v_mfma_f32_16x16x32_bf16 v[78:81], v[238:241], v[214:217], v[78:81]
	v_mfma_f32_16x16x32_bf16 v[70:73], v[230:233], v[222:225], v[70:73]
	v_mfma_f32_16x16x32_bf16 v[66:69], v[238:241], v[222:225], v[66:69]
	v_mfma_f32_16x16x32_bf16 v[118:121], v[234:237], v[182:185], v[118:121]
	v_mfma_f32_16x16x32_bf16 v[110:113], v[242:245], v[182:185], v[110:113]
	v_mfma_f32_16x16x32_bf16 v[102:105], v[234:237], v[210:213], v[102:105]
	v_mfma_f32_16x16x32_bf16 v[94:97], v[242:245], v[210:213], v[94:97]
	v_mfma_f32_16x16x32_bf16 v[86:89], v[234:237], v[218:221], v[86:89]
	v_mfma_f32_16x16x32_bf16 v[78:81], v[242:245], v[218:221], v[78:81]
	v_mfma_f32_16x16x32_bf16 v[70:73], v[234:237], v[226:229], v[70:73]
	v_mfma_f32_16x16x32_bf16 v[66:69], v[242:245], v[226:229], v[66:69]
	s_barrier
	s_mov_b32 m0, s47
	v_lshl_add_u64 v[248:249], s[48:49], 0, v[162:163]
	ds_read_b128 v[172:175], v180 offset:16384
	ds_read_b128 v[182:185], v180 offset:17408
	ds_read_b128 v[206:209], v180 offset:18432
	ds_read_b128 v[210:213], v180 offset:19456
	ds_read_b128 v[214:217], v180 offset:20480
	ds_read_b128 v[218:221], v180 offset:21504
	ds_read_b128 v[222:225], v180 offset:22528
	ds_read_b128 v[226:229], v180 offset:23552
	global_load_lds_dwordx4 v[248:249], off
	v_lshl_add_u64 v[250:251], s[48:49], 0, v[164:165]
	s_mov_b32 m0, s50
	s_nop 0
	global_load_lds_dwordx4 v[250:251], off
	s_barrier
	s_waitcnt lgkmcnt(0)
	v_mfma_f32_16x16x32_bf16 v[62:65], v[130:133], v[172:175], v[62:65]
	v_mfma_f32_16x16x32_bf16 v[58:61], v[138:141], v[172:175], v[58:61]
	v_mfma_f32_16x16x32_bf16 v[50:53], v[130:133], v[206:209], v[50:53]
	v_mfma_f32_16x16x32_bf16 v[42:45], v[138:141], v[206:209], v[42:45]
	v_mfma_f32_16x16x32_bf16 v[34:37], v[130:133], v[214:217], v[34:37]
	v_mfma_f32_16x16x32_bf16 v[26:29], v[138:141], v[214:217], v[26:29]
	v_mfma_f32_16x16x32_bf16 v[18:21], v[130:133], v[222:225], v[18:21]
	v_mfma_f32_16x16x32_bf16 v[10:13], v[138:141], v[222:225], v[10:13]
	v_mfma_f32_16x16x32_bf16 v[62:65], v[134:137], v[182:185], v[62:65]
	v_mfma_f32_16x16x32_bf16 v[58:61], v[142:145], v[182:185], v[58:61]
	v_mfma_f32_16x16x32_bf16 v[50:53], v[134:137], v[210:213], v[50:53]
	v_mfma_f32_16x16x32_bf16 v[42:45], v[142:145], v[210:213], v[42:45]
	v_mfma_f32_16x16x32_bf16 v[34:37], v[134:137], v[218:221], v[34:37]
	v_mfma_f32_16x16x32_bf16 v[26:29], v[142:145], v[218:221], v[26:29]
	v_mfma_f32_16x16x32_bf16 v[18:21], v[134:137], v[226:229], v[18:21]
	v_mfma_f32_16x16x32_bf16 v[10:13], v[142:145], v[226:229], v[10:13]
	s_barrier
	s_add_u32 s66, s22, 0x40000
	s_addc_u32 s67, s23, 0
	s_add_i32 s65, s68, s27
	v_lshl_add_u64 v[130:131], s[66:67], 0, v[0:1]
	s_mov_b32 m0, s65
	s_nop 0
	global_load_lds_dwordx4 v[130:131], off
	v_lshl_add_u64 v[130:131], s[66:67], 0, v[166:167]
	s_add_i32 m0, s65, 0x2000
	s_nop 0
	global_load_lds_dwordx4 v[130:131], off
	s_waitcnt vmcnt(6)
	s_barrier
	v_mfma_f32_16x16x32_bf16 v[54:57], v[230:233], v[172:175], v[54:57]
	v_mfma_f32_16x16x32_bf16 v[46:49], v[238:241], v[172:175], v[46:49]
	v_mfma_f32_16x16x32_bf16 v[38:41], v[230:233], v[206:209], v[38:41]
	v_mfma_f32_16x16x32_bf16 v[30:33], v[238:241], v[206:209], v[30:33]
	v_mfma_f32_16x16x32_bf16 v[22:25], v[230:233], v[214:217], v[22:25]
	v_mfma_f32_16x16x32_bf16 v[14:17], v[238:241], v[214:217], v[14:17]
	v_mfma_f32_16x16x32_bf16 v[6:9], v[230:233], v[222:225], v[6:9]
	v_mfma_f32_16x16x32_bf16 v[2:5], v[238:241], v[222:225], v[2:5]
	v_mfma_f32_16x16x32_bf16 v[54:57], v[234:237], v[182:185], v[54:57]
	v_mfma_f32_16x16x32_bf16 v[46:49], v[242:245], v[182:185], v[46:49]
	v_mfma_f32_16x16x32_bf16 v[38:41], v[234:237], v[210:213], v[38:41]
	v_mfma_f32_16x16x32_bf16 v[30:33], v[242:245], v[210:213], v[30:33]
	v_mfma_f32_16x16x32_bf16 v[22:25], v[234:237], v[218:221], v[22:25]
	v_mfma_f32_16x16x32_bf16 v[14:17], v[242:245], v[218:221], v[14:17]
	v_mfma_f32_16x16x32_bf16 v[6:9], v[234:237], v[226:229], v[6:9]
	v_mfma_f32_16x16x32_bf16 v[2:5], v[242:245], v[226:229], v[2:5]
	s_barrier
	s_add_i32 s65, 0, 0x18000
	v_add_u32_e32 v142, s65, v178
	ds_read_b128 v[130:133], v142
	ds_read_b128 v[134:137], v142 offset:1024
	ds_read_b128 v[138:141], v142 offset:2048
	ds_read_b128 v[142:145], v142 offset:3072
	s_add_u32 s48, s48, 0x40000
	s_addc_u32 s49, s49, 0
	s_mov_b32 m0, s51
	v_lshl_add_u64 v[230:231], s[48:49], 0, v[162:163]
	ds_read_b128 v[172:175], v180 offset:32768
	ds_read_b128 v[182:185], v180 offset:33792
	ds_read_b128 v[206:209], v180 offset:34816
	ds_read_b128 v[210:213], v180 offset:35840
	ds_read_b128 v[214:217], v180 offset:36864
	ds_read_b128 v[218:221], v180 offset:37888
	ds_read_b128 v[222:225], v180 offset:38912
	ds_read_b128 v[226:229], v180 offset:39936
	global_load_lds_dwordx4 v[230:231], off
	v_lshl_add_u64 v[230:231], s[48:49], 0, v[164:165]
	s_mov_b32 m0, s54
	s_nop 0
	global_load_lds_dwordx4 v[230:231], off
	s_waitcnt lgkmcnt(8)
	s_barrier
	s_waitcnt lgkmcnt(0)
	v_mfma_f32_16x16x32_bf16 v[126:129], v[130:133], v[172:175], v[126:129]
	v_mfma_f32_16x16x32_bf16 v[122:125], v[138:141], v[172:175], v[122:125]
	v_mfma_f32_16x16x32_bf16 v[114:117], v[130:133], v[206:209], v[114:117]
	v_mfma_f32_16x16x32_bf16 v[106:109], v[138:141], v[206:209], v[106:109]
	v_mfma_f32_16x16x32_bf16 v[98:101], v[130:133], v[214:217], v[98:101]
	v_mfma_f32_16x16x32_bf16 v[90:93], v[138:141], v[214:217], v[90:93]
	v_mfma_f32_16x16x32_bf16 v[82:85], v[130:133], v[222:225], v[82:85]
	v_mfma_f32_16x16x32_bf16 v[74:77], v[138:141], v[222:225], v[74:77]
	v_mfma_f32_16x16x32_bf16 v[126:129], v[134:137], v[182:185], v[126:129]
	v_mfma_f32_16x16x32_bf16 v[122:125], v[142:145], v[182:185], v[122:125]
	v_mfma_f32_16x16x32_bf16 v[114:117], v[134:137], v[210:213], v[114:117]
	v_mfma_f32_16x16x32_bf16 v[106:109], v[142:145], v[210:213], v[106:109]
	v_mfma_f32_16x16x32_bf16 v[98:101], v[134:137], v[218:221], v[98:101]
	v_mfma_f32_16x16x32_bf16 v[90:93], v[142:145], v[218:221], v[90:93]
	v_mfma_f32_16x16x32_bf16 v[82:85], v[134:137], v[226:229], v[82:85]
	v_mfma_f32_16x16x32_bf16 v[74:77], v[142:145], v[226:229], v[74:77]
	s_barrier
	s_add_i32 s48, 0, 0x1c000
	s_add_i32 s49, s65, s27
	v_add_u32_e32 v181, s48, v178
	v_lshl_add_u64 v[186:187], v[186:187], 0, s[94:95]
	s_mov_b32 m0, s49
	ds_read_b128 v[230:233], v181
	ds_read_b128 v[234:237], v181 offset:1024
	ds_read_b128 v[238:241], v181 offset:2048
	ds_read_b128 v[242:245], v181 offset:3072
	global_load_lds_dwordx4 v[186:187], off
	v_lshl_add_u64 v[186:187], v[246:247], 0, s[94:95]
	s_add_i32 m0, s49, 0x2000
	s_nop 0
	global_load_lds_dwordx4 v[186:187], off
	s_barrier
	s_waitcnt lgkmcnt(0)
	v_mfma_f32_16x16x32_bf16 v[118:121], v[230:233], v[172:175], v[118:121]
	v_mfma_f32_16x16x32_bf16 v[110:113], v[238:241], v[172:175], v[110:113]
	v_mfma_f32_16x16x32_bf16 v[102:105], v[230:233], v[206:209], v[102:105]
	v_mfma_f32_16x16x32_bf16 v[94:97], v[238:241], v[206:209], v[94:97]
	v_mfma_f32_16x16x32_bf16 v[86:89], v[230:233], v[214:217], v[86:89]
	v_mfma_f32_16x16x32_bf16 v[78:81], v[238:241], v[214:217], v[78:81]
	v_mfma_f32_16x16x32_bf16 v[70:73], v[230:233], v[222:225], v[70:73]
	v_mfma_f32_16x16x32_bf16 v[66:69], v[238:241], v[222:225], v[66:69]
	v_mfma_f32_16x16x32_bf16 v[118:121], v[234:237], v[182:185], v[118:121]
	v_mfma_f32_16x16x32_bf16 v[110:113], v[242:245], v[182:185], v[110:113]
	v_mfma_f32_16x16x32_bf16 v[102:105], v[234:237], v[210:213], v[102:105]
	v_mfma_f32_16x16x32_bf16 v[94:97], v[242:245], v[210:213], v[94:97]
	v_mfma_f32_16x16x32_bf16 v[86:89], v[234:237], v[218:221], v[86:89]
	v_mfma_f32_16x16x32_bf16 v[78:81], v[242:245], v[218:221], v[78:81]
	v_mfma_f32_16x16x32_bf16 v[70:73], v[234:237], v[226:229], v[70:73]
	v_mfma_f32_16x16x32_bf16 v[66:69], v[242:245], v[226:229], v[66:69]
	s_barrier
	s_mov_b32 m0, s55
	v_lshl_add_u64 v[186:187], v[248:249], 0, s[94:95]
	ds_read_b128 v[172:175], v180 offset:49152
	ds_read_b128 v[182:185], v180 offset:50176
	ds_read_b128 v[206:209], v180 offset:51200
	ds_read_b128 v[210:213], v180 offset:52224
	ds_read_b128 v[214:217], v180 offset:53248
	ds_read_b128 v[218:221], v180 offset:54272
	ds_read_b128 v[222:225], v180 offset:55296
	ds_read_b128 v[226:229], v180 offset:56320
	global_load_lds_dwordx4 v[186:187], off
	v_lshl_add_u64 v[186:187], v[250:251], 0, s[94:95]
	s_mov_b32 m0, s56
	s_nop 0
	global_load_lds_dwordx4 v[186:187], off
	s_barrier
	s_waitcnt lgkmcnt(0)
	v_mfma_f32_16x16x32_bf16 v[62:65], v[130:133], v[172:175], v[62:65]
	v_mfma_f32_16x16x32_bf16 v[58:61], v[138:141], v[172:175], v[58:61]
	v_mfma_f32_16x16x32_bf16 v[50:53], v[130:133], v[206:209], v[50:53]
	v_mfma_f32_16x16x32_bf16 v[42:45], v[138:141], v[206:209], v[42:45]
	v_mfma_f32_16x16x32_bf16 v[34:37], v[130:133], v[214:217], v[34:37]
	v_mfma_f32_16x16x32_bf16 v[26:29], v[138:141], v[214:217], v[26:29]
	v_mfma_f32_16x16x32_bf16 v[18:21], v[130:133], v[222:225], v[18:21]
	v_mfma_f32_16x16x32_bf16 v[10:13], v[138:141], v[222:225], v[10:13]
	v_mfma_f32_16x16x32_bf16 v[62:65], v[134:137], v[182:185], v[62:65]
	v_mfma_f32_16x16x32_bf16 v[58:61], v[142:145], v[182:185], v[58:61]
	v_mfma_f32_16x16x32_bf16 v[50:53], v[134:137], v[210:213], v[50:53]
	v_mfma_f32_16x16x32_bf16 v[42:45], v[142:145], v[210:213], v[42:45]
	v_mfma_f32_16x16x32_bf16 v[34:37], v[134:137], v[218:221], v[34:37]
	v_mfma_f32_16x16x32_bf16 v[26:29], v[142:145], v[218:221], v[26:29]
	v_mfma_f32_16x16x32_bf16 v[18:21], v[134:137], v[226:229], v[18:21]
	v_mfma_f32_16x16x32_bf16 v[10:13], v[142:145], v[226:229], v[10:13]
	s_barrier
	s_add_u32 s22, s22, 0x40080
	s_addc_u32 s23, s23, 0
	s_add_i32 s48, s48, s27
	v_lshl_add_u64 v[130:131], s[22:23], 0, v[0:1]
	s_mov_b32 m0, s48
	s_nop 0
	global_load_lds_dwordx4 v[130:131], off
	v_lshl_add_u64 v[130:131], s[22:23], 0, v[166:167]
	s_add_i32 m0, s48, 0x2000
	s_nop 0
	global_load_lds_dwordx4 v[130:131], off
	s_waitcnt vmcnt(6)
	s_barrier
	v_mfma_f32_16x16x32_bf16 v[54:57], v[230:233], v[172:175], v[54:57]
	v_mfma_f32_16x16x32_bf16 v[46:49], v[238:241], v[172:175], v[46:49]
	v_mfma_f32_16x16x32_bf16 v[38:41], v[230:233], v[206:209], v[38:41]
	v_mfma_f32_16x16x32_bf16 v[30:33], v[238:241], v[206:209], v[30:33]
	v_mfma_f32_16x16x32_bf16 v[22:25], v[230:233], v[214:217], v[22:25]
	v_mfma_f32_16x16x32_bf16 v[14:17], v[238:241], v[214:217], v[14:17]
	v_mfma_f32_16x16x32_bf16 v[6:9], v[230:233], v[222:225], v[6:9]
	v_mfma_f32_16x16x32_bf16 v[2:5], v[238:241], v[222:225], v[2:5]
	v_mfma_f32_16x16x32_bf16 v[54:57], v[234:237], v[182:185], v[54:57]
	v_mfma_f32_16x16x32_bf16 v[46:49], v[242:245], v[182:185], v[46:49]
	v_mfma_f32_16x16x32_bf16 v[38:41], v[234:237], v[210:213], v[38:41]
	v_mfma_f32_16x16x32_bf16 v[30:33], v[242:245], v[210:213], v[30:33]
	v_mfma_f32_16x16x32_bf16 v[22:25], v[234:237], v[218:221], v[22:25]
	v_mfma_f32_16x16x32_bf16 v[14:17], v[242:245], v[218:221], v[14:17]
	v_mfma_f32_16x16x32_bf16 v[6:9], v[234:237], v[226:229], v[6:9]
	v_mfma_f32_16x16x32_bf16 v[2:5], v[242:245], v[226:229], v[2:5]
	s_barrier
	s_add_i32 s64, s64, 2
	s_add_u32 s0, s0, 0x100
	s_addc_u32 s1, s1, 0
	s_add_u32 s62, s62, 0x100
	s_addc_u32 s63, s63, 0
	s_cmp_gt_u32 s64, 13
	s_cbranch_scc0 .LBB0_57
	v_lshl_or_b32 v172, s59, 8, v179
	v_ashrrev_i32_e32 v173, 31, v172
	v_cndmask_b32_e64 v131, 0, 1, s[2:3]
	v_lshl_add_u64 v[174:175], v[172:173], 2, s[8:9]
	v_mov_b32_e32 v130, 0
	v_cmp_ne_u32_e64 s[0:1], 1, v131
	s_andn2_b64 vcc, exec, s[2:3]
	v_mov_b32_e32 v134, 0
	v_mov_b32_e32 v135, 0
	v_mov_b32_e32 v136, 0
	v_mov_b32_e32 v137, 0
	s_cbranch_vccnz .LBB0_60
	global_load_dwordx4 v[134:137], v[174:175], off

.LBB0_94:
	s_ashr_i32 s49, s48, 31
	s_lshl_b64 s[26:27], s[48:49], 19
	s_add_u32 s50, s14, s26
	v_cmp_lt_i64_e32 vcc, s[28:29], v[152:153]
	s_addc_u32 s51, s15, s27
	s_and_b64 s[26:27], vcc, exec
	s_cselect_b32 s25, s51, s9
	s_cselect_b32 s26, s50, s8
	s_ashr_i32 s47, s46, 31
	s_lshl_b64 s[28:29], s[46:47], 19
	s_add_u32 s54, s19, s28
	s_addc_u32 s55, s34, s29
	s_and_b64 s[28:29], vcc, exec
	s_cselect_b32 s27, s55, s23
	s_cselect_b32 s30, s54, s22
	s_add_u32 s8, s8, 0x40080
	s_addc_u32 s9, s9, 0
	s_add_u32 s31, s22, 0x100
	s_addc_u32 s47, s23, 0
	s_mov_b32 s49, -2
	v_mov_b64_e32 v[50:51], 0
	v_mov_b64_e32 v[52:53], 0
	s_nop 1
	v_mfma_f32_32x32x16_bf16 v[2:17], v[50:53], v[50:53], 0
	v_mov_b64_e32 v[54:55], 0
	v_mov_b64_e32 v[56:57], 0
	v_mov_b64_e32 v[62:63], 0
	v_mov_b64_e32 v[64:65], 0
	v_mov_b64_e32 v[70:71], 0
	v_mfma_f32_32x32x16_bf16 v[18:33], v[50:53], v[50:53], 0
	v_mov_b64_e32 v[72:73], 0
	v_mov_b64_e32 v[130:131], 0
	v_mov_b64_e32 v[132:133], 0
	v_mov_b64_e32 v[134:135], 0
	v_mov_b64_e32 v[136:137], 0
	v_mfma_f32_32x32x16_bf16 v[34:49], v[50:53], v[50:53], 0
	v_mov_b64_e32 v[138:139], 0
	v_mov_b64_e32 v[140:141], 0
	v_mov_b64_e32 v[142:143], 0
	v_mov_b64_e32 v[144:145], 0
	v_mov_b64_e32 v[114:115], 0
	v_mfma_f32_32x32x16_bf16 v[82:97], v[50:53], v[50:53], 0
	v_mov_b64_e32 v[116:117], 0
	v_mov_b64_e32 v[118:119], 0
	v_mov_b64_e32 v[120:121], 0
	v_mov_b64_e32 v[122:123], 0
	v_mov_b64_e32 v[124:125], 0
	v_mfma_f32_32x32x16_bf16 v[98:113], v[50:53], v[50:53], 0
	v_mov_b64_e32 v[126:127], 0
	v_mov_b64_e32 v[128:129], 0
.LBB0_95:
	s_add_u32 s22, s8, 0xfffc0080
	s_addc_u32 s23, s9, -1
	s_add_i32 s63, 0, 0x10000
	v_add_u32_e32 v78, s63, v178
	ds_read_b128 v[58:61], v78
	ds_read_b128 v[66:69], v78 offset:1024
	ds_read_b128 v[74:77], v78 offset:2048
	ds_read_b128 v[78:81], v78 offset:3072
	s_cmp_eq_u32 s49, 12
	s_cselect_b32 s29, s25, s23
	s_cselect_b32 s28, s26, s22
	s_cselect_b32 s23, s27, s47
	s_cselect_b32 s22, s30, s31
	v_lshl_add_u64 v[186:187], s[8:9], 0, v[168:169]
	s_add_i32 m0, s3, 0xc000
	ds_read_b128 v[172:175], v180
	ds_read_b128 v[182:185], v180 offset:1024
	ds_read_b128 v[206:209], v180 offset:2048
	ds_read_b128 v[210:213], v180 offset:3072
	ds_read_b128 v[214:217], v180 offset:4096
	ds_read_b128 v[218:221], v180 offset:5120
	ds_read_b128 v[222:225], v180 offset:6144
	ds_read_b128 v[226:229], v180 offset:7168
	global_load_lds_dwordx4 v[186:187], off
	v_lshl_add_u64 v[186:187], s[8:9], 0, v[170:171]
	s_add_i32 m0, s3, 0xe000
	s_nop 0
	global_load_lds_dwordx4 v[186:187], off
	s_waitcnt lgkmcnt(8)
	s_barrier
	s_waitcnt lgkmcnt(0)
	v_mfma_f32_16x16x32_bf16 v[142:145], v[58:61], v[172:175], v[142:145]
	v_mfma_f32_16x16x32_bf16 v[138:141], v[74:77], v[172:175], v[138:141]
	v_mfma_f32_16x16x32_bf16 v[126:129], v[58:61], v[206:209], v[126:129]
	v_mfma_f32_16x16x32_bf16 v[118:121], v[74:77], v[206:209], v[118:121]
	v_mfma_f32_16x16x32_bf16 v[110:113], v[58:61], v[214:217], v[110:113]
	v_mfma_f32_16x16x32_bf16 v[102:105], v[74:77], v[214:217], v[102:105]
	v_mfma_f32_16x16x32_bf16 v[94:97], v[58:61], v[222:225], v[94:97]
	v_mfma_f32_16x16x32_bf16 v[86:89], v[74:77], v[222:225], v[86:89]
	v_mfma_f32_16x16x32_bf16 v[142:145], v[66:69], v[182:185], v[142:145]
	v_mfma_f32_16x16x32_bf16 v[138:141], v[78:81], v[182:185], v[138:141]
	v_mfma_f32_16x16x32_bf16 v[126:129], v[66:69], v[210:213], v[126:129]
	v_mfma_f32_16x16x32_bf16 v[118:121], v[78:81], v[210:213], v[118:121]
	v_mfma_f32_16x16x32_bf16 v[110:113], v[66:69], v[218:221], v[110:113]
	v_mfma_f32_16x16x32_bf16 v[102:105], v[78:81], v[218:221], v[102:105]
	v_mfma_f32_16x16x32_bf16 v[94:97], v[66:69], v[226:229], v[94:97]
	v_mfma_f32_16x16x32_bf16 v[86:89], v[78:81], v[226:229], v[86:89]
	s_barrier
	s_add_i32 s66, 0, 0x14000
	s_add_i32 s63, s63, s37
	v_add_u32_e32 v181, s66, v178
	v_lshl_add_u64 v[186:187], s[22:23], 0, v[0:1]
	s_mov_b32 m0, s63
	ds_read_b128 v[230:233], v181
	ds_read_b128 v[234:237], v181 offset:1024
	ds_read_b128 v[238:241], v181 offset:2048
	ds_read_b128 v[242:245], v181 offset:3072
	global_load_lds_dwordx4 v[186:187], off
	v_lshl_add_u64 v[246:247], s[22:23], 0, v[166:167]
	s_add_i32 m0, s63, 0x2000
	s_nop 0
	global_load_lds_dwordx4 v[246:247], off
	s_barrier
	s_waitcnt lgkmcnt(0)
	v_mfma_f32_16x16x32_bf16 v[134:137], v[230:233], v[172:175], v[134:137]
	v_mfma_f32_16x16x32_bf16 v[130:133], v[238:241], v[172:175], v[130:133]
	v_mfma_f32_16x16x32_bf16 v[122:125], v[230:233], v[206:209], v[122:125]
	v_mfma_f32_16x16x32_bf16 v[114:117], v[238:241], v[206:209], v[114:117]
	v_mfma_f32_16x16x32_bf16 v[106:109], v[230:233], v[214:217], v[106:109]
	v_mfma_f32_16x16x32_bf16 v[98:101], v[238:241], v[214:217], v[98:101]
	v_mfma_f32_16x16x32_bf16 v[90:93], v[230:233], v[222:225], v[90:93]
	v_mfma_f32_16x16x32_bf16 v[82:85], v[238:241], v[222:225], v[82:85]
	v_mfma_f32_16x16x32_bf16 v[134:137], v[234:237], v[182:185], v[134:137]
	v_mfma_f32_16x16x32_bf16 v[130:133], v[242:245], v[182:185], v[130:133]
	v_mfma_f32_16x16x32_bf16 v[122:125], v[234:237], v[210:213], v[122:125]
	v_mfma_f32_16x16x32_bf16 v[114:117], v[242:245], v[210:213], v[114:117]
	v_mfma_f32_16x16x32_bf16 v[106:109], v[234:237], v[218:221], v[106:109]
	v_mfma_f32_16x16x32_bf16 v[98:101], v[242:245], v[218:221], v[98:101]
	v_mfma_f32_16x16x32_bf16 v[90:93], v[234:237], v[226:229], v[90:93]
	v_mfma_f32_16x16x32_bf16 v[82:85], v[242:245], v[226:229], v[82:85]
	s_barrier
	s_mov_b32 m0, s3
	v_lshl_add_u64 v[248:249], s[28:29], 0, v[162:163]
	ds_read_b128 v[172:175], v180 offset:16384
	ds_read_b128 v[182:185], v180 offset:17408
	ds_read_b128 v[206:209], v180 offset:18432
	ds_read_b128 v[210:213], v180 offset:19456
	ds_read_b128 v[214:217], v180 offset:20480
	ds_read_b128 v[218:221], v180 offset:21504
	ds_read_b128 v[222:225], v180 offset:22528
	ds_read_b128 v[226:229], v180 offset:23552
	global_load_lds_dwordx4 v[248:249], off
	v_lshl_add_u64 v[250:251], s[28:29], 0, v[164:165]
	s_mov_b32 m0, s56
	s_nop 0
	global_load_lds_dwordx4 v[250:251], off
	s_barrier
	s_waitcnt lgkmcnt(0)
	v_mfma_f32_16x16x32_bf16 v[70:73], v[58:61], v[172:175], v[70:73]
	v_mfma_f32_16x16x32_bf16 v[54:57], v[74:77], v[172:175], v[54:57]
	v_mfma_f32_16x16x32_bf16 v[46:49], v[58:61], v[206:209], v[46:49]
	v_mfma_f32_16x16x32_bf16 v[38:41], v[74:77], v[206:209], v[38:41]
	v_mfma_f32_16x16x32_bf16 v[30:33], v[58:61], v[214:217], v[30:33]
	v_mfma_f32_16x16x32_bf16 v[22:25], v[74:77], v[214:217], v[22:25]
	v_mfma_f32_16x16x32_bf16 v[14:17], v[58:61], v[222:225], v[14:17]
	v_mfma_f32_16x16x32_bf16 v[6:9], v[74:77], v[222:225], v[6:9]
	v_mfma_f32_16x16x32_bf16 v[70:73], v[66:69], v[182:185], v[70:73]
	v_mfma_f32_16x16x32_bf16 v[54:57], v[78:81], v[182:185], v[54:57]
	v_mfma_f32_16x16x32_bf16 v[46:49], v[66:69], v[210:213], v[46:49]
	v_mfma_f32_16x16x32_bf16 v[38:41], v[78:81], v[210:213], v[38:41]
	v_mfma_f32_16x16x32_bf16 v[30:33], v[66:69], v[218:221], v[30:33]
	v_mfma_f32_16x16x32_bf16 v[22:25], v[78:81], v[218:221], v[22:25]
	v_mfma_f32_16x16x32_bf16 v[14:17], v[66:69], v[226:229], v[14:17]
	v_mfma_f32_16x16x32_bf16 v[6:9], v[78:81], v[226:229], v[6:9]
	s_barrier
	s_add_u32 s64, s22, 0x40000
	s_addc_u32 s65, s23, 0
	s_add_i32 s63, s66, s37
	v_lshl_add_u64 v[58:59], s[64:65], 0, v[0:1]
	s_mov_b32 m0, s63
	s_nop 0
	global_load_lds_dwordx4 v[58:59], off
	v_lshl_add_u64 v[58:59], s[64:65], 0, v[166:167]
	s_add_i32 m0, s63, 0x2000
	s_nop 0
	global_load_lds_dwordx4 v[58:59], off
	s_waitcnt vmcnt(6)
	s_barrier
	v_mfma_f32_16x16x32_bf16 v[50:53], v[238:241], v[172:175], v[50:53]
	v_mfma_f32_16x16x32_bf16 v[42:45], v[230:233], v[206:209], v[42:45]
	v_mfma_f32_16x16x32_bf16 v[34:37], v[238:241], v[206:209], v[34:37]
	v_mfma_f32_16x16x32_bf16 v[26:29], v[230:233], v[214:217], v[26:29]
	v_mfma_f32_16x16x32_bf16 v[18:21], v[238:241], v[214:217], v[18:21]
	v_mfma_f32_16x16x32_bf16 v[10:13], v[230:233], v[222:225], v[10:13]
	v_mfma_f32_16x16x32_bf16 v[2:5], v[238:241], v[222:225], v[2:5]
	v_mfma_f32_16x16x32_bf16 v[58:61], v[230:233], v[172:175], v[62:65]
	v_mfma_f32_16x16x32_bf16 v[50:53], v[242:245], v[182:185], v[50:53]
	v_mfma_f32_16x16x32_bf16 v[42:45], v[234:237], v[210:213], v[42:45]
	v_mfma_f32_16x16x32_bf16 v[34:37], v[242:245], v[210:213], v[34:37]
	v_mfma_f32_16x16x32_bf16 v[26:29], v[234:237], v[218:221], v[26:29]
	v_mfma_f32_16x16x32_bf16 v[18:21], v[242:245], v[218:221], v[18:21]
	v_mfma_f32_16x16x32_bf16 v[10:13], v[234:237], v[226:229], v[10:13]
	v_mfma_f32_16x16x32_bf16 v[2:5], v[242:245], v[226:229], v[2:5]
	v_mfma_f32_16x16x32_bf16 v[58:61], v[234:237], v[182:185], v[58:61]
	s_barrier
	s_add_i32 s63, 0, 0x18000
	v_add_u32_e32 v78, s63, v178
	ds_read_b128 v[62:65], v78
	ds_read_b128 v[66:69], v78 offset:1024
	ds_read_b128 v[74:77], v78 offset:2048
	ds_read_b128 v[78:81], v78 offset:3072
	s_add_u32 s28, s28, 0x40000
	s_addc_u32 s29, s29, 0
	s_mov_b32 m0, s57
	v_lshl_add_u64 v[230:231], s[28:29], 0, v[162:163]
	ds_read_b128 v[172:175], v180 offset:32768
	ds_read_b128 v[182:185], v180 offset:33792
	ds_read_b128 v[206:209], v180 offset:34816
	ds_read_b128 v[210:213], v180 offset:35840
	ds_read_b128 v[214:217], v180 offset:36864
	ds_read_b128 v[218:221], v180 offset:37888
	ds_read_b128 v[222:225], v180 offset:38912
	ds_read_b128 v[226:229], v180 offset:39936
	global_load_lds_dwordx4 v[230:231], off
	v_lshl_add_u64 v[230:231], s[28:29], 0, v[164:165]
	s_mov_b32 m0, s58
	s_nop 0
	global_load_lds_dwordx4 v[230:231], off
	s_waitcnt lgkmcnt(8)
	s_barrier
	s_waitcnt lgkmcnt(0)
	v_mfma_f32_16x16x32_bf16 v[142:145], v[62:65], v[172:175], v[142:145]
	v_mfma_f32_16x16x32_bf16 v[138:141], v[74:77], v[172:175], v[138:141]
	v_mfma_f32_16x16x32_bf16 v[126:129], v[62:65], v[206:209], v[126:129]
	v_mfma_f32_16x16x32_bf16 v[118:121], v[74:77], v[206:209], v[118:121]
	v_mfma_f32_16x16x32_bf16 v[110:113], v[62:65], v[214:217], v[110:113]
	v_mfma_f32_16x16x32_bf16 v[102:105], v[74:77], v[214:217], v[102:105]
	v_mfma_f32_16x16x32_bf16 v[94:97], v[62:65], v[222:225], v[94:97]
	v_mfma_f32_16x16x32_bf16 v[86:89], v[74:77], v[222:225], v[86:89]
	v_mfma_f32_16x16x32_bf16 v[142:145], v[66:69], v[182:185], v[142:145]
	v_mfma_f32_16x16x32_bf16 v[138:141], v[78:81], v[182:185], v[138:141]
	v_mfma_f32_16x16x32_bf16 v[126:129], v[66:69], v[210:213], v[126:129]
	v_mfma_f32_16x16x32_bf16 v[118:121], v[78:81], v[210:213], v[118:121]
	v_mfma_f32_16x16x32_bf16 v[110:113], v[66:69], v[218:221], v[110:113]
	v_mfma_f32_16x16x32_bf16 v[102:105], v[78:81], v[218:221], v[102:105]
	v_mfma_f32_16x16x32_bf16 v[94:97], v[66:69], v[226:229], v[94:97]
	v_mfma_f32_16x16x32_bf16 v[86:89], v[78:81], v[226:229], v[86:89]
	s_barrier
	s_add_i32 s28, 0, 0x1c000
	s_add_i32 s29, s63, s37
	v_add_u32_e32 v181, s28, v178
	v_lshl_add_u64 v[186:187], v[186:187], 0, s[94:95]
	s_mov_b32 m0, s29
	ds_read_b128 v[230:233], v181
	ds_read_b128 v[234:237], v181 offset:1024
	ds_read_b128 v[238:241], v181 offset:2048
	ds_read_b128 v[242:245], v181 offset:3072
	global_load_lds_dwordx4 v[186:187], off
	v_lshl_add_u64 v[186:187], v[246:247], 0, s[94:95]
	s_add_i32 m0, s29, 0x2000
	s_nop 0
	global_load_lds_dwordx4 v[186:187], off
	s_barrier
	s_waitcnt lgkmcnt(0)
	v_mfma_f32_16x16x32_bf16 v[134:137], v[230:233], v[172:175], v[134:137]
	v_mfma_f32_16x16x32_bf16 v[130:133], v[238:241], v[172:175], v[130:133]
	v_mfma_f32_16x16x32_bf16 v[122:125], v[230:233], v[206:209], v[122:125]
	v_mfma_f32_16x16x32_bf16 v[114:117], v[238:241], v[206:209], v[114:117]
	v_mfma_f32_16x16x32_bf16 v[106:109], v[230:233], v[214:217], v[106:109]
	v_mfma_f32_16x16x32_bf16 v[98:101], v[238:241], v[214:217], v[98:101]
	v_mfma_f32_16x16x32_bf16 v[90:93], v[230:233], v[222:225], v[90:93]
	v_mfma_f32_16x16x32_bf16 v[82:85], v[238:241], v[222:225], v[82:85]
	v_mfma_f32_16x16x32_bf16 v[134:137], v[234:237], v[182:185], v[134:137]
	v_mfma_f32_16x16x32_bf16 v[130:133], v[242:245], v[182:185], v[130:133]
	v_mfma_f32_16x16x32_bf16 v[122:125], v[234:237], v[210:213], v[122:125]
	v_mfma_f32_16x16x32_bf16 v[114:117], v[242:245], v[210:213], v[114:117]
	v_mfma_f32_16x16x32_bf16 v[106:109], v[234:237], v[218:221], v[106:109]
	v_mfma_f32_16x16x32_bf16 v[98:101], v[242:245], v[218:221], v[98:101]
	v_mfma_f32_16x16x32_bf16 v[90:93], v[234:237], v[226:229], v[90:93]
	v_mfma_f32_16x16x32_bf16 v[82:85], v[242:245], v[226:229], v[82:85]
	s_barrier
	s_mov_b32 m0, s59
	v_lshl_add_u64 v[186:187], v[248:249], 0, s[94:95]
	ds_read_b128 v[172:175], v180 offset:49152
	ds_read_b128 v[182:185], v180 offset:50176
	ds_read_b128 v[206:209], v180 offset:51200
	ds_read_b128 v[210:213], v180 offset:52224
	ds_read_b128 v[214:217], v180 offset:53248
	ds_read_b128 v[218:221], v180 offset:54272
	ds_read_b128 v[222:225], v180 offset:55296
	ds_read_b128 v[226:229], v180 offset:56320
	global_load_lds_dwordx4 v[186:187], off
	v_lshl_add_u64 v[186:187], v[250:251], 0, s[94:95]
	s_mov_b32 m0, s60
	s_nop 0
	global_load_lds_dwordx4 v[186:187], off
	s_barrier
	s_waitcnt lgkmcnt(0)
	v_mfma_f32_16x16x32_bf16 v[70:73], v[62:65], v[172:175], v[70:73]
	v_mfma_f32_16x16x32_bf16 v[54:57], v[74:77], v[172:175], v[54:57]
	v_mfma_f32_16x16x32_bf16 v[46:49], v[62:65], v[206:209], v[46:49]
	v_mfma_f32_16x16x32_bf16 v[38:41], v[74:77], v[206:209], v[38:41]
	v_mfma_f32_16x16x32_bf16 v[30:33], v[62:65], v[214:217], v[30:33]
	v_mfma_f32_16x16x32_bf16 v[22:25], v[74:77], v[214:217], v[22:25]
	v_mfma_f32_16x16x32_bf16 v[14:17], v[62:65], v[222:225], v[14:17]
	v_mfma_f32_16x16x32_bf16 v[6:9], v[74:77], v[222:225], v[6:9]
	v_mfma_f32_16x16x32_bf16 v[70:73], v[66:69], v[182:185], v[70:73]
	v_mfma_f32_16x16x32_bf16 v[54:57], v[78:81], v[182:185], v[54:57]
	v_mfma_f32_16x16x32_bf16 v[46:49], v[66:69], v[210:213], v[46:49]
	v_mfma_f32_16x16x32_bf16 v[38:41], v[78:81], v[210:213], v[38:41]
	v_mfma_f32_16x16x32_bf16 v[30:33], v[66:69], v[218:221], v[30:33]
	v_mfma_f32_16x16x32_bf16 v[22:25], v[78:81], v[218:221], v[22:25]
	v_mfma_f32_16x16x32_bf16 v[14:17], v[66:69], v[226:229], v[14:17]
	v_mfma_f32_16x16x32_bf16 v[6:9], v[78:81], v[226:229], v[6:9]
	s_barrier
	s_add_u32 s22, s22, 0x40080
	s_addc_u32 s23, s23, 0
	s_add_i32 s28, s28, s37
	v_lshl_add_u64 v[62:63], s[22:23], 0, v[0:1]
	s_mov_b32 m0, s28
	s_nop 0
	global_load_lds_dwordx4 v[62:63], off
	v_lshl_add_u64 v[62:63], s[22:23], 0, v[166:167]
	s_add_i32 m0, s28, 0x2000
	s_nop 0
	global_load_lds_dwordx4 v[62:63], off
	s_waitcnt vmcnt(6)
	s_barrier
	v_mfma_f32_16x16x32_bf16 v[58:61], v[230:233], v[172:175], v[58:61]
	v_mfma_f32_16x16x32_bf16 v[50:53], v[238:241], v[172:175], v[50:53]
	v_mfma_f32_16x16x32_bf16 v[42:45], v[230:233], v[206:209], v[42:45]
	v_mfma_f32_16x16x32_bf16 v[34:37], v[238:241], v[206:209], v[34:37]
	v_mfma_f32_16x16x32_bf16 v[26:29], v[230:233], v[214:217], v[26:29]
	v_mfma_f32_16x16x32_bf16 v[18:21], v[238:241], v[214:217], v[18:21]
	v_mfma_f32_16x16x32_bf16 v[10:13], v[230:233], v[222:225], v[10:13]
	v_mfma_f32_16x16x32_bf16 v[2:5], v[238:241], v[222:225], v[2:5]
	v_mfma_f32_16x16x32_bf16 v[62:65], v[234:237], v[182:185], v[58:61]
	v_mfma_f32_16x16x32_bf16 v[50:53], v[242:245], v[182:185], v[50:53]
	v_mfma_f32_16x16x32_bf16 v[42:45], v[234:237], v[210:213], v[42:45]
	v_mfma_f32_16x16x32_bf16 v[34:37], v[242:245], v[210:213], v[34:37]
	v_mfma_f32_16x16x32_bf16 v[26:29], v[234:237], v[218:221], v[26:29]
	v_mfma_f32_16x16x32_bf16 v[18:21], v[242:245], v[218:221], v[18:21]
	v_mfma_f32_16x16x32_bf16 v[10:13], v[234:237], v[226:229], v[10:13]
	v_mfma_f32_16x16x32_bf16 v[2:5], v[242:245], v[226:229], v[2:5]
	s_barrier
	s_add_i32 s49, s49, 2
	s_add_u32 s8, s8, 0x100
	s_addc_u32 s9, s9, 0
	s_add_u32 s31, s31, 0x100
	s_addc_u32 s47, s47, 0
	s_cmp_gt_u32 s49, 13
	s_cbranch_scc0 .LBB0_95
	v_lshl_or_b32 v172, s24, 7, v179
	v_ashrrev_i32_e32 v173, 31, v172
	v_lshlrev_b64 v[58:59], 2, v[172:173]
	v_lshl_add_u64 v[60:61], s[40:41], 0, v[58:59]
	v_lshl_add_u64 v[74:75], s[44:45], 0, v[58:59]
	global_load_dwordx4 v[66:69], v[60:61], off offset:16
	global_load_dwordx4 v[78:81], v[60:61], off
	s_nop 0
	global_load_dwordx4 v[58:61], v[74:75], off offset:16
	s_nop 0
	global_load_dwordx4 v[74:77], v[74:75], off
	v_lshl_add_u32 v174, s2, 8, v177
	v_ashrrev_i32_e32 v175, 31, v174
	v_lshl_add_u64 v[172:173], v[172:173], 1, s[20:21]
	v_lshlrev_b64 v[182:183], 11, v[174:175]
	s_mov_b32 s2, 0x50000
	s_mov_b32 s24, s46
	s_mov_b64 s[22:23], s[54:55]
	s_mov_b64 s[8:9], s[50:51]
	s_waitcnt vmcnt(0)
	v_add_f32_e32 v138, v138, v66
	v_add_f32_e32 v126, v126, v78
	v_add_f32_e32 v130, v130, v58
	v_mul_f32_e32 v130, 0xbfb8aa3b, v130
	v_add_f32_e32 v131, v131, v59
	v_add_f32_e32 v122, v122, v74
	v_exp_f32_e32 v130, v130
	v_mul_f32_e32 v131, 0xbfb8aa3b, v131
	v_mul_f32_e32 v122, 0xbfb8aa3b, v122
	v_add_f32_e32 v123, v123, v75
	v_exp_f32_e32 v131, v131
	v_exp_f32_e32 v122, v122
	v_mul_f32_e32 v123, 0xbfb8aa3b, v123
	v_add_f32_e32 v124, v124, v76
	v_exp_f32_e32 v123, v123
	v_mul_f32_e32 v124, 0xbfb8aa3b, v124
	v_add_f32_e32 v125, v125, v77
	v_add_f32_e32 v114, v114, v58
	v_exp_f32_e32 v124, v124
	v_mul_f32_e32 v125, 0xbfb8aa3b, v125
	v_mul_f32_e32 v114, 0xbfb8aa3b, v114
	v_add_f32_e32 v115, v115, v59
	v_add_f32_e32 v106, v106, v74
	v_add_f32_e32 v130, 1.0, v130
	v_exp_f32_e32 v125, v125
	v_exp_f32_e32 v114, v114
	v_mul_f32_e32 v115, 0xbfb8aa3b, v115
	v_mul_f32_e32 v106, 0xbfb8aa3b, v106
	v_add_f32_e32 v107, v107, v75
	v_rcp_f32_e32 v130, v130
	v_add_f32_e32 v131, 1.0, v131
	v_add_f32_e32 v122, 1.0, v122
	v_exp_f32_e32 v115, v115
	v_exp_f32_e32 v106, v106
	v_mul_f32_e32 v107, 0xbfb8aa3b, v107
	v_add_f32_e32 v108, v108, v76
	v_rcp_f32_e32 v131, v131
	v_rcp_f32_e32 v122, v122
	v_add_f32_e32 v123, 1.0, v123
	v_exp_f32_e32 v107, v107
	v_mul_f32_e32 v108, 0xbfb8aa3b, v108
	v_add_f32_e32 v109, v109, v77
	v_add_f32_e32 v98, v98, v58
	v_rcp_f32_e32 v123, v123
	v_add_f32_e32 v124, 1.0, v124
	v_exp_f32_e32 v108, v108
	v_mul_f32_e32 v109, 0xbfb8aa3b, v109
	v_mul_f32_e32 v98, 0xbfb8aa3b, v98
	v_add_f32_e32 v99, v99, v59
	v_add_f32_e32 v90, v90, v74
	v_rcp_f32_e32 v124, v124
	v_add_f32_e32 v125, 1.0, v125
	v_add_f32_e32 v114, 1.0, v114
	v_exp_f32_e32 v109, v109
	v_exp_f32_e32 v98, v98
	v_mul_f32_e32 v99, 0xbfb8aa3b, v99
	v_mul_f32_e32 v90, 0xbfb8aa3b, v90
	v_add_f32_e32 v91, v91, v75
	v_mul_f32_e32 v138, v138, v130
	v_add_f32_e32 v130, v139, v67
	v_rcp_f32_e32 v125, v125
	v_rcp_f32_e32 v114, v114
	v_add_f32_e32 v115, 1.0, v115
	v_add_f32_e32 v106, 1.0, v106
	v_exp_f32_e32 v99, v99
	v_exp_f32_e32 v90, v90
	v_mul_f32_e32 v91, 0xbfb8aa3b, v91
	v_add_f32_e32 v92, v92, v76
	v_mul_f32_e32 v139, v130, v131
	v_add_f32_e32 v131, v132, v60
	v_mul_f32_e32 v122, v126, v122
	v_add_f32_e32 v126, v127, v79
	v_rcp_f32_e32 v115, v115
	v_rcp_f32_e32 v106, v106
	v_add_f32_e32 v107, 1.0, v107
	v_exp_f32_e32 v91, v91
	v_mul_f32_e32 v92, 0xbfb8aa3b, v92
	v_add_f32_e32 v93, v93, v77
	v_add_f32_e32 v82, v82, v58
	v_mul_f32_e32 v131, 0xbfb8aa3b, v131
	v_mul_f32_e32 v123, v126, v123
	v_add_f32_e32 v126, v128, v80
	v_rcp_f32_e32 v107, v107
	v_add_f32_e32 v108, 1.0, v108
	v_exp_f32_e32 v92, v92
	v_mul_f32_e32 v93, 0xbfb8aa3b, v93
	v_mul_f32_e32 v82, 0xbfb8aa3b, v82
	v_add_f32_e32 v83, v83, v59
	v_add_f32_e32 v50, v50, v58
	v_exp_f32_e32 v131, v131
	v_mul_f32_e32 v124, v126, v124
	v_add_f32_e32 v126, v129, v81
	v_add_f32_e32 v118, v118, v66
	v_rcp_f32_e32 v108, v108
	v_add_f32_e32 v109, 1.0, v109
	v_add_f32_e32 v98, 1.0, v98
	v_exp_f32_e32 v93, v93
	v_exp_f32_e32 v82, v82
	v_mul_f32_e32 v83, 0xbfb8aa3b, v83
	v_mul_f32_e32 v50, 0xbfb8aa3b, v50
	v_add_f32_e32 v51, v51, v59
	v_mul_f32_e32 v125, v126, v125
	v_mul_f32_e32 v126, v118, v114
	v_add_f32_e32 v114, v119, v67
	v_add_f32_e32 v110, v110, v78
	v_rcp_f32_e32 v109, v109
	v_rcp_f32_e32 v98, v98
	v_add_f32_e32 v99, 1.0, v99
	v_add_f32_e32 v90, 1.0, v90
	v_exp_f32_e32 v83, v83
	v_exp_f32_e32 v50, v50
	v_mul_f32_e32 v51, 0xbfb8aa3b, v51
	v_add_f32_e32 v34, v34, v58
	v_mul_f32_e32 v127, v114, v115
	v_add_f32_e32 v115, v116, v60
	v_mul_f32_e32 v106, v110, v106
	v_add_f32_e32 v110, v111, v79
	v_rcp_f32_e32 v99, v99
	v_rcp_f32_e32 v90, v90
	v_add_f32_e32 v91, 1.0, v91
	v_exp_f32_e32 v51, v51
	v_mul_f32_e32 v34, 0xbfb8aa3b, v34
	v_add_f32_e32 v35, v35, v59
	v_mul_f32_e32 v115, 0xbfb8aa3b, v115
	v_mul_f32_e32 v107, v110, v107
	v_add_f32_e32 v110, v112, v80
	v_rcp_f32_e32 v91, v91
	v_add_f32_e32 v92, 1.0, v92
	v_exp_f32_e32 v34, v34
	v_mul_f32_e32 v35, 0xbfb8aa3b, v35
	v_add_f32_e32 v18, v18, v58
	v_add_f32_e32 v131, 1.0, v131
	v_exp_f32_e32 v115, v115
	v_mul_f32_e32 v108, v110, v108
	v_add_f32_e32 v110, v113, v81
	v_add_f32_e32 v102, v102, v66
	v_rcp_f32_e32 v92, v92
	v_add_f32_e32 v93, 1.0, v93
	v_add_f32_e32 v82, 1.0, v82
	v_exp_f32_e32 v35, v35
	v_mul_f32_e32 v18, 0xbfb8aa3b, v18
	v_add_f32_e32 v19, v19, v59
	v_rcp_f32_e32 v131, v131
	v_mul_f32_e32 v109, v110, v109
	v_mul_f32_e32 v110, v102, v98
	v_add_f32_e32 v98, v103, v67
	v_add_f32_e32 v94, v94, v78
	v_rcp_f32_e32 v93, v93
	v_rcp_f32_e32 v82, v82
	v_add_f32_e32 v83, 1.0, v83
	v_add_f32_e32 v50, 1.0, v50
	v_exp_f32_e32 v18, v18
	v_mul_f32_e32 v19, 0xbfb8aa3b, v19
	v_add_f32_e32 v2, v2, v58
	v_mul_f32_e32 v111, v98, v99
	v_add_f32_e32 v99, v100, v60
	v_mul_f32_e32 v90, v94, v90
	v_add_f32_e32 v94, v95, v79
	v_rcp_f32_e32 v83, v83
	v_rcp_f32_e32 v50, v50
	v_add_f32_e32 v51, 1.0, v51
	v_exp_f32_e32 v19, v19
	v_mul_f32_e32 v2, 0xbfb8aa3b, v2
	v_add_f32_e32 v3, v3, v59
	v_add_f32_e32 v134, v134, v74
	v_mul_f32_e32 v99, 0xbfb8aa3b, v99
	v_mul_f32_e32 v91, v94, v91
	v_add_f32_e32 v94, v96, v80
	v_rcp_f32_e32 v51, v51
	v_add_f32_e32 v34, 1.0, v34
	v_exp_f32_e32 v2, v2
	v_mul_f32_e32 v3, 0xbfb8aa3b, v3
	v_mul_f32_e32 v134, 0xbfb8aa3b, v134
	v_add_f32_e32 v135, v135, v75
	v_add_f32_e32 v130, v140, v68
	v_add_f32_e32 v115, 1.0, v115
	v_exp_f32_e32 v99, v99
	v_mul_f32_e32 v92, v94, v92
	v_add_f32_e32 v94, v97, v81
	v_add_f32_e32 v86, v86, v66
	v_rcp_f32_e32 v34, v34
	v_add_f32_e32 v35, 1.0, v35
	v_exp_f32_e32 v3, v3
	v_exp_f32_e32 v134, v134
	v_mul_f32_e32 v135, 0xbfb8aa3b, v135
	v_add_f32_e32 v136, v136, v76
	v_mul_f32_e32 v140, v130, v131
	v_add_f32_e32 v131, v133, v61
	v_rcp_f32_e32 v115, v115
	v_mul_f32_e32 v93, v94, v93
	v_mul_f32_e32 v94, v86, v82
	v_add_f32_e32 v82, v87, v67
	v_add_f32_e32 v54, v54, v66
	v_rcp_f32_e32 v35, v35
	v_add_f32_e32 v18, 1.0, v18
	v_exp_f32_e32 v135, v135
	v_mul_f32_e32 v136, 0xbfb8aa3b, v136
	v_add_f32_e32 v137, v137, v77
	v_mul_f32_e32 v131, 0xbfb8aa3b, v131
	v_mul_f32_e32 v95, v82, v83
	v_add_f32_e32 v83, v84, v60
	v_mul_f32_e32 v54, v54, v50
	v_add_f32_e32 v50, v55, v67
	v_rcp_f32_e32 v18, v18
	v_add_f32_e32 v19, 1.0, v19
	v_exp_f32_e32 v136, v136
	v_mul_f32_e32 v137, 0xbfb8aa3b, v137
	v_exp_f32_e32 v131, v131
	v_mul_f32_e32 v83, 0xbfb8aa3b, v83
	v_mul_f32_e32 v55, v50, v51
	v_add_f32_e32 v51, v52, v60
	v_add_f32_e32 v38, v38, v66
	v_rcp_f32_e32 v19, v19
	v_add_f32_e32 v2, 1.0, v2
	v_exp_f32_e32 v137, v137
	v_add_f32_e32 v114, v120, v68
	v_add_f32_e32 v99, 1.0, v99
	v_exp_f32_e32 v83, v83
	v_mul_f32_e32 v51, 0xbfb8aa3b, v51
	v_mul_f32_e32 v38, v38, v34
	v_add_f32_e32 v34, v39, v67
	v_rcp_f32_e32 v2, v2
	v_add_f32_e32 v3, 1.0, v3
	v_add_f32_e32 v134, 1.0, v134
	v_mul_f32_e32 v120, v114, v115
	v_add_f32_e32 v115, v117, v61
	v_rcp_f32_e32 v99, v99
	v_exp_f32_e32 v51, v51
	v_mul_f32_e32 v39, v34, v35
	v_add_f32_e32 v35, v36, v60
	v_add_f32_e32 v22, v22, v66
	v_rcp_f32_e32 v3, v3
	v_rcp_f32_e32 v134, v134
	v_add_f32_e32 v135, 1.0, v135
	v_mul_f32_e32 v115, 0xbfb8aa3b, v115
	v_mul_f32_e32 v35, 0xbfb8aa3b, v35
	v_mul_f32_e32 v22, v22, v18
	v_add_f32_e32 v18, v23, v67
	v_rcp_f32_e32 v135, v135
	v_add_f32_e32 v136, 1.0, v136
	v_add_f32_e32 v131, 1.0, v131
	v_exp_f32_e32 v115, v115
	v_exp_f32_e32 v35, v35
	v_mul_f32_e32 v23, v18, v19
	v_add_f32_e32 v19, v20, v60
	v_add_f32_e32 v6, v6, v66
	v_rcp_f32_e32 v136, v136
	v_add_f32_e32 v137, 1.0, v137
	v_rcp_f32_e32 v131, v131
	v_add_f32_e32 v98, v104, v68
	v_add_f32_e32 v83, 1.0, v83
	v_mul_f32_e32 v19, 0xbfb8aa3b, v19
	v_mul_f32_e32 v6, v6, v2
	v_add_f32_e32 v2, v7, v67
	v_add_f32_e32 v142, v142, v78
	v_rcp_f32_e32 v137, v137
	v_mul_f32_e32 v104, v98, v99
	v_add_f32_e32 v99, v101, v61
	v_rcp_f32_e32 v83, v83
	v_add_f32_e32 v51, 1.0, v51
	v_exp_f32_e32 v19, v19
	v_mul_f32_e32 v7, v2, v3
	v_add_f32_e32 v3, v4, v60
	v_mul_f32_e32 v134, v142, v134
	v_add_f32_e32 v142, v143, v79
	v_mul_f32_e32 v99, 0xbfb8aa3b, v99
	v_rcp_f32_e32 v51, v51
	v_mul_f32_e32 v3, 0xbfb8aa3b, v3
	v_mul_f32_e32 v135, v142, v135
	v_add_f32_e32 v142, v144, v80
	v_add_f32_e32 v130, v141, v69
	v_add_f32_e32 v115, 1.0, v115
	v_exp_f32_e32 v99, v99
	v_add_f32_e32 v62, v62, v74
	v_add_f32_e32 v35, 1.0, v35
	v_exp_f32_e32 v3, v3
	v_mul_f32_e32 v136, v142, v136
	v_add_f32_e32 v142, v145, v81
	v_mul_f32_e32 v141, v130, v131
	v_lshl_add_u64 v[130:131], v[172:173], 0, v[182:183]
	v_cvt_pk_bf16_f32 v132, v134, v135
	v_rcp_f32_e32 v115, v115
	v_add_f32_e32 v82, v88, v68
	v_mul_f32_e32 v62, 0xbfb8aa3b, v62
	v_add_f32_e32 v63, v63, v75
	v_rcp_f32_e32 v35, v35
	v_mul_f32_e32 v137, v142, v137
	v_cvt_pk_bf16_f32 v133, v136, v137
	v_cvt_pk_bf16_f32 v134, v138, v139
	v_cvt_pk_bf16_f32 v135, v140, v141
	global_store_dwordx4 v[130:131], v[132:135], off
	v_mul_f32_e32 v88, v82, v83
	v_add_f32_e32 v83, v85, v61
	v_or_b32_e32 v132, 16, v174
	v_exp_f32_e32 v62, v62
	v_mul_f32_e32 v63, 0xbfb8aa3b, v63
	v_add_f32_e32 v64, v64, v76
	v_add_f32_e32 v50, v56, v68
	v_add_f32_e32 v42, v42, v74
	v_add_f32_e32 v19, 1.0, v19
	v_ashrrev_i32_e32 v133, 31, v132
	v_mul_f32_e32 v83, 0xbfb8aa3b, v83
	v_exp_f32_e32 v63, v63
	v_mul_f32_e32 v64, 0xbfb8aa3b, v64
	v_add_f32_e32 v65, v65, v77
	v_mul_f32_e32 v56, v50, v51
	v_add_f32_e32 v51, v53, v61
	v_mul_f32_e32 v42, 0xbfb8aa3b, v42
	v_add_f32_e32 v43, v43, v75
	v_rcp_f32_e32 v19, v19
	v_lshlrev_b64 v[132:133], 11, v[132:133]
	v_add_f32_e32 v114, v121, v69
	v_add_f32_e32 v99, 1.0, v99
	v_exp_f32_e32 v83, v83
	v_exp_f32_e32 v64, v64
	v_mul_f32_e32 v65, 0xbfb8aa3b, v65
	v_mul_f32_e32 v51, 0xbfb8aa3b, v51
	v_exp_f32_e32 v42, v42
	v_mul_f32_e32 v43, 0xbfb8aa3b, v43
	v_add_f32_e32 v44, v44, v76
	v_add_f32_e32 v34, v40, v68
	v_add_f32_e32 v26, v26, v74
	v_add_f32_e32 v3, 1.0, v3
	v_mul_f32_e32 v117, v114, v115
	v_lshl_add_u64 v[118:119], v[172:173], 0, v[132:133]
	v_cvt_pk_bf16_f32 v114, v122, v123
	v_rcp_f32_e32 v99, v99
	v_exp_f32_e32 v65, v65
	v_exp_f32_e32 v51, v51
	v_exp_f32_e32 v43, v43
	v_mul_f32_e32 v44, 0xbfb8aa3b, v44
	v_add_f32_e32 v45, v45, v77
	v_mul_f32_e32 v40, v34, v35
	v_add_f32_e32 v35, v37, v61
	v_mul_f32_e32 v26, 0xbfb8aa3b, v26
	v_add_f32_e32 v27, v27, v75
	v_rcp_f32_e32 v3, v3
	v_cvt_pk_bf16_f32 v115, v124, v125
	v_cvt_pk_bf16_f32 v116, v126, v127
	v_cvt_pk_bf16_f32 v117, v120, v117
	global_store_dwordx4 v[118:119], v[114:117], off
	v_add_f32_e32 v62, 1.0, v62
	v_exp_f32_e32 v44, v44
	v_or_b32_e32 v114, 32, v174
	v_mul_f32_e32 v45, 0xbfb8aa3b, v45
	v_mul_f32_e32 v35, 0xbfb8aa3b, v35
	v_exp_f32_e32 v26, v26
	v_mul_f32_e32 v27, 0xbfb8aa3b, v27
	v_add_f32_e32 v28, v28, v76
	v_add_f32_e32 v18, v24, v68
	v_add_f32_e32 v10, v10, v74
	v_ashrrev_i32_e32 v115, 31, v114
	v_rcp_f32_e32 v62, v62
	v_add_f32_e32 v63, 1.0, v63
	v_exp_f32_e32 v45, v45
	v_exp_f32_e32 v35, v35
	v_exp_f32_e32 v27, v27
	v_mul_f32_e32 v28, 0xbfb8aa3b, v28
	v_add_f32_e32 v29, v29, v77
	v_mul_f32_e32 v24, v18, v19
	v_add_f32_e32 v19, v21, v61
	v_mul_f32_e32 v10, 0xbfb8aa3b, v10
	v_add_f32_e32 v11, v11, v75
	v_lshlrev_b64 v[114:115], 11, v[114:115]
	v_add_f32_e32 v98, v105, v69
	v_add_f32_e32 v83, 1.0, v83
	v_rcp_f32_e32 v63, v63
	v_add_f32_e32 v64, 1.0, v64
	v_add_f32_e32 v42, 1.0, v42
	v_exp_f32_e32 v28, v28
	v_mul_f32_e32 v29, 0xbfb8aa3b, v29
	v_mul_f32_e32 v19, 0xbfb8aa3b, v19
	v_exp_f32_e32 v10, v10
	v_mul_f32_e32 v11, 0xbfb8aa3b, v11
	v_add_f32_e32 v12, v12, v76
	v_add_f32_e32 v2, v8, v68
	v_mul_f32_e32 v101, v98, v99
	v_lshl_add_u64 v[102:103], v[172:173], 0, v[114:115]
	v_cvt_pk_bf16_f32 v98, v106, v107
	v_rcp_f32_e32 v83, v83
	v_rcp_f32_e32 v64, v64
	v_add_f32_e32 v65, 1.0, v65
	v_add_f32_e32 v51, 1.0, v51
	v_rcp_f32_e32 v42, v42
	v_add_f32_e32 v43, 1.0, v43
	v_exp_f32_e32 v29, v29
	v_exp_f32_e32 v19, v19
	v_exp_f32_e32 v11, v11
	v_mul_f32_e32 v12, 0xbfb8aa3b, v12
	v_add_f32_e32 v13, v13, v77
	v_mul_f32_e32 v8, v2, v3
	v_add_f32_e32 v3, v5, v61
	v_cvt_pk_bf16_f32 v99, v108, v109
	v_cvt_pk_bf16_f32 v100, v110, v111
	v_cvt_pk_bf16_f32 v101, v104, v101
	global_store_dwordx4 v[102:103], v[98:101], off
	v_add_f32_e32 v70, v70, v78
	v_rcp_f32_e32 v65, v65
	v_or_b32_e32 v98, 48, v174
	v_rcp_f32_e32 v51, v51
	v_rcp_f32_e32 v43, v43
	v_add_f32_e32 v44, 1.0, v44
	v_add_f32_e32 v26, 1.0, v26
	v_exp_f32_e32 v12, v12
	v_mul_f32_e32 v13, 0xbfb8aa3b, v13
	v_mul_f32_e32 v3, 0xbfb8aa3b, v3
	v_ashrrev_i32_e32 v99, 31, v98
	v_mul_f32_e32 v62, v70, v62
	v_add_f32_e32 v70, v71, v79
	v_rcp_f32_e32 v44, v44
	v_add_f32_e32 v45, 1.0, v45
	v_add_f32_e32 v35, 1.0, v35
	v_rcp_f32_e32 v26, v26
	v_add_f32_e32 v27, 1.0, v27
	v_exp_f32_e32 v13, v13
	v_exp_f32_e32 v3, v3
	v_lshlrev_b64 v[98:99], 11, v[98:99]
	v_add_f32_e32 v82, v89, v69
	v_mul_f32_e32 v63, v70, v63
	v_add_f32_e32 v70, v72, v80
	v_add_f32_e32 v46, v46, v78
	v_rcp_f32_e32 v45, v45
	v_rcp_f32_e32 v35, v35
	v_rcp_f32_e32 v27, v27
	v_add_f32_e32 v28, 1.0, v28
	v_add_f32_e32 v10, 1.0, v10
	v_mul_f32_e32 v85, v82, v83
	v_lshl_add_u64 v[86:87], v[172:173], 0, v[98:99]
	v_mul_f32_e32 v64, v70, v64
	v_add_f32_e32 v70, v73, v81
	v_add_f32_e32 v50, v57, v69
	v_mul_f32_e32 v42, v46, v42
	v_add_f32_e32 v46, v47, v79
	v_rcp_f32_e32 v28, v28
	v_add_f32_e32 v29, 1.0, v29
	v_add_f32_e32 v19, 1.0, v19
	v_rcp_f32_e32 v10, v10
	v_add_f32_e32 v11, 1.0, v11
	v_cvt_pk_bf16_f32 v82, v90, v91
	v_cvt_pk_bf16_f32 v83, v92, v93
	v_cvt_pk_bf16_f32 v84, v94, v95
	v_cvt_pk_bf16_f32 v85, v88, v85
	global_store_dwordx4 v[86:87], v[82:85], off
	v_mul_f32_e32 v65, v70, v65
	v_mul_f32_e32 v53, v50, v51
	v_cvt_pk_bf16_f32 v50, v62, v63
	v_cvt_pk_bf16_f32 v51, v64, v65
	v_cvt_pk_bf16_f32 v52, v54, v55
	v_add_co_u32_e32 v54, vcc, s67, v130
	v_mul_f32_e32 v43, v46, v43
	v_add_f32_e32 v46, v48, v80
	v_add_f32_e32 v30, v30, v78
	v_rcp_f32_e32 v29, v29
	v_rcp_f32_e32 v19, v19
	v_rcp_f32_e32 v11, v11
	v_add_f32_e32 v12, 1.0, v12
	v_addc_co_u32_e32 v55, vcc, 0, v131, vcc
	v_mul_f32_e32 v44, v46, v44
	v_add_f32_e32 v46, v49, v81
	v_add_f32_e32 v34, v41, v69
	v_mul_f32_e32 v26, v30, v26
	v_add_f32_e32 v30, v31, v79
	v_rcp_f32_e32 v12, v12
	v_add_f32_e32 v13, 1.0, v13
	v_add_f32_e32 v3, 1.0, v3
	v_cvt_pk_bf16_f32 v53, v56, v53
	global_store_dwordx4 v[54:55], v[50:53], off
	v_mul_f32_e32 v45, v46, v45
	v_mul_f32_e32 v37, v34, v35
	v_cvt_pk_bf16_f32 v34, v42, v43
	v_cvt_pk_bf16_f32 v35, v44, v45
	v_cvt_pk_bf16_f32 v36, v38, v39
	v_add_co_u32_e32 v38, vcc, s68, v130
	v_mul_f32_e32 v27, v30, v27
	v_add_f32_e32 v30, v32, v80
	v_add_f32_e32 v14, v14, v78
	v_rcp_f32_e32 v13, v13
	v_rcp_f32_e32 v3, v3
	v_addc_co_u32_e32 v39, vcc, 0, v131, vcc
	v_mul_f32_e32 v28, v30, v28
	v_add_f32_e32 v30, v33, v81
	v_add_f32_e32 v18, v25, v69
	v_mul_f32_e32 v10, v14, v10
	v_add_f32_e32 v14, v15, v79
	v_cvt_pk_bf16_f32 v37, v40, v37
	global_store_dwordx4 v[38:39], v[34:37], off
	v_mul_f32_e32 v29, v30, v29
	v_mul_f32_e32 v21, v18, v19
	v_cvt_pk_bf16_f32 v18, v26, v27
	v_cvt_pk_bf16_f32 v19, v28, v29
	v_cvt_pk_bf16_f32 v20, v22, v23
	v_add_co_u32_e32 v22, vcc, s2, v130
	v_mul_f32_e32 v11, v14, v11
	v_add_f32_e32 v14, v16, v80
	v_addc_co_u32_e32 v23, vcc, 0, v131, vcc
	v_mul_f32_e32 v12, v14, v12
	v_add_f32_e32 v14, v17, v81
	v_add_f32_e32 v2, v9, v69
	v_cvt_pk_bf16_f32 v21, v24, v21
	global_store_dwordx4 v[22:23], v[18:21], off
	v_mul_f32_e32 v13, v14, v13
	v_mul_f32_e32 v5, v2, v3
	v_cvt_pk_bf16_f32 v2, v10, v11
	v_cvt_pk_bf16_f32 v3, v12, v13
	v_cvt_pk_bf16_f32 v4, v6, v7
	v_add_co_u32_e32 v6, vcc, 0x58000, v130
	s_mov_b32 s2, s48
	s_nop 0
	v_addc_co_u32_e32 v7, vcc, 0, v131, vcc
	s_and_b64 vcc, exec, s[38:39]
	v_cvt_pk_bf16_f32 v5, v8, v5
	global_store_dwordx4 v[6:7], v[2:5], off
	s_cbranch_vccz .LBB0_88
	s_waitcnt vmcnt(8)
	s_cmpk_gt_u32 s35, 0xff
	s_cbranch_scc1 .LBB0_99
	s_barrier

.LBB0_259:
	s_ashr_i32 s35, s34, 31
	v_cmp_lt_i64_e32 vcc, s[36:37], v[150:151]
	s_lshl_b64 s[36:37], s[34:35], 19
	s_add_u32 s36, s12, s36
	s_addc_u32 s37, s13, s37
	s_and_b64 s[42:43], vcc, exec
	s_cselect_b32 s35, s37, s1
	s_cselect_b32 s55, s36, s0
	s_ashr_i32 s31, s30, 31
	s_lshl_b64 s[42:43], s[30:31], 19
	s_add_u32 s42, s17, s42
	s_addc_u32 s43, s19, s43
	s_and_b64 s[46:47], vcc, exec
	s_cselect_b32 s31, s43, s23
	s_cselect_b32 s56, s42, s22
	s_add_u32 s0, s0, 0x40080
	s_addc_u32 s1, s1, 0
	s_add_u32 s57, s22, 0x100
	s_addc_u32 s58, s23, 0
	s_mov_b32 s59, -2
	v_mov_b64_e32 v[82:83], 0
	v_mov_b64_e32 v[84:85], 0
	s_nop 1
	v_mfma_f32_32x32x16_bf16 v[2:17], v[82:85], v[82:85], 0
	v_mov_b64_e32 v[114:115], 0
	v_mov_b64_e32 v[116:117], 0
	v_mov_b64_e32 v[118:119], 0
	v_mov_b64_e32 v[120:121], 0
	v_mov_b64_e32 v[122:123], 0
	v_mfma_f32_32x32x16_bf16 v[18:33], v[82:85], v[82:85], 0
	v_mov_b64_e32 v[124:125], 0
	v_mov_b64_e32 v[126:127], 0
	v_mov_b64_e32 v[128:129], 0
	v_mov_b64_e32 v[98:99], 0
	v_mov_b64_e32 v[100:101], 0
	v_mfma_f32_32x32x16_bf16 v[34:49], v[82:85], v[82:85], 0
	v_mov_b64_e32 v[102:103], 0
	v_mov_b64_e32 v[104:105], 0
	v_mov_b64_e32 v[106:107], 0
	v_mov_b64_e32 v[108:109], 0
	v_mov_b64_e32 v[110:111], 0
	v_mfma_f32_32x32x16_bf16 v[50:65], v[82:85], v[82:85], 0
	v_mov_b64_e32 v[112:113], 0
	v_mov_b64_e32 v[86:87], 0
	v_mov_b64_e32 v[88:89], 0
	v_mov_b64_e32 v[90:91], 0
	v_mov_b64_e32 v[92:93], 0
	v_mfma_f32_32x32x16_bf16 v[66:81], v[82:85], v[82:85], 0
	v_mov_b64_e32 v[94:95], 0
	v_mov_b64_e32 v[96:97], 0
.LBB0_260:
	s_add_u32 s22, s0, 0xfffc0080
	s_addc_u32 s23, s1, -1
	s_add_i32 s60, 0, 0x10000
	v_add_u32_e32 v142, s60, v178
	ds_read_b128 v[130:133], v142
	ds_read_b128 v[134:137], v142 offset:1024
	ds_read_b128 v[138:141], v142 offset:2048
	ds_read_b128 v[142:145], v142 offset:3072
	s_cmp_eq_u32 s59, 12
	s_cselect_b32 s47, s35, s23
	s_cselect_b32 s46, s55, s22
	s_cselect_b32 s23, s31, s58
	s_cselect_b32 s22, s56, s57
	v_lshl_add_u64 v[186:187], s[0:1], 0, v[168:169]
	s_add_i32 m0, s27, 0xc000
	ds_read_b128 v[172:175], v180
	ds_read_b128 v[182:185], v180 offset:1024
	ds_read_b128 v[206:209], v180 offset:2048
	ds_read_b128 v[210:213], v180 offset:3072
	ds_read_b128 v[214:217], v180 offset:4096
	ds_read_b128 v[218:221], v180 offset:5120
	ds_read_b128 v[222:225], v180 offset:6144
	ds_read_b128 v[226:229], v180 offset:7168
	global_load_lds_dwordx4 v[186:187], off
	v_lshl_add_u64 v[186:187], s[0:1], 0, v[170:171]
	s_add_i32 m0, s27, 0xe000
	s_nop 0
	global_load_lds_dwordx4 v[186:187], off
	s_waitcnt lgkmcnt(8)
	s_barrier
	s_waitcnt lgkmcnt(0)
	v_mfma_f32_16x16x32_bf16 v[126:129], v[130:133], v[172:175], v[126:129]
	v_mfma_f32_16x16x32_bf16 v[122:125], v[138:141], v[172:175], v[122:125]
	v_mfma_f32_16x16x32_bf16 v[110:113], v[130:133], v[206:209], v[110:113]
	v_mfma_f32_16x16x32_bf16 v[106:109], v[138:141], v[206:209], v[106:109]
	v_mfma_f32_16x16x32_bf16 v[94:97], v[130:133], v[214:217], v[94:97]
	v_mfma_f32_16x16x32_bf16 v[90:93], v[138:141], v[214:217], v[90:93]
	v_mfma_f32_16x16x32_bf16 v[78:81], v[130:133], v[222:225], v[78:81]
	v_mfma_f32_16x16x32_bf16 v[74:77], v[138:141], v[222:225], v[74:77]
	v_mfma_f32_16x16x32_bf16 v[126:129], v[134:137], v[182:185], v[126:129]
	v_mfma_f32_16x16x32_bf16 v[122:125], v[142:145], v[182:185], v[122:125]
	v_mfma_f32_16x16x32_bf16 v[110:113], v[134:137], v[210:213], v[110:113]
	v_mfma_f32_16x16x32_bf16 v[106:109], v[142:145], v[210:213], v[106:109]
	v_mfma_f32_16x16x32_bf16 v[94:97], v[134:137], v[218:221], v[94:97]
	v_mfma_f32_16x16x32_bf16 v[90:93], v[142:145], v[218:221], v[90:93]
	v_mfma_f32_16x16x32_bf16 v[78:81], v[134:137], v[226:229], v[78:81]
	v_mfma_f32_16x16x32_bf16 v[74:77], v[142:145], v[226:229], v[74:77]
	s_barrier
	s_add_i32 s62, 0, 0x14000
	s_add_i32 s60, s60, s25
	v_add_u32_e32 v181, s62, v178
	v_lshl_add_u64 v[186:187], s[22:23], 0, v[0:1]
	s_mov_b32 m0, s60
	ds_read_b128 v[230:233], v181
	ds_read_b128 v[234:237], v181 offset:1024
	ds_read_b128 v[238:241], v181 offset:2048
	ds_read_b128 v[242:245], v181 offset:3072
	global_load_lds_dwordx4 v[186:187], off
	v_lshl_add_u64 v[246:247], s[22:23], 0, v[162:163]
	s_add_i32 m0, s60, 0x2000
	s_nop 0
	global_load_lds_dwordx4 v[246:247], off
	s_barrier
	s_waitcnt lgkmcnt(0)
	v_mfma_f32_16x16x32_bf16 v[118:121], v[230:233], v[172:175], v[118:121]
	v_mfma_f32_16x16x32_bf16 v[114:117], v[238:241], v[172:175], v[114:117]
	v_mfma_f32_16x16x32_bf16 v[102:105], v[230:233], v[206:209], v[102:105]
	v_mfma_f32_16x16x32_bf16 v[98:101], v[238:241], v[206:209], v[98:101]
	v_mfma_f32_16x16x32_bf16 v[86:89], v[230:233], v[214:217], v[86:89]
	v_mfma_f32_16x16x32_bf16 v[82:85], v[238:241], v[214:217], v[82:85]
	v_mfma_f32_16x16x32_bf16 v[70:73], v[230:233], v[222:225], v[70:73]
	v_mfma_f32_16x16x32_bf16 v[66:69], v[238:241], v[222:225], v[66:69]
	v_mfma_f32_16x16x32_bf16 v[118:121], v[234:237], v[182:185], v[118:121]
	v_mfma_f32_16x16x32_bf16 v[114:117], v[242:245], v[182:185], v[114:117]
	v_mfma_f32_16x16x32_bf16 v[102:105], v[234:237], v[210:213], v[102:105]
	v_mfma_f32_16x16x32_bf16 v[98:101], v[242:245], v[210:213], v[98:101]
	v_mfma_f32_16x16x32_bf16 v[86:89], v[234:237], v[218:221], v[86:89]
	v_mfma_f32_16x16x32_bf16 v[82:85], v[242:245], v[218:221], v[82:85]
	v_mfma_f32_16x16x32_bf16 v[70:73], v[234:237], v[226:229], v[70:73]
	v_mfma_f32_16x16x32_bf16 v[66:69], v[242:245], v[226:229], v[66:69]
	s_barrier
	s_mov_b32 m0, s27
	v_lshl_add_u64 v[248:249], s[46:47], 0, v[166:167]
	ds_read_b128 v[172:175], v180 offset:16384
	ds_read_b128 v[182:185], v180 offset:17408
	ds_read_b128 v[206:209], v180 offset:18432
	ds_read_b128 v[210:213], v180 offset:19456
	ds_read_b128 v[214:217], v180 offset:20480
	ds_read_b128 v[218:221], v180 offset:21504
	ds_read_b128 v[222:225], v180 offset:22528
	ds_read_b128 v[226:229], v180 offset:23552
	global_load_lds_dwordx4 v[248:249], off
	v_lshl_add_u64 v[250:251], s[46:47], 0, v[164:165]
	s_mov_b32 m0, s45
	s_nop 0
	global_load_lds_dwordx4 v[250:251], off
	s_barrier
	s_waitcnt lgkmcnt(0)
	v_mfma_f32_16x16x32_bf16 v[62:65], v[130:133], v[172:175], v[62:65]
	v_mfma_f32_16x16x32_bf16 v[58:61], v[138:141], v[172:175], v[58:61]
	v_mfma_f32_16x16x32_bf16 v[50:53], v[130:133], v[206:209], v[50:53]
	v_mfma_f32_16x16x32_bf16 v[42:45], v[138:141], v[206:209], v[42:45]
	v_mfma_f32_16x16x32_bf16 v[34:37], v[130:133], v[214:217], v[34:37]
	v_mfma_f32_16x16x32_bf16 v[26:29], v[138:141], v[214:217], v[26:29]
	v_mfma_f32_16x16x32_bf16 v[18:21], v[130:133], v[222:225], v[18:21]
	v_mfma_f32_16x16x32_bf16 v[10:13], v[138:141], v[222:225], v[10:13]
	v_mfma_f32_16x16x32_bf16 v[62:65], v[134:137], v[182:185], v[62:65]
	v_mfma_f32_16x16x32_bf16 v[58:61], v[142:145], v[182:185], v[58:61]
	v_mfma_f32_16x16x32_bf16 v[50:53], v[134:137], v[210:213], v[50:53]
	v_mfma_f32_16x16x32_bf16 v[42:45], v[142:145], v[210:213], v[42:45]
	v_mfma_f32_16x16x32_bf16 v[34:37], v[134:137], v[218:221], v[34:37]
	v_mfma_f32_16x16x32_bf16 v[26:29], v[142:145], v[218:221], v[26:29]
	v_mfma_f32_16x16x32_bf16 v[18:21], v[134:137], v[226:229], v[18:21]
	v_mfma_f32_16x16x32_bf16 v[10:13], v[142:145], v[226:229], v[10:13]
	s_barrier
	s_add_u32 s60, s22, 0x40000
	s_addc_u32 s61, s23, 0
	s_add_i32 s62, s62, s25
	v_lshl_add_u64 v[130:131], s[60:61], 0, v[0:1]
	s_mov_b32 m0, s62
	s_nop 0
	global_load_lds_dwordx4 v[130:131], off
	v_lshl_add_u64 v[130:131], s[60:61], 0, v[162:163]
	s_add_i32 m0, s62, 0x2000
	s_nop 0
	global_load_lds_dwordx4 v[130:131], off
	s_waitcnt vmcnt(6)
	s_barrier
	v_mfma_f32_16x16x32_bf16 v[54:57], v[230:233], v[172:175], v[54:57]
	v_mfma_f32_16x16x32_bf16 v[46:49], v[238:241], v[172:175], v[46:49]
	v_mfma_f32_16x16x32_bf16 v[38:41], v[230:233], v[206:209], v[38:41]
	v_mfma_f32_16x16x32_bf16 v[30:33], v[238:241], v[206:209], v[30:33]
	v_mfma_f32_16x16x32_bf16 v[22:25], v[230:233], v[214:217], v[22:25]
	v_mfma_f32_16x16x32_bf16 v[14:17], v[238:241], v[214:217], v[14:17]
	v_mfma_f32_16x16x32_bf16 v[6:9], v[230:233], v[222:225], v[6:9]
	v_mfma_f32_16x16x32_bf16 v[2:5], v[238:241], v[222:225], v[2:5]
	v_mfma_f32_16x16x32_bf16 v[54:57], v[234:237], v[182:185], v[54:57]
	v_mfma_f32_16x16x32_bf16 v[46:49], v[242:245], v[182:185], v[46:49]
	v_mfma_f32_16x16x32_bf16 v[38:41], v[234:237], v[210:213], v[38:41]
	v_mfma_f32_16x16x32_bf16 v[30:33], v[242:245], v[210:213], v[30:33]
	v_mfma_f32_16x16x32_bf16 v[22:25], v[234:237], v[218:221], v[22:25]
	v_mfma_f32_16x16x32_bf16 v[14:17], v[242:245], v[218:221], v[14:17]
	v_mfma_f32_16x16x32_bf16 v[6:9], v[234:237], v[226:229], v[6:9]
	v_mfma_f32_16x16x32_bf16 v[2:5], v[242:245], v[226:229], v[2:5]
	s_barrier
	s_add_i32 s60, 0, 0x18000
	v_add_u32_e32 v142, s60, v178
	ds_read_b128 v[130:133], v142
	ds_read_b128 v[134:137], v142 offset:1024
	ds_read_b128 v[138:141], v142 offset:2048
	ds_read_b128 v[142:145], v142 offset:3072
	s_add_u32 s46, s46, 0x40000
	s_addc_u32 s47, s47, 0
	s_mov_b32 m0, s48
	v_lshl_add_u64 v[230:231], s[46:47], 0, v[166:167]
	ds_read_b128 v[172:175], v180 offset:32768
	ds_read_b128 v[182:185], v180 offset:33792
	ds_read_b128 v[206:209], v180 offset:34816
	ds_read_b128 v[210:213], v180 offset:35840
	ds_read_b128 v[214:217], v180 offset:36864
	ds_read_b128 v[218:221], v180 offset:37888
	ds_read_b128 v[222:225], v180 offset:38912
	ds_read_b128 v[226:229], v180 offset:39936
	global_load_lds_dwordx4 v[230:231], off
	v_lshl_add_u64 v[230:231], s[46:47], 0, v[164:165]
	s_mov_b32 m0, s49
	s_nop 0
	global_load_lds_dwordx4 v[230:231], off
	s_waitcnt lgkmcnt(8)
	s_barrier
	s_waitcnt lgkmcnt(0)
	v_mfma_f32_16x16x32_bf16 v[126:129], v[130:133], v[172:175], v[126:129]
	v_mfma_f32_16x16x32_bf16 v[122:125], v[138:141], v[172:175], v[122:125]
	v_mfma_f32_16x16x32_bf16 v[110:113], v[130:133], v[206:209], v[110:113]
	v_mfma_f32_16x16x32_bf16 v[106:109], v[138:141], v[206:209], v[106:109]
	v_mfma_f32_16x16x32_bf16 v[94:97], v[130:133], v[214:217], v[94:97]
	v_mfma_f32_16x16x32_bf16 v[90:93], v[138:141], v[214:217], v[90:93]
	v_mfma_f32_16x16x32_bf16 v[78:81], v[130:133], v[222:225], v[78:81]
	v_mfma_f32_16x16x32_bf16 v[74:77], v[138:141], v[222:225], v[74:77]
	v_mfma_f32_16x16x32_bf16 v[126:129], v[134:137], v[182:185], v[126:129]
	v_mfma_f32_16x16x32_bf16 v[122:125], v[142:145], v[182:185], v[122:125]
	v_mfma_f32_16x16x32_bf16 v[110:113], v[134:137], v[210:213], v[110:113]
	v_mfma_f32_16x16x32_bf16 v[106:109], v[142:145], v[210:213], v[106:109]
	v_mfma_f32_16x16x32_bf16 v[94:97], v[134:137], v[218:221], v[94:97]
	v_mfma_f32_16x16x32_bf16 v[90:93], v[142:145], v[218:221], v[90:93]
	v_mfma_f32_16x16x32_bf16 v[78:81], v[134:137], v[226:229], v[78:81]
	v_mfma_f32_16x16x32_bf16 v[74:77], v[142:145], v[226:229], v[74:77]
	s_barrier
	s_add_i32 s46, 0, 0x1c000
	s_add_i32 s47, s60, s25
	v_add_u32_e32 v181, s46, v178
	v_lshl_add_u64 v[186:187], v[186:187], 0, s[94:95]
	s_mov_b32 m0, s47
	ds_read_b128 v[230:233], v181
	ds_read_b128 v[234:237], v181 offset:1024
	ds_read_b128 v[238:241], v181 offset:2048
	ds_read_b128 v[242:245], v181 offset:3072
	global_load_lds_dwordx4 v[186:187], off
	v_lshl_add_u64 v[186:187], v[246:247], 0, s[94:95]
	s_add_i32 m0, s47, 0x2000
	s_nop 0
	global_load_lds_dwordx4 v[186:187], off
	s_barrier
	s_waitcnt lgkmcnt(0)
	v_mfma_f32_16x16x32_bf16 v[118:121], v[230:233], v[172:175], v[118:121]
	v_mfma_f32_16x16x32_bf16 v[114:117], v[238:241], v[172:175], v[114:117]
	v_mfma_f32_16x16x32_bf16 v[102:105], v[230:233], v[206:209], v[102:105]
	v_mfma_f32_16x16x32_bf16 v[98:101], v[238:241], v[206:209], v[98:101]
	v_mfma_f32_16x16x32_bf16 v[86:89], v[230:233], v[214:217], v[86:89]
	v_mfma_f32_16x16x32_bf16 v[82:85], v[238:241], v[214:217], v[82:85]
	v_mfma_f32_16x16x32_bf16 v[70:73], v[230:233], v[222:225], v[70:73]
	v_mfma_f32_16x16x32_bf16 v[66:69], v[238:241], v[222:225], v[66:69]
	v_mfma_f32_16x16x32_bf16 v[118:121], v[234:237], v[182:185], v[118:121]
	v_mfma_f32_16x16x32_bf16 v[114:117], v[242:245], v[182:185], v[114:117]
	v_mfma_f32_16x16x32_bf16 v[102:105], v[234:237], v[210:213], v[102:105]
	v_mfma_f32_16x16x32_bf16 v[98:101], v[242:245], v[210:213], v[98:101]
	v_mfma_f32_16x16x32_bf16 v[86:89], v[234:237], v[218:221], v[86:89]
	v_mfma_f32_16x16x32_bf16 v[82:85], v[242:245], v[218:221], v[82:85]
	v_mfma_f32_16x16x32_bf16 v[70:73], v[234:237], v[226:229], v[70:73]
	v_mfma_f32_16x16x32_bf16 v[66:69], v[242:245], v[226:229], v[66:69]
	s_barrier
	s_mov_b32 m0, s51
	v_lshl_add_u64 v[186:187], v[248:249], 0, s[94:95]
	ds_read_b128 v[172:175], v180 offset:49152
	ds_read_b128 v[182:185], v180 offset:50176
	ds_read_b128 v[206:209], v180 offset:51200
	ds_read_b128 v[210:213], v180 offset:52224
	ds_read_b128 v[214:217], v180 offset:53248
	ds_read_b128 v[218:221], v180 offset:54272
	ds_read_b128 v[222:225], v180 offset:55296
	ds_read_b128 v[226:229], v180 offset:56320
	global_load_lds_dwordx4 v[186:187], off
	v_lshl_add_u64 v[186:187], v[250:251], 0, s[94:95]
	s_mov_b32 m0, s52
	s_nop 0
	global_load_lds_dwordx4 v[186:187], off
	s_barrier
	s_waitcnt lgkmcnt(0)
	v_mfma_f32_16x16x32_bf16 v[62:65], v[130:133], v[172:175], v[62:65]
	v_mfma_f32_16x16x32_bf16 v[58:61], v[138:141], v[172:175], v[58:61]
	v_mfma_f32_16x16x32_bf16 v[50:53], v[130:133], v[206:209], v[50:53]
	v_mfma_f32_16x16x32_bf16 v[42:45], v[138:141], v[206:209], v[42:45]
	v_mfma_f32_16x16x32_bf16 v[34:37], v[130:133], v[214:217], v[34:37]
	v_mfma_f32_16x16x32_bf16 v[26:29], v[138:141], v[214:217], v[26:29]
	v_mfma_f32_16x16x32_bf16 v[18:21], v[130:133], v[222:225], v[18:21]
	v_mfma_f32_16x16x32_bf16 v[10:13], v[138:141], v[222:225], v[10:13]
	v_mfma_f32_16x16x32_bf16 v[62:65], v[134:137], v[182:185], v[62:65]
	v_mfma_f32_16x16x32_bf16 v[58:61], v[142:145], v[182:185], v[58:61]
	v_mfma_f32_16x16x32_bf16 v[50:53], v[134:137], v[210:213], v[50:53]
	v_mfma_f32_16x16x32_bf16 v[42:45], v[142:145], v[210:213], v[42:45]
	v_mfma_f32_16x16x32_bf16 v[34:37], v[134:137], v[218:221], v[34:37]
	v_mfma_f32_16x16x32_bf16 v[26:29], v[142:145], v[218:221], v[26:29]
	v_mfma_f32_16x16x32_bf16 v[18:21], v[134:137], v[226:229], v[18:21]
	v_mfma_f32_16x16x32_bf16 v[10:13], v[142:145], v[226:229], v[10:13]
	s_barrier
	s_add_u32 s22, s22, 0x40080
	s_addc_u32 s23, s23, 0
	s_add_i32 s46, s46, s25
	v_lshl_add_u64 v[130:131], s[22:23], 0, v[0:1]
	s_mov_b32 m0, s46
	s_nop 0
	global_load_lds_dwordx4 v[130:131], off
	v_lshl_add_u64 v[130:131], s[22:23], 0, v[162:163]
	s_add_i32 m0, s46, 0x2000
	s_nop 0
	global_load_lds_dwordx4 v[130:131], off
	s_waitcnt vmcnt(6)
	s_barrier
	v_mfma_f32_16x16x32_bf16 v[54:57], v[230:233], v[172:175], v[54:57]
	v_mfma_f32_16x16x32_bf16 v[46:49], v[238:241], v[172:175], v[46:49]
	v_mfma_f32_16x16x32_bf16 v[38:41], v[230:233], v[206:209], v[38:41]
	v_mfma_f32_16x16x32_bf16 v[30:33], v[238:241], v[206:209], v[30:33]
	v_mfma_f32_16x16x32_bf16 v[22:25], v[230:233], v[214:217], v[22:25]
	v_mfma_f32_16x16x32_bf16 v[14:17], v[238:241], v[214:217], v[14:17]
	v_mfma_f32_16x16x32_bf16 v[6:9], v[230:233], v[222:225], v[6:9]
	v_mfma_f32_16x16x32_bf16 v[2:5], v[238:241], v[222:225], v[2:5]
	v_mfma_f32_16x16x32_bf16 v[54:57], v[234:237], v[182:185], v[54:57]
	v_mfma_f32_16x16x32_bf16 v[46:49], v[242:245], v[182:185], v[46:49]
	v_mfma_f32_16x16x32_bf16 v[38:41], v[234:237], v[210:213], v[38:41]
	v_mfma_f32_16x16x32_bf16 v[30:33], v[242:245], v[210:213], v[30:33]
	v_mfma_f32_16x16x32_bf16 v[22:25], v[234:237], v[218:221], v[22:25]
	v_mfma_f32_16x16x32_bf16 v[14:17], v[242:245], v[218:221], v[14:17]
	v_mfma_f32_16x16x32_bf16 v[6:9], v[234:237], v[226:229], v[6:9]
	v_mfma_f32_16x16x32_bf16 v[2:5], v[242:245], v[226:229], v[2:5]
	s_barrier
	s_add_i32 s59, s59, 2
	s_add_u32 s0, s0, 0x100
	s_addc_u32 s1, s1, 0
	s_add_u32 s57, s57, 0x100
	s_addc_u32 s58, s58, 0
	s_cmp_gt_u32 s59, 13
	s_cbranch_scc0 .LBB0_260
	v_lshl_or_b32 v172, s54, 8, v179
	v_ashrrev_i32_e32 v173, 31, v172
	v_cndmask_b32_e64 v131, 0, 1, s[2:3]
	v_lshl_add_u64 v[174:175], v[172:173], 2, s[8:9]
	v_mov_b32_e32 v130, 0
	v_cmp_ne_u32_e64 s[0:1], 1, v131
	s_andn2_b64 vcc, exec, s[2:3]
	v_mov_b32_e32 v134, 0
	v_mov_b32_e32 v135, 0
	v_mov_b32_e32 v136, 0
	v_mov_b32_e32 v137, 0
	s_cbranch_vccnz .LBB0_263
	global_load_dwordx4 v[134:137], v[174:175], off

.LBB0_330:
	s_add_u32 s40, s22, 0x100
	s_addc_u32 s41, s23, 0
	s_mov_b32 s51, -2
	v_mov_b64_e32 v[82:83], 0
	v_mov_b64_e32 v[84:85], 0
	s_nop 1
	v_mfma_f32_32x32x16_bf16 v[2:17], v[82:85], v[82:85], 0
	v_mov_b64_e32 v[114:115], 0
	v_mov_b64_e32 v[116:117], 0
	v_mov_b64_e32 v[118:119], 0
	v_mov_b64_e32 v[120:121], 0
	v_mov_b64_e32 v[122:123], 0
	v_mfma_f32_32x32x16_bf16 v[18:33], v[82:85], v[82:85], 0
	v_mov_b64_e32 v[124:125], 0
	v_mov_b64_e32 v[126:127], 0
	v_mov_b64_e32 v[128:129], 0
	v_mov_b64_e32 v[98:99], 0
	v_mov_b64_e32 v[100:101], 0
	v_mfma_f32_32x32x16_bf16 v[34:49], v[82:85], v[82:85], 0
	v_mov_b64_e32 v[102:103], 0
	v_mov_b64_e32 v[104:105], 0
	v_mov_b64_e32 v[106:107], 0
	v_mov_b64_e32 v[108:109], 0
	v_mov_b64_e32 v[110:111], 0
	v_mfma_f32_32x32x16_bf16 v[50:65], v[82:85], v[82:85], 0
	v_mov_b64_e32 v[112:113], 0
	v_mov_b64_e32 v[86:87], 0
	v_mov_b64_e32 v[88:89], 0
	v_mov_b64_e32 v[90:91], 0
	v_mov_b64_e32 v[92:93], 0
	v_mfma_f32_32x32x16_bf16 v[66:81], v[82:85], v[82:85], 0
	v_mov_b64_e32 v[94:95], 0
	v_mov_b64_e32 v[96:97], 0
.LBB0_331:
	s_add_u32 s22, s24, 0x100
	s_addc_u32 s23, s25, 0
	s_add_i32 s52, 0, 0x10000
	v_add_u32_e32 v140, s52, v144
	ds_read_b128 v[164:167], v140
	ds_read_b128 v[168:171], v140 offset:1024
	ds_read_b128 v[172:175], v140 offset:2048
	ds_read_b128 v[176:179], v140 offset:3072
	s_cmp_eq_u32 s51, 40
	s_cselect_b32 s29, s3, s23
	s_cselect_b32 s28, s2, s22
	s_cselect_b32 s27, s1, s41
	s_cselect_b32 s26, s0, s40
	v_lshl_add_u64 v[140:141], s[24:25], 0, v[136:137]
	s_add_i32 m0, s35, 0xc000
	ds_read_b128 v[180:183], v162
	ds_read_b128 v[184:187], v162 offset:1024
	ds_read_b128 v[206:209], v162 offset:2048
	ds_read_b128 v[210:213], v162 offset:3072
	ds_read_b128 v[214:217], v162 offset:4096
	ds_read_b128 v[218:221], v162 offset:5120
	ds_read_b128 v[222:225], v162 offset:6144
	ds_read_b128 v[226:229], v162 offset:7168
	global_load_lds_dwordx4 v[140:141], off
	v_lshl_add_u64 v[140:141], s[24:25], 0, v[138:139]
	s_add_i32 m0, s35, 0xe000
	s_nop 0
	global_load_lds_dwordx4 v[140:141], off
	s_waitcnt lgkmcnt(8)
	s_barrier
	s_waitcnt lgkmcnt(0)
	v_mfma_f32_16x16x32_bf16 v[126:129], v[164:167], v[180:183], v[126:129]
	v_mfma_f32_16x16x32_bf16 v[122:125], v[172:175], v[180:183], v[122:125]
	v_mfma_f32_16x16x32_bf16 v[114:117], v[164:167], v[206:209], v[114:117]
	v_mfma_f32_16x16x32_bf16 v[106:109], v[172:175], v[206:209], v[106:109]
	v_mfma_f32_16x16x32_bf16 v[98:101], v[164:167], v[214:217], v[98:101]
	v_mfma_f32_16x16x32_bf16 v[90:93], v[172:175], v[214:217], v[90:93]
	v_mfma_f32_16x16x32_bf16 v[82:85], v[164:167], v[222:225], v[82:85]
	v_mfma_f32_16x16x32_bf16 v[74:77], v[172:175], v[222:225], v[74:77]
	v_mfma_f32_16x16x32_bf16 v[126:129], v[168:171], v[184:187], v[126:129]
	v_mfma_f32_16x16x32_bf16 v[122:125], v[176:179], v[184:187], v[122:125]
	v_mfma_f32_16x16x32_bf16 v[114:117], v[168:171], v[210:213], v[114:117]
	v_mfma_f32_16x16x32_bf16 v[106:109], v[176:179], v[210:213], v[106:109]
	v_mfma_f32_16x16x32_bf16 v[98:101], v[168:171], v[218:221], v[98:101]
	v_mfma_f32_16x16x32_bf16 v[90:93], v[176:179], v[218:221], v[90:93]
	v_mfma_f32_16x16x32_bf16 v[82:85], v[168:171], v[226:229], v[82:85]
	v_mfma_f32_16x16x32_bf16 v[74:77], v[176:179], v[226:229], v[74:77]
	s_barrier
	s_add_i32 s53, 0, 0x14000
	v_add_u32_e32 v140, s53, v144
	s_add_i32 s24, s52, s31
	ds_read_b128 v[230:233], v140
	ds_read_b128 v[234:237], v140 offset:1024
	ds_read_b128 v[238:241], v140 offset:2048
	ds_read_b128 v[242:245], v140 offset:3072
	v_lshl_add_u64 v[140:141], s[26:27], 0, v[0:1]
	s_mov_b32 m0, s24
	v_lshl_add_u64 v[246:247], s[26:27], 0, v[130:131]
	global_load_lds_dwordx4 v[140:141], off
	s_add_i32 m0, s24, 0x2000
	s_nop 0
	global_load_lds_dwordx4 v[246:247], off
	s_barrier
	s_waitcnt lgkmcnt(0)
	v_mfma_f32_16x16x32_bf16 v[118:121], v[230:233], v[180:183], v[118:121]
	v_mfma_f32_16x16x32_bf16 v[110:113], v[238:241], v[180:183], v[110:113]
	v_mfma_f32_16x16x32_bf16 v[102:105], v[230:233], v[206:209], v[102:105]
	v_mfma_f32_16x16x32_bf16 v[94:97], v[238:241], v[206:209], v[94:97]
	v_mfma_f32_16x16x32_bf16 v[86:89], v[230:233], v[214:217], v[86:89]
	v_mfma_f32_16x16x32_bf16 v[78:81], v[238:241], v[214:217], v[78:81]
	v_mfma_f32_16x16x32_bf16 v[70:73], v[230:233], v[222:225], v[70:73]
	v_mfma_f32_16x16x32_bf16 v[66:69], v[238:241], v[222:225], v[66:69]
	v_mfma_f32_16x16x32_bf16 v[118:121], v[234:237], v[184:187], v[118:121]
	v_mfma_f32_16x16x32_bf16 v[110:113], v[242:245], v[184:187], v[110:113]
	v_mfma_f32_16x16x32_bf16 v[102:105], v[234:237], v[210:213], v[102:105]
	v_mfma_f32_16x16x32_bf16 v[94:97], v[242:245], v[210:213], v[94:97]
	v_mfma_f32_16x16x32_bf16 v[86:89], v[234:237], v[218:221], v[86:89]
	v_mfma_f32_16x16x32_bf16 v[78:81], v[242:245], v[218:221], v[78:81]
	v_mfma_f32_16x16x32_bf16 v[70:73], v[234:237], v[226:229], v[70:73]
	v_mfma_f32_16x16x32_bf16 v[66:69], v[242:245], v[226:229], v[66:69]
	s_barrier
	s_mov_b32 m0, s35
	v_lshl_add_u64 v[248:249], s[28:29], 0, v[134:135]
	ds_read_b128 v[180:183], v162 offset:16384
	ds_read_b128 v[184:187], v162 offset:17408
	ds_read_b128 v[206:209], v162 offset:18432
	ds_read_b128 v[210:213], v162 offset:19456
	ds_read_b128 v[214:217], v162 offset:20480
	ds_read_b128 v[218:221], v162 offset:21504
	ds_read_b128 v[222:225], v162 offset:22528
	ds_read_b128 v[226:229], v162 offset:23552
	global_load_lds_dwordx4 v[248:249], off
	v_lshl_add_u64 v[250:251], s[28:29], 0, v[132:133]
	s_mov_b32 m0, s36
	s_nop 0
	global_load_lds_dwordx4 v[250:251], off
	s_barrier
	s_waitcnt lgkmcnt(0)
	v_mfma_f32_16x16x32_bf16 v[62:65], v[164:167], v[180:183], v[62:65]
	v_mfma_f32_16x16x32_bf16 v[58:61], v[172:175], v[180:183], v[58:61]
	v_mfma_f32_16x16x32_bf16 v[50:53], v[164:167], v[206:209], v[50:53]
	v_mfma_f32_16x16x32_bf16 v[42:45], v[172:175], v[206:209], v[42:45]
	v_mfma_f32_16x16x32_bf16 v[34:37], v[164:167], v[214:217], v[34:37]
	v_mfma_f32_16x16x32_bf16 v[26:29], v[172:175], v[214:217], v[26:29]
	v_mfma_f32_16x16x32_bf16 v[18:21], v[164:167], v[222:225], v[18:21]
	v_mfma_f32_16x16x32_bf16 v[10:13], v[172:175], v[222:225], v[10:13]
	v_mfma_f32_16x16x32_bf16 v[62:65], v[168:171], v[184:187], v[62:65]
	v_mfma_f32_16x16x32_bf16 v[58:61], v[176:179], v[184:187], v[58:61]
	v_mfma_f32_16x16x32_bf16 v[50:53], v[168:171], v[210:213], v[50:53]
	v_mfma_f32_16x16x32_bf16 v[42:45], v[176:179], v[210:213], v[42:45]
	v_mfma_f32_16x16x32_bf16 v[34:37], v[168:171], v[218:221], v[34:37]
	v_mfma_f32_16x16x32_bf16 v[26:29], v[176:179], v[218:221], v[26:29]
	v_mfma_f32_16x16x32_bf16 v[18:21], v[168:171], v[226:229], v[18:21]
	v_mfma_f32_16x16x32_bf16 v[10:13], v[176:179], v[226:229], v[10:13]
	s_barrier
	s_add_u32 s24, s26, 0xb0000
	s_addc_u32 s25, s27, 0
	s_add_i32 s52, s53, s31
	v_lshl_add_u64 v[164:165], s[24:25], 0, v[0:1]
	s_mov_b32 m0, s52
	s_nop 0
	global_load_lds_dwordx4 v[164:165], off
	v_lshl_add_u64 v[164:165], s[24:25], 0, v[130:131]
	s_add_i32 m0, s52, 0x2000
	s_nop 0
	global_load_lds_dwordx4 v[164:165], off
	s_waitcnt vmcnt(6)
	s_barrier
	v_mfma_f32_16x16x32_bf16 v[54:57], v[230:233], v[180:183], v[54:57]
	v_mfma_f32_16x16x32_bf16 v[46:49], v[238:241], v[180:183], v[46:49]
	v_mfma_f32_16x16x32_bf16 v[38:41], v[230:233], v[206:209], v[38:41]
	v_mfma_f32_16x16x32_bf16 v[30:33], v[238:241], v[206:209], v[30:33]
	v_mfma_f32_16x16x32_bf16 v[22:25], v[230:233], v[214:217], v[22:25]
	v_mfma_f32_16x16x32_bf16 v[14:17], v[238:241], v[214:217], v[14:17]
	v_mfma_f32_16x16x32_bf16 v[6:9], v[230:233], v[222:225], v[6:9]
	v_mfma_f32_16x16x32_bf16 v[2:5], v[238:241], v[222:225], v[2:5]
	v_mfma_f32_16x16x32_bf16 v[54:57], v[234:237], v[184:187], v[54:57]
	v_mfma_f32_16x16x32_bf16 v[46:49], v[242:245], v[184:187], v[46:49]
	v_mfma_f32_16x16x32_bf16 v[38:41], v[234:237], v[210:213], v[38:41]
	v_mfma_f32_16x16x32_bf16 v[30:33], v[242:245], v[210:213], v[30:33]
	v_mfma_f32_16x16x32_bf16 v[22:25], v[234:237], v[218:221], v[22:25]
	v_mfma_f32_16x16x32_bf16 v[14:17], v[242:245], v[218:221], v[14:17]
	v_mfma_f32_16x16x32_bf16 v[6:9], v[234:237], v[226:229], v[6:9]
	v_mfma_f32_16x16x32_bf16 v[2:5], v[242:245], v[226:229], v[2:5]
	s_barrier
	s_add_i32 s52, 0, 0x18000
	v_add_u32_e32 v163, s52, v144
	ds_read_b128 v[164:167], v163
	ds_read_b128 v[168:171], v163 offset:1024
	ds_read_b128 v[172:175], v163 offset:2048
	ds_read_b128 v[176:179], v163 offset:3072
	s_add_u32 s24, s28, 0xb0000
	s_addc_u32 s25, s29, 0
	s_mov_b32 m0, s37
	v_lshl_add_u64 v[230:231], s[24:25], 0, v[134:135]
	ds_read_b128 v[180:183], v162 offset:32768
	ds_read_b128 v[184:187], v162 offset:33792
	ds_read_b128 v[206:209], v162 offset:34816
	ds_read_b128 v[210:213], v162 offset:35840
	ds_read_b128 v[214:217], v162 offset:36864
	ds_read_b128 v[218:221], v162 offset:37888
	ds_read_b128 v[222:225], v162 offset:38912
	ds_read_b128 v[226:229], v162 offset:39936
	global_load_lds_dwordx4 v[230:231], off
	v_lshl_add_u64 v[230:231], s[24:25], 0, v[132:133]
	s_mov_b32 m0, s42
	s_nop 0
	global_load_lds_dwordx4 v[230:231], off
	s_waitcnt lgkmcnt(8)
	s_barrier
	s_waitcnt lgkmcnt(0)
	v_mfma_f32_16x16x32_bf16 v[126:129], v[164:167], v[180:183], v[126:129]
	v_mfma_f32_16x16x32_bf16 v[122:125], v[172:175], v[180:183], v[122:125]
	v_mfma_f32_16x16x32_bf16 v[114:117], v[164:167], v[206:209], v[114:117]
	v_mfma_f32_16x16x32_bf16 v[106:109], v[172:175], v[206:209], v[106:109]
	v_mfma_f32_16x16x32_bf16 v[98:101], v[164:167], v[214:217], v[98:101]
	v_mfma_f32_16x16x32_bf16 v[90:93], v[172:175], v[214:217], v[90:93]
	v_mfma_f32_16x16x32_bf16 v[82:85], v[164:167], v[222:225], v[82:85]
	v_mfma_f32_16x16x32_bf16 v[74:77], v[172:175], v[222:225], v[74:77]
	v_mfma_f32_16x16x32_bf16 v[126:129], v[168:171], v[184:187], v[126:129]
	v_mfma_f32_16x16x32_bf16 v[122:125], v[176:179], v[184:187], v[122:125]
	v_mfma_f32_16x16x32_bf16 v[114:117], v[168:171], v[210:213], v[114:117]
	v_mfma_f32_16x16x32_bf16 v[106:109], v[176:179], v[210:213], v[106:109]
	v_mfma_f32_16x16x32_bf16 v[98:101], v[168:171], v[218:221], v[98:101]
	v_mfma_f32_16x16x32_bf16 v[90:93], v[176:179], v[218:221], v[90:93]
	v_mfma_f32_16x16x32_bf16 v[82:85], v[168:171], v[226:229], v[82:85]
	v_mfma_f32_16x16x32_bf16 v[74:77], v[176:179], v[226:229], v[74:77]
	s_barrier
	s_add_i32 s28, 0, 0x1c000
	s_add_i32 s24, s52, s31
	v_add_u32_e32 v163, s28, v144
	v_lshl_add_u64 v[140:141], v[140:141], 0, s[94:95]
	s_mov_b32 m0, s24
	ds_read_b128 v[230:233], v163
	ds_read_b128 v[234:237], v163 offset:1024
	ds_read_b128 v[238:241], v163 offset:2048
	ds_read_b128 v[242:245], v163 offset:3072
	global_load_lds_dwordx4 v[140:141], off
	v_lshl_add_u64 v[140:141], v[246:247], 0, s[94:95]
	s_add_i32 m0, s24, 0x2000
	s_nop 0
	global_load_lds_dwordx4 v[140:141], off
	s_barrier
	s_waitcnt lgkmcnt(0)
	v_mfma_f32_16x16x32_bf16 v[118:121], v[230:233], v[180:183], v[118:121]
	v_mfma_f32_16x16x32_bf16 v[110:113], v[238:241], v[180:183], v[110:113]
	v_mfma_f32_16x16x32_bf16 v[102:105], v[230:233], v[206:209], v[102:105]
	v_mfma_f32_16x16x32_bf16 v[94:97], v[238:241], v[206:209], v[94:97]
	v_mfma_f32_16x16x32_bf16 v[86:89], v[230:233], v[214:217], v[86:89]
	v_mfma_f32_16x16x32_bf16 v[78:81], v[238:241], v[214:217], v[78:81]
	v_mfma_f32_16x16x32_bf16 v[70:73], v[230:233], v[222:225], v[70:73]
	v_mfma_f32_16x16x32_bf16 v[66:69], v[238:241], v[222:225], v[66:69]
	v_mfma_f32_16x16x32_bf16 v[118:121], v[234:237], v[184:187], v[118:121]
	v_mfma_f32_16x16x32_bf16 v[110:113], v[242:245], v[184:187], v[110:113]
	v_mfma_f32_16x16x32_bf16 v[102:105], v[234:237], v[210:213], v[102:105]
	v_mfma_f32_16x16x32_bf16 v[94:97], v[242:245], v[210:213], v[94:97]
	v_mfma_f32_16x16x32_bf16 v[86:89], v[234:237], v[218:221], v[86:89]
	v_mfma_f32_16x16x32_bf16 v[78:81], v[242:245], v[218:221], v[78:81]
	v_mfma_f32_16x16x32_bf16 v[70:73], v[234:237], v[226:229], v[70:73]
	v_mfma_f32_16x16x32_bf16 v[66:69], v[242:245], v[226:229], v[66:69]
	s_barrier
	s_mov_b32 m0, s44
	v_lshl_add_u64 v[140:141], v[248:249], 0, s[94:95]
	ds_read_b128 v[180:183], v162 offset:49152
	ds_read_b128 v[184:187], v162 offset:50176
	ds_read_b128 v[206:209], v162 offset:51200
	ds_read_b128 v[210:213], v162 offset:52224
	ds_read_b128 v[214:217], v162 offset:53248
	ds_read_b128 v[218:221], v162 offset:54272
	ds_read_b128 v[222:225], v162 offset:55296
	ds_read_b128 v[226:229], v162 offset:56320
	global_load_lds_dwordx4 v[140:141], off
	v_lshl_add_u64 v[140:141], v[250:251], 0, s[94:95]
	s_mov_b32 m0, s45
	s_nop 0
	global_load_lds_dwordx4 v[140:141], off
	s_barrier
	s_waitcnt lgkmcnt(0)
	v_mfma_f32_16x16x32_bf16 v[62:65], v[164:167], v[180:183], v[62:65]
	v_mfma_f32_16x16x32_bf16 v[58:61], v[172:175], v[180:183], v[58:61]
	v_mfma_f32_16x16x32_bf16 v[50:53], v[164:167], v[206:209], v[50:53]
	v_mfma_f32_16x16x32_bf16 v[42:45], v[172:175], v[206:209], v[42:45]
	v_mfma_f32_16x16x32_bf16 v[34:37], v[164:167], v[214:217], v[34:37]
	v_mfma_f32_16x16x32_bf16 v[26:29], v[172:175], v[214:217], v[26:29]
	v_mfma_f32_16x16x32_bf16 v[18:21], v[164:167], v[222:225], v[18:21]
	v_mfma_f32_16x16x32_bf16 v[10:13], v[172:175], v[222:225], v[10:13]
	v_mfma_f32_16x16x32_bf16 v[62:65], v[168:171], v[184:187], v[62:65]
	v_mfma_f32_16x16x32_bf16 v[58:61], v[176:179], v[184:187], v[58:61]
	v_mfma_f32_16x16x32_bf16 v[50:53], v[168:171], v[210:213], v[50:53]
	v_mfma_f32_16x16x32_bf16 v[42:45], v[176:179], v[210:213], v[42:45]
	v_mfma_f32_16x16x32_bf16 v[34:37], v[168:171], v[218:221], v[34:37]
	v_mfma_f32_16x16x32_bf16 v[26:29], v[176:179], v[218:221], v[26:29]
	v_mfma_f32_16x16x32_bf16 v[18:21], v[168:171], v[226:229], v[18:21]
	v_mfma_f32_16x16x32_bf16 v[10:13], v[176:179], v[226:229], v[10:13]
	s_barrier
	s_add_u32 s24, s26, 0xb0080
	s_addc_u32 s25, s27, 0
	s_add_i32 s26, s28, s31
	v_lshl_add_u64 v[140:141], s[24:25], 0, v[0:1]
	s_mov_b32 m0, s26
	s_nop 0
	global_load_lds_dwordx4 v[140:141], off
	v_lshl_add_u64 v[140:141], s[24:25], 0, v[130:131]
	s_add_i32 m0, s26, 0x2000
	s_nop 0
	global_load_lds_dwordx4 v[140:141], off
	s_waitcnt vmcnt(6)
	s_barrier
	v_mfma_f32_16x16x32_bf16 v[54:57], v[230:233], v[180:183], v[54:57]
	v_mfma_f32_16x16x32_bf16 v[46:49], v[238:241], v[180:183], v[46:49]
	v_mfma_f32_16x16x32_bf16 v[38:41], v[230:233], v[206:209], v[38:41]
	v_mfma_f32_16x16x32_bf16 v[30:33], v[238:241], v[206:209], v[30:33]
	v_mfma_f32_16x16x32_bf16 v[22:25], v[230:233], v[214:217], v[22:25]
	v_mfma_f32_16x16x32_bf16 v[14:17], v[238:241], v[214:217], v[14:17]
	v_mfma_f32_16x16x32_bf16 v[6:9], v[230:233], v[222:225], v[6:9]
	v_mfma_f32_16x16x32_bf16 v[2:5], v[238:241], v[222:225], v[2:5]
	v_mfma_f32_16x16x32_bf16 v[54:57], v[234:237], v[184:187], v[54:57]
	v_mfma_f32_16x16x32_bf16 v[46:49], v[242:245], v[184:187], v[46:49]
	v_mfma_f32_16x16x32_bf16 v[38:41], v[234:237], v[210:213], v[38:41]
	v_mfma_f32_16x16x32_bf16 v[30:33], v[242:245], v[210:213], v[30:33]
	v_mfma_f32_16x16x32_bf16 v[22:25], v[234:237], v[218:221], v[22:25]
	v_mfma_f32_16x16x32_bf16 v[14:17], v[242:245], v[218:221], v[14:17]
	v_mfma_f32_16x16x32_bf16 v[6:9], v[234:237], v[226:229], v[6:9]
	v_mfma_f32_16x16x32_bf16 v[2:5], v[242:245], v[226:229], v[2:5]
	s_barrier
	s_add_i32 s51, s51, 2
	s_add_u32 s40, s40, 0x100
	s_addc_u32 s41, s41, 0
	s_cmp_gt_u32 s51, 41
	s_mov_b64 s[24:25], s[22:23]
	s_cbranch_scc0 .LBB0_331
	v_lshl_or_b32 v140, s50, 8, v145
	v_lshl_add_u32 v164, s49, 8, v143
	v_ashrrev_i32_e32 v141, 31, v140
	v_ashrrev_i32_e32 v165, 31, v164
	v_lshl_add_u64 v[166:167], v[140:141], 1, s[20:21]
	v_lshlrev_b64 v[140:141], 11, v[164:165]
	v_lshl_add_u64 v[140:141], v[166:167], 0, v[140:141]
	v_pk_add_f32 v[128:129], v[128:129], 0 op_sel_hi:[1,0]
	v_pk_add_f32 v[126:127], v[126:127], 0 op_sel_hi:[1,0]
	v_pk_add_f32 v[168:169], v[124:125], 0 op_sel_hi:[1,0]
	v_pk_add_f32 v[124:125], v[122:123], 0 op_sel_hi:[1,0]
	v_cvt_pk_bf16_f32 v122, v126, v127
	v_cvt_pk_bf16_f32 v123, v128, v129
	v_pk_add_f32 v[118:119], v[118:119], 0 op_sel_hi:[1,0]
	v_cvt_pk_bf16_f32 v124, v124, v125
	v_cvt_pk_bf16_f32 v125, v168, v169
	global_store_dwordx4 v[140:141], v[122:125], off
	v_pk_add_f32 v[120:121], v[120:121], 0 op_sel_hi:[1,0]
	v_pk_add_f32 v[114:115], v[114:115], 0 op_sel_hi:[1,0]
	v_pk_add_f32 v[122:123], v[112:113], 0 op_sel_hi:[1,0]
	v_pk_add_f32 v[112:113], v[110:111], 0 op_sel_hi:[1,0]
	v_cvt_pk_bf16_f32 v110, v118, v119
	v_cvt_pk_bf16_f32 v111, v120, v121
	v_pk_add_f32 v[102:103], v[102:103], 0 op_sel_hi:[1,0]
	v_cvt_pk_bf16_f32 v112, v112, v113
	v_cvt_pk_bf16_f32 v113, v122, v123
	global_store_dwordx4 v[140:141], v[110:113], off offset:256
	v_pk_add_f32 v[104:105], v[104:105], 0 op_sel_hi:[1,0]
	v_pk_add_f32 v[98:99], v[98:99], 0 op_sel_hi:[1,0]
	v_or_b32_e32 v110, 16, v164
	v_ashrrev_i32_e32 v111, 31, v110
	v_lshlrev_b64 v[110:111], 11, v[110:111]
	v_lshl_add_u64 v[110:111], v[166:167], 0, v[110:111]
	v_pk_add_f32 v[112:113], v[116:117], 0 op_sel_hi:[1,0]
	v_pk_add_f32 v[116:117], v[108:109], 0 op_sel_hi:[1,0]
	v_pk_add_f32 v[108:109], v[106:107], 0 op_sel_hi:[1,0]
	v_cvt_pk_bf16_f32 v106, v114, v115
	v_cvt_pk_bf16_f32 v107, v112, v113
	v_pk_add_f32 v[86:87], v[86:87], 0 op_sel_hi:[1,0]
	v_cvt_pk_bf16_f32 v108, v108, v109
	v_cvt_pk_bf16_f32 v109, v116, v117
	global_store_dwordx4 v[110:111], v[106:109], off
	v_pk_add_f32 v[88:89], v[88:89], 0 op_sel_hi:[1,0]
	v_pk_add_f32 v[82:83], v[82:83], 0 op_sel_hi:[1,0]
	v_pk_add_f32 v[106:107], v[96:97], 0 op_sel_hi:[1,0]
	v_pk_add_f32 v[96:97], v[94:95], 0 op_sel_hi:[1,0]
	v_cvt_pk_bf16_f32 v94, v102, v103
	v_cvt_pk_bf16_f32 v95, v104, v105
	v_pk_add_f32 v[72:73], v[72:73], 0 op_sel_hi:[1,0]
	v_cvt_pk_bf16_f32 v96, v96, v97
	v_cvt_pk_bf16_f32 v97, v106, v107
	global_store_dwordx4 v[110:111], v[94:97], off offset:256
	v_pk_add_f32 v[70:71], v[70:71], 0 op_sel_hi:[1,0]
	v_pk_add_f32 v[62:63], v[62:63], 0 op_sel_hi:[1,0]
	v_or_b32_e32 v94, 32, v164
	v_ashrrev_i32_e32 v95, 31, v94
	v_lshlrev_b64 v[94:95], 11, v[94:95]
	v_lshl_add_u64 v[94:95], v[166:167], 0, v[94:95]
	v_pk_add_f32 v[96:97], v[100:101], 0 op_sel_hi:[1,0]
	v_pk_add_f32 v[100:101], v[92:93], 0 op_sel_hi:[1,0]
	v_pk_add_f32 v[92:93], v[90:91], 0 op_sel_hi:[1,0]
	v_cvt_pk_bf16_f32 v90, v98, v99
	v_cvt_pk_bf16_f32 v91, v96, v97
	v_pk_add_f32 v[64:65], v[64:65], 0 op_sel_hi:[1,0]
	v_cvt_pk_bf16_f32 v92, v92, v93
	v_cvt_pk_bf16_f32 v93, v100, v101
	global_store_dwordx4 v[94:95], v[90:93], off
	s_mov_b64 s[22:23], 0x40000
	v_pk_add_f32 v[56:57], v[56:57], 0 op_sel_hi:[1,0]
	v_pk_add_f32 v[90:91], v[80:81], 0 op_sel_hi:[1,0]
	v_pk_add_f32 v[80:81], v[78:79], 0 op_sel_hi:[1,0]
	v_cvt_pk_bf16_f32 v78, v86, v87
	v_cvt_pk_bf16_f32 v79, v88, v89
	v_pk_add_f32 v[54:55], v[54:55], 0 op_sel_hi:[1,0]
	v_cvt_pk_bf16_f32 v80, v80, v81
	v_cvt_pk_bf16_f32 v81, v90, v91
	global_store_dwordx4 v[94:95], v[78:81], off offset:256
	v_pk_add_f32 v[50:51], v[50:51], 0 op_sel_hi:[1,0]
	v_pk_add_f32 v[40:41], v[40:41], 0 op_sel_hi:[1,0]
	v_or_b32_e32 v78, 48, v164
	v_ashrrev_i32_e32 v79, 31, v78
	v_lshlrev_b64 v[78:79], 11, v[78:79]
	v_lshl_add_u64 v[78:79], v[166:167], 0, v[78:79]
	v_pk_add_f32 v[80:81], v[84:85], 0 op_sel_hi:[1,0]
	v_pk_add_f32 v[84:85], v[76:77], 0 op_sel_hi:[1,0]
	v_pk_add_f32 v[76:77], v[74:75], 0 op_sel_hi:[1,0]
	v_cvt_pk_bf16_f32 v74, v82, v83
	v_cvt_pk_bf16_f32 v75, v80, v81
	v_pk_add_f32 v[38:39], v[38:39], 0 op_sel_hi:[1,0]
	v_cvt_pk_bf16_f32 v76, v76, v77
	v_cvt_pk_bf16_f32 v77, v84, v85
	global_store_dwordx4 v[78:79], v[74:77], off
	v_pk_add_f32 v[34:35], v[34:35], 0 op_sel_hi:[1,0]
	v_pk_add_f32 v[24:25], v[24:25], 0 op_sel_hi:[1,0]
	v_pk_add_f32 v[74:75], v[68:69], 0 op_sel_hi:[1,0]
	v_pk_add_f32 v[68:69], v[66:67], 0 op_sel_hi:[1,0]
	v_cvt_pk_bf16_f32 v66, v70, v71
	v_cvt_pk_bf16_f32 v67, v72, v73
	v_pk_add_f32 v[22:23], v[22:23], 0 op_sel_hi:[1,0]
	v_cvt_pk_bf16_f32 v68, v68, v69
	v_cvt_pk_bf16_f32 v69, v74, v75
	global_store_dwordx4 v[78:79], v[66:69], off offset:256
	v_pk_add_f32 v[18:19], v[18:19], 0 op_sel_hi:[1,0]
	s_mov_b32 s50, s47
	v_pk_add_f32 v[68:69], v[60:61], 0 op_sel_hi:[1,0]
	v_pk_add_f32 v[60:61], v[58:59], 0 op_sel_hi:[1,0]
	v_cvt_pk_bf16_f32 v58, v62, v63
	v_add_co_u32_e32 v62, vcc, s67, v140
	v_cvt_pk_bf16_f32 v59, v64, v65
	v_cvt_pk_bf16_f32 v60, v60, v61
	v_cvt_pk_bf16_f32 v61, v68, v69
	v_lshl_add_u64 v[66:67], v[140:141], 0, s[22:23]
	s_nop 0
	v_addc_co_u32_e32 v63, vcc, 0, v141, vcc
	global_store_dwordx4 v[62:63], v[58:61], off
	s_mov_b64 s[22:23], 0x48000
	s_mov_b32 s49, s48
	v_pk_add_f32 v[58:59], v[48:49], 0 op_sel_hi:[1,0]
	v_pk_add_f32 v[48:49], v[46:47], 0 op_sel_hi:[1,0]
	v_cvt_pk_bf16_f32 v46, v54, v55
	v_cvt_pk_bf16_f32 v47, v56, v57
	s_mov_b64 s[24:25], s[2:3]
	v_cvt_pk_bf16_f32 v48, v48, v49
	v_cvt_pk_bf16_f32 v49, v58, v59
	global_store_dwordx4 v[66:67], v[46:49], off offset:256
	v_pk_add_f32 v[8:9], v[8:9], 0 op_sel_hi:[1,0]
	v_pk_add_f32 v[6:7], v[6:7], 0 op_sel_hi:[1,0]
	v_pk_add_f32 v[48:49], v[52:53], 0 op_sel_hi:[1,0]
	v_pk_add_f32 v[52:53], v[44:45], 0 op_sel_hi:[1,0]
	v_pk_add_f32 v[44:45], v[42:43], 0 op_sel_hi:[1,0]
	v_cvt_pk_bf16_f32 v42, v50, v51
	v_cvt_pk_bf16_f32 v43, v48, v49
	v_add_co_u32_e32 v48, vcc, s68, v140
	v_cvt_pk_bf16_f32 v44, v44, v45
	v_cvt_pk_bf16_f32 v45, v52, v53
	v_lshl_add_u64 v[46:47], v[140:141], 0, s[22:23]
	s_nop 0
	v_addc_co_u32_e32 v49, vcc, 0, v141, vcc
	global_store_dwordx4 v[48:49], v[42:45], off
	s_mov_b64 s[22:23], 0x50000
	s_nop 0
	v_pk_add_f32 v[42:43], v[32:33], 0 op_sel_hi:[1,0]
	v_pk_add_f32 v[32:33], v[30:31], 0 op_sel_hi:[1,0]
	v_cvt_pk_bf16_f32 v30, v38, v39
	v_cvt_pk_bf16_f32 v31, v40, v41
	s_nop 0
	v_cvt_pk_bf16_f32 v32, v32, v33
	v_cvt_pk_bf16_f32 v33, v42, v43
	global_store_dwordx4 v[46:47], v[30:33], off offset:256
	s_nop 1
	v_lshl_add_u64 v[30:31], v[140:141], 0, s[22:23]
	v_pk_add_f32 v[32:33], v[36:37], 0 op_sel_hi:[1,0]
	s_mov_b32 s22, 0x50000
	v_pk_add_f32 v[36:37], v[28:29], 0 op_sel_hi:[1,0]
	v_pk_add_f32 v[28:29], v[26:27], 0 op_sel_hi:[1,0]
	v_cvt_pk_bf16_f32 v26, v34, v35
	v_cvt_pk_bf16_f32 v27, v32, v33
	v_add_co_u32_e32 v32, vcc, s22, v140
	v_cvt_pk_bf16_f32 v28, v28, v29
	v_cvt_pk_bf16_f32 v29, v36, v37
	s_mov_b64 s[22:23], 0x58000
	s_nop 0
	v_addc_co_u32_e32 v33, vcc, 0, v141, vcc
	global_store_dwordx4 v[32:33], v[26:29], off
	s_nop 1
	v_pk_add_f32 v[26:27], v[16:17], 0 op_sel_hi:[1,0]
	v_pk_add_f32 v[16:17], v[14:15], 0 op_sel_hi:[1,0]
	v_cvt_pk_bf16_f32 v14, v22, v23
	v_cvt_pk_bf16_f32 v15, v24, v25
	s_nop 0
	v_cvt_pk_bf16_f32 v16, v16, v17
	v_cvt_pk_bf16_f32 v17, v26, v27
	global_store_dwordx4 v[30:31], v[14:17], off offset:256
	s_nop 1
	v_lshl_add_u64 v[14:15], v[140:141], 0, s[22:23]
	v_pk_add_f32 v[16:17], v[20:21], 0 op_sel_hi:[1,0]
	s_mov_b32 s22, 0x58000
	v_pk_add_f32 v[20:21], v[12:13], 0 op_sel_hi:[1,0]
	v_pk_add_f32 v[12:13], v[10:11], 0 op_sel_hi:[1,0]
	v_cvt_pk_bf16_f32 v10, v18, v19
	v_cvt_pk_bf16_f32 v11, v16, v17
	v_add_co_u32_e32 v16, vcc, s22, v140
	v_cvt_pk_bf16_f32 v12, v12, v13
	v_cvt_pk_bf16_f32 v13, v20, v21
	s_mov_b64 s[22:23], s[0:1]
	s_nop 0
	v_addc_co_u32_e32 v17, vcc, 0, v141, vcc
	global_store_dwordx4 v[16:17], v[10:13], off
	s_and_b64 vcc, exec, s[38:39]
	s_nop 0
	v_pk_add_f32 v[10:11], v[4:5], 0 op_sel_hi:[1,0]
	v_pk_add_f32 v[4:5], v[2:3], 0 op_sel_hi:[1,0]
	v_cvt_pk_bf16_f32 v2, v6, v7
	v_cvt_pk_bf16_f32 v3, v8, v9
	s_nop 0
	v_cvt_pk_bf16_f32 v4, v4, v5
	v_cvt_pk_bf16_f32 v5, v10, v11
	global_store_dwordx4 v[14:15], v[2:5], off offset:256
	s_cbranch_vccz .LBB0_320
	s_waitcnt vmcnt(16)
	s_cmpk_gt_u32 s30, 0xff
	s_cbranch_scc1 .LBB0_335
	s_barrier

.LBB0_359:
	s_ashr_i32 s35, s34, 31
	v_cmp_lt_i64_e32 vcc, s[36:37], v[156:157]
	s_lshl_b64 s[36:37], s[34:35], 19
	s_add_u32 s36, s12, s36
	s_addc_u32 s37, s13, s37
	s_and_b64 s[40:41], vcc, exec
	s_cselect_b32 s1, s37, s45
	s_cselect_b32 s3, s36, s44
	s_ashr_i32 s31, s30, 31
	s_lshl_b64 s[40:41], s[30:31], 19
	s_add_u32 s40, s48, s40
	s_addc_u32 s41, s49, s41
	s_and_b64 s[46:47], vcc, exec
	s_cselect_b32 s31, s41, s43
	s_cselect_b32 s35, s40, s42
	s_add_u32 s60, s42, 0x100
	s_addc_u32 s61, s43, 0
	s_add_u32 s42, s44, 0x40080
	s_addc_u32 s43, s45, 0
	s_mov_b32 s62, -2
	v_mov_b64_e32 v[98:99], 0
	v_mov_b64_e32 v[100:101], 0
	s_nop 1
	v_mfma_f32_32x32x16_bf16 v[2:17], v[98:101], v[98:101], 0
	v_mov_b64_e32 v[130:131], 0
	v_mov_b64_e32 v[132:133], 0
	v_mov_b64_e32 v[134:135], 0
	v_mov_b64_e32 v[136:137], 0
	v_mov_b64_e32 v[138:139], 0
	v_mfma_f32_32x32x16_bf16 v[18:33], v[98:101], v[98:101], 0
	v_mov_b64_e32 v[140:141], 0
	v_mov_b64_e32 v[142:143], 0
	v_mov_b64_e32 v[144:145], 0
	v_mov_b64_e32 v[114:115], 0
	v_mov_b64_e32 v[116:117], 0
	v_mfma_f32_32x32x16_bf16 v[34:49], v[98:101], v[98:101], 0
	v_mov_b64_e32 v[118:119], 0
	v_mov_b64_e32 v[120:121], 0
	v_mov_b64_e32 v[122:123], 0
	v_mov_b64_e32 v[124:125], 0
	v_mov_b64_e32 v[126:127], 0
	v_mfma_f32_32x32x16_bf16 v[50:65], v[98:101], v[98:101], 0
	v_mov_b64_e32 v[128:129], 0
	v_mov_b64_e32 v[102:103], 0
	v_mov_b64_e32 v[104:105], 0
	v_mov_b64_e32 v[106:107], 0
	v_mov_b64_e32 v[108:109], 0
	v_mfma_f32_32x32x16_bf16 v[66:81], v[98:101], v[98:101], 0
	v_mov_b64_e32 v[110:111], 0
	v_mov_b64_e32 v[112:113], 0
.LBB0_360:
	s_add_u32 s44, s42, 0xfffc0080
	s_addc_u32 s45, s43, -1
	s_add_i32 s63, 0, 0x10000
	v_add_u32_e32 v0, s63, v206
	ds_read_b128 v[82:85], v0
	ds_read_b128 v[86:89], v0 offset:1024
	ds_read_b128 v[90:93], v0 offset:2048
	ds_read_b128 v[94:97], v0 offset:3072
	s_cmp_eq_u32 s62, 12
	s_cselect_b32 s47, s1, s45
	s_cselect_b32 s46, s3, s44
	s_cselect_b32 s45, s31, s61
	s_cselect_b32 s44, s35, s60
	v_lshl_add_u64 v[230:231], s[42:43], 0, v[174:175]
	s_add_i32 m0, s51, 0xc000
	ds_read_b128 v[176:179], v208
	ds_read_b128 v[180:183], v208 offset:1024
	ds_read_b128 v[184:187], v208 offset:2048
	ds_read_b128 v[210:213], v208 offset:3072
	ds_read_b128 v[214:217], v208 offset:4096
	ds_read_b128 v[218:221], v208 offset:5120
	ds_read_b128 v[222:225], v208 offset:6144
	ds_read_b128 v[226:229], v208 offset:7168
	global_load_lds_dwordx4 v[230:231], off
	v_lshl_add_u64 v[230:231], s[42:43], 0, v[172:173]
	s_add_i32 m0, s51, 0xe000
	s_nop 0
	global_load_lds_dwordx4 v[230:231], off
	s_waitcnt lgkmcnt(8)
	s_barrier
	s_waitcnt lgkmcnt(0)
	v_mfma_f32_16x16x32_bf16 v[142:145], v[82:85], v[176:179], v[142:145]
	v_mfma_f32_16x16x32_bf16 v[138:141], v[90:93], v[176:179], v[138:141]
	v_mfma_f32_16x16x32_bf16 v[126:129], v[82:85], v[184:187], v[126:129]
	v_mfma_f32_16x16x32_bf16 v[122:125], v[90:93], v[184:187], v[122:125]
	v_mfma_f32_16x16x32_bf16 v[110:113], v[82:85], v[214:217], v[110:113]
	v_mfma_f32_16x16x32_bf16 v[106:109], v[90:93], v[214:217], v[106:109]
	v_mfma_f32_16x16x32_bf16 v[78:81], v[82:85], v[222:225], v[78:81]
	v_mfma_f32_16x16x32_bf16 v[74:77], v[90:93], v[222:225], v[74:77]
	v_mfma_f32_16x16x32_bf16 v[142:145], v[86:89], v[180:183], v[142:145]
	v_mfma_f32_16x16x32_bf16 v[138:141], v[94:97], v[180:183], v[138:141]
	v_mfma_f32_16x16x32_bf16 v[126:129], v[86:89], v[210:213], v[126:129]
	v_mfma_f32_16x16x32_bf16 v[122:125], v[94:97], v[210:213], v[122:125]
	v_mfma_f32_16x16x32_bf16 v[110:113], v[86:89], v[218:221], v[110:113]
	v_mfma_f32_16x16x32_bf16 v[106:109], v[94:97], v[218:221], v[106:109]
	v_mfma_f32_16x16x32_bf16 v[78:81], v[86:89], v[226:229], v[78:81]
	v_mfma_f32_16x16x32_bf16 v[74:77], v[94:97], v[226:229], v[74:77]
	s_barrier
	s_add_i32 s66, 0, 0x14000
	s_add_i32 s63, s63, s50
	v_add_u32_e32 v0, s66, v206
	v_lshl_add_u64 v[246:247], s[44:45], 0, v[164:165]
	s_mov_b32 m0, s63
	ds_read_b128 v[230:233], v0
	ds_read_b128 v[234:237], v0 offset:1024
	ds_read_b128 v[238:241], v0 offset:2048
	ds_read_b128 v[242:245], v0 offset:3072
	global_load_lds_dwordx4 v[246:247], off
	v_lshl_add_u64 v[248:249], s[44:45], 0, v[168:169]
	s_add_i32 m0, s63, 0x2000
	s_nop 0
	global_load_lds_dwordx4 v[248:249], off
	s_barrier
	s_waitcnt lgkmcnt(0)
	v_mfma_f32_16x16x32_bf16 v[134:137], v[230:233], v[176:179], v[134:137]
	v_mfma_f32_16x16x32_bf16 v[130:133], v[238:241], v[176:179], v[130:133]
	v_mfma_f32_16x16x32_bf16 v[118:121], v[230:233], v[184:187], v[118:121]
	v_mfma_f32_16x16x32_bf16 v[114:117], v[238:241], v[184:187], v[114:117]
	v_mfma_f32_16x16x32_bf16 v[102:105], v[230:233], v[214:217], v[102:105]
	v_mfma_f32_16x16x32_bf16 v[98:101], v[238:241], v[214:217], v[98:101]
	v_mfma_f32_16x16x32_bf16 v[70:73], v[230:233], v[222:225], v[70:73]
	v_mfma_f32_16x16x32_bf16 v[66:69], v[238:241], v[222:225], v[66:69]
	v_mfma_f32_16x16x32_bf16 v[134:137], v[234:237], v[180:183], v[134:137]
	v_mfma_f32_16x16x32_bf16 v[130:133], v[242:245], v[180:183], v[130:133]
	v_mfma_f32_16x16x32_bf16 v[118:121], v[234:237], v[210:213], v[118:121]
	v_mfma_f32_16x16x32_bf16 v[114:117], v[242:245], v[210:213], v[114:117]
	v_mfma_f32_16x16x32_bf16 v[102:105], v[234:237], v[218:221], v[102:105]
	v_mfma_f32_16x16x32_bf16 v[98:101], v[242:245], v[218:221], v[98:101]
	v_mfma_f32_16x16x32_bf16 v[70:73], v[234:237], v[226:229], v[70:73]
	v_mfma_f32_16x16x32_bf16 v[66:69], v[242:245], v[226:229], v[66:69]
	s_barrier
	s_mov_b32 m0, s51
	v_lshl_add_u64 v[250:251], s[46:47], 0, v[162:163]
	ds_read_b128 v[176:179], v208 offset:16384
	ds_read_b128 v[180:183], v208 offset:17408
	ds_read_b128 v[184:187], v208 offset:18432
	ds_read_b128 v[210:213], v208 offset:19456
	ds_read_b128 v[214:217], v208 offset:20480
	ds_read_b128 v[218:221], v208 offset:21504
	ds_read_b128 v[222:225], v208 offset:22528
	ds_read_b128 v[226:229], v208 offset:23552
	global_load_lds_dwordx4 v[250:251], off
	v_lshl_add_u64 v[252:253], s[46:47], 0, v[166:167]
	s_mov_b32 m0, s52
	s_nop 0
	global_load_lds_dwordx4 v[252:253], off
	s_barrier
	s_waitcnt lgkmcnt(0)
	v_mfma_f32_16x16x32_bf16 v[62:65], v[82:85], v[176:179], v[62:65]
	v_mfma_f32_16x16x32_bf16 v[58:61], v[90:93], v[176:179], v[58:61]
	v_mfma_f32_16x16x32_bf16 v[46:49], v[82:85], v[184:187], v[46:49]
	v_mfma_f32_16x16x32_bf16 v[42:45], v[90:93], v[184:187], v[42:45]
	v_mfma_f32_16x16x32_bf16 v[30:33], v[82:85], v[214:217], v[30:33]
	v_mfma_f32_16x16x32_bf16 v[26:29], v[90:93], v[214:217], v[26:29]
	v_mfma_f32_16x16x32_bf16 v[14:17], v[82:85], v[222:225], v[14:17]
	v_mfma_f32_16x16x32_bf16 v[10:13], v[90:93], v[222:225], v[10:13]
	v_mfma_f32_16x16x32_bf16 v[62:65], v[86:89], v[180:183], v[62:65]
	v_mfma_f32_16x16x32_bf16 v[58:61], v[94:97], v[180:183], v[58:61]
	v_mfma_f32_16x16x32_bf16 v[46:49], v[86:89], v[210:213], v[46:49]
	v_mfma_f32_16x16x32_bf16 v[42:45], v[94:97], v[210:213], v[42:45]
	v_mfma_f32_16x16x32_bf16 v[30:33], v[86:89], v[218:221], v[30:33]
	v_mfma_f32_16x16x32_bf16 v[26:29], v[94:97], v[218:221], v[26:29]
	v_mfma_f32_16x16x32_bf16 v[14:17], v[86:89], v[226:229], v[14:17]
	v_mfma_f32_16x16x32_bf16 v[10:13], v[94:97], v[226:229], v[10:13]
	s_barrier
	s_add_u32 s64, s44, 0x40000
	s_addc_u32 s65, s45, 0
	s_add_i32 s63, s66, s50
	v_lshl_add_u64 v[82:83], s[64:65], 0, v[164:165]
	s_mov_b32 m0, s63
	s_nop 0
	global_load_lds_dwordx4 v[82:83], off
	v_lshl_add_u64 v[82:83], s[64:65], 0, v[168:169]
	s_add_i32 m0, s63, 0x2000
	s_nop 0
	global_load_lds_dwordx4 v[82:83], off
	s_waitcnt vmcnt(6)
	s_barrier
	v_mfma_f32_16x16x32_bf16 v[54:57], v[230:233], v[176:179], v[54:57]
	v_mfma_f32_16x16x32_bf16 v[50:53], v[238:241], v[176:179], v[50:53]
	v_mfma_f32_16x16x32_bf16 v[38:41], v[230:233], v[184:187], v[38:41]
	v_mfma_f32_16x16x32_bf16 v[34:37], v[238:241], v[184:187], v[34:37]
	v_mfma_f32_16x16x32_bf16 v[22:25], v[230:233], v[214:217], v[22:25]
	v_mfma_f32_16x16x32_bf16 v[18:21], v[238:241], v[214:217], v[18:21]
	v_mfma_f32_16x16x32_bf16 v[6:9], v[230:233], v[222:225], v[6:9]
	v_mfma_f32_16x16x32_bf16 v[2:5], v[238:241], v[222:225], v[2:5]
	v_mfma_f32_16x16x32_bf16 v[54:57], v[234:237], v[180:183], v[54:57]
	v_mfma_f32_16x16x32_bf16 v[50:53], v[242:245], v[180:183], v[50:53]
	v_mfma_f32_16x16x32_bf16 v[38:41], v[234:237], v[210:213], v[38:41]
	v_mfma_f32_16x16x32_bf16 v[34:37], v[242:245], v[210:213], v[34:37]
	v_mfma_f32_16x16x32_bf16 v[22:25], v[234:237], v[218:221], v[22:25]
	v_mfma_f32_16x16x32_bf16 v[18:21], v[242:245], v[218:221], v[18:21]
	v_mfma_f32_16x16x32_bf16 v[6:9], v[234:237], v[226:229], v[6:9]
	v_mfma_f32_16x16x32_bf16 v[2:5], v[242:245], v[226:229], v[2:5]
	s_barrier
	s_add_i32 s63, 0, 0x18000
	v_add_u32_e32 v0, s63, v206
	ds_read_b128 v[82:85], v0
	ds_read_b128 v[86:89], v0 offset:1024
	ds_read_b128 v[90:93], v0 offset:2048
	ds_read_b128 v[94:97], v0 offset:3072
	s_add_u32 s46, s46, 0x40000
	s_addc_u32 s47, s47, 0
	s_mov_b32 m0, s53
	v_lshl_add_u64 v[230:231], s[46:47], 0, v[162:163]
	ds_read_b128 v[176:179], v208 offset:32768
	ds_read_b128 v[180:183], v208 offset:33792
	ds_read_b128 v[184:187], v208 offset:34816
	ds_read_b128 v[210:213], v208 offset:35840
	ds_read_b128 v[214:217], v208 offset:36864
	ds_read_b128 v[218:221], v208 offset:37888
	ds_read_b128 v[222:225], v208 offset:38912
	ds_read_b128 v[226:229], v208 offset:39936
	global_load_lds_dwordx4 v[230:231], off
	v_lshl_add_u64 v[230:231], s[46:47], 0, v[166:167]
	s_mov_b32 m0, s54
	s_nop 0
	global_load_lds_dwordx4 v[230:231], off
	s_waitcnt lgkmcnt(8)
	s_barrier
	s_waitcnt lgkmcnt(0)
	v_mfma_f32_16x16x32_bf16 v[142:145], v[82:85], v[176:179], v[142:145]
	v_mfma_f32_16x16x32_bf16 v[138:141], v[90:93], v[176:179], v[138:141]
	v_mfma_f32_16x16x32_bf16 v[126:129], v[82:85], v[184:187], v[126:129]
	v_mfma_f32_16x16x32_bf16 v[122:125], v[90:93], v[184:187], v[122:125]
	v_mfma_f32_16x16x32_bf16 v[110:113], v[82:85], v[214:217], v[110:113]
	v_mfma_f32_16x16x32_bf16 v[106:109], v[90:93], v[214:217], v[106:109]
	v_mfma_f32_16x16x32_bf16 v[78:81], v[82:85], v[222:225], v[78:81]
	v_mfma_f32_16x16x32_bf16 v[74:77], v[90:93], v[222:225], v[74:77]
	v_mfma_f32_16x16x32_bf16 v[142:145], v[86:89], v[180:183], v[142:145]
	v_mfma_f32_16x16x32_bf16 v[138:141], v[94:97], v[180:183], v[138:141]
	v_mfma_f32_16x16x32_bf16 v[126:129], v[86:89], v[210:213], v[126:129]
	v_mfma_f32_16x16x32_bf16 v[122:125], v[94:97], v[210:213], v[122:125]
	v_mfma_f32_16x16x32_bf16 v[110:113], v[86:89], v[218:221], v[110:113]
	v_mfma_f32_16x16x32_bf16 v[106:109], v[94:97], v[218:221], v[106:109]
	v_mfma_f32_16x16x32_bf16 v[78:81], v[86:89], v[226:229], v[78:81]
	v_mfma_f32_16x16x32_bf16 v[74:77], v[94:97], v[226:229], v[74:77]
	s_barrier
	s_add_i32 s46, 0, 0x1c000
	s_add_i32 s47, s63, s50
	v_add_u32_e32 v0, s46, v206
	v_lshl_add_u64 v[246:247], v[246:247], 0, s[94:95]
	s_mov_b32 m0, s47
	ds_read_b128 v[230:233], v0
	ds_read_b128 v[234:237], v0 offset:1024
	ds_read_b128 v[238:241], v0 offset:2048
	ds_read_b128 v[242:245], v0 offset:3072
	global_load_lds_dwordx4 v[246:247], off
	v_lshl_add_u64 v[246:247], v[248:249], 0, s[94:95]
	s_add_i32 m0, s47, 0x2000
	s_nop 0
	global_load_lds_dwordx4 v[246:247], off
	s_barrier
	s_waitcnt lgkmcnt(0)
	v_mfma_f32_16x16x32_bf16 v[134:137], v[230:233], v[176:179], v[134:137]
	v_mfma_f32_16x16x32_bf16 v[130:133], v[238:241], v[176:179], v[130:133]
	v_mfma_f32_16x16x32_bf16 v[118:121], v[230:233], v[184:187], v[118:121]
	v_mfma_f32_16x16x32_bf16 v[114:117], v[238:241], v[184:187], v[114:117]
	v_mfma_f32_16x16x32_bf16 v[102:105], v[230:233], v[214:217], v[102:105]
	v_mfma_f32_16x16x32_bf16 v[98:101], v[238:241], v[214:217], v[98:101]
	v_mfma_f32_16x16x32_bf16 v[70:73], v[230:233], v[222:225], v[70:73]
	v_mfma_f32_16x16x32_bf16 v[66:69], v[238:241], v[222:225], v[66:69]
	v_mfma_f32_16x16x32_bf16 v[134:137], v[234:237], v[180:183], v[134:137]
	v_mfma_f32_16x16x32_bf16 v[130:133], v[242:245], v[180:183], v[130:133]
	v_mfma_f32_16x16x32_bf16 v[118:121], v[234:237], v[210:213], v[118:121]
	v_mfma_f32_16x16x32_bf16 v[114:117], v[242:245], v[210:213], v[114:117]
	v_mfma_f32_16x16x32_bf16 v[102:105], v[234:237], v[218:221], v[102:105]
	v_mfma_f32_16x16x32_bf16 v[98:101], v[242:245], v[218:221], v[98:101]
	v_mfma_f32_16x16x32_bf16 v[70:73], v[234:237], v[226:229], v[70:73]
	v_mfma_f32_16x16x32_bf16 v[66:69], v[242:245], v[226:229], v[66:69]
	s_barrier
	s_mov_b32 m0, s56
	v_lshl_add_u64 v[246:247], v[250:251], 0, s[94:95]
	ds_read_b128 v[176:179], v208 offset:49152
	ds_read_b128 v[180:183], v208 offset:50176
	ds_read_b128 v[184:187], v208 offset:51200
	ds_read_b128 v[210:213], v208 offset:52224
	ds_read_b128 v[214:217], v208 offset:53248
	ds_read_b128 v[218:221], v208 offset:54272
	ds_read_b128 v[222:225], v208 offset:55296
	ds_read_b128 v[226:229], v208 offset:56320
	global_load_lds_dwordx4 v[246:247], off
	v_lshl_add_u64 v[246:247], v[252:253], 0, s[94:95]
	s_mov_b32 m0, s57
	s_nop 0
	global_load_lds_dwordx4 v[246:247], off
	s_barrier
	s_waitcnt lgkmcnt(0)
	v_mfma_f32_16x16x32_bf16 v[62:65], v[82:85], v[176:179], v[62:65]
	v_mfma_f32_16x16x32_bf16 v[58:61], v[90:93], v[176:179], v[58:61]
	v_mfma_f32_16x16x32_bf16 v[46:49], v[82:85], v[184:187], v[46:49]
	v_mfma_f32_16x16x32_bf16 v[42:45], v[90:93], v[184:187], v[42:45]
	v_mfma_f32_16x16x32_bf16 v[30:33], v[82:85], v[214:217], v[30:33]
	v_mfma_f32_16x16x32_bf16 v[26:29], v[90:93], v[214:217], v[26:29]
	v_mfma_f32_16x16x32_bf16 v[14:17], v[82:85], v[222:225], v[14:17]
	v_mfma_f32_16x16x32_bf16 v[10:13], v[90:93], v[222:225], v[10:13]
	v_mfma_f32_16x16x32_bf16 v[62:65], v[86:89], v[180:183], v[62:65]
	v_mfma_f32_16x16x32_bf16 v[58:61], v[94:97], v[180:183], v[58:61]
	v_mfma_f32_16x16x32_bf16 v[46:49], v[86:89], v[210:213], v[46:49]
	v_mfma_f32_16x16x32_bf16 v[42:45], v[94:97], v[210:213], v[42:45]
	v_mfma_f32_16x16x32_bf16 v[30:33], v[86:89], v[218:221], v[30:33]
	v_mfma_f32_16x16x32_bf16 v[26:29], v[94:97], v[218:221], v[26:29]
	v_mfma_f32_16x16x32_bf16 v[14:17], v[86:89], v[226:229], v[14:17]
	v_mfma_f32_16x16x32_bf16 v[10:13], v[94:97], v[226:229], v[10:13]
	s_barrier
	s_add_u32 s44, s44, 0x40080
	s_addc_u32 s45, s45, 0
	s_add_i32 s46, s46, s50
	v_lshl_add_u64 v[82:83], s[44:45], 0, v[164:165]
	s_mov_b32 m0, s46
	s_nop 0
	global_load_lds_dwordx4 v[82:83], off
	v_lshl_add_u64 v[82:83], s[44:45], 0, v[168:169]
	s_add_i32 m0, s46, 0x2000
	s_nop 0
	global_load_lds_dwordx4 v[82:83], off
	s_waitcnt vmcnt(6)
	s_barrier
	v_mfma_f32_16x16x32_bf16 v[54:57], v[230:233], v[176:179], v[54:57]
	v_mfma_f32_16x16x32_bf16 v[50:53], v[238:241], v[176:179], v[50:53]
	v_mfma_f32_16x16x32_bf16 v[38:41], v[230:233], v[184:187], v[38:41]
	v_mfma_f32_16x16x32_bf16 v[34:37], v[238:241], v[184:187], v[34:37]
	v_mfma_f32_16x16x32_bf16 v[22:25], v[230:233], v[214:217], v[22:25]
	v_mfma_f32_16x16x32_bf16 v[18:21], v[238:241], v[214:217], v[18:21]
	v_mfma_f32_16x16x32_bf16 v[6:9], v[230:233], v[222:225], v[6:9]
	v_mfma_f32_16x16x32_bf16 v[2:5], v[238:241], v[222:225], v[2:5]
	v_mfma_f32_16x16x32_bf16 v[54:57], v[234:237], v[180:183], v[54:57]
	v_mfma_f32_16x16x32_bf16 v[50:53], v[242:245], v[180:183], v[50:53]
	v_mfma_f32_16x16x32_bf16 v[38:41], v[234:237], v[210:213], v[38:41]
	v_mfma_f32_16x16x32_bf16 v[34:37], v[242:245], v[210:213], v[34:37]
	v_mfma_f32_16x16x32_bf16 v[22:25], v[234:237], v[218:221], v[22:25]
	v_mfma_f32_16x16x32_bf16 v[18:21], v[242:245], v[218:221], v[18:21]
	v_mfma_f32_16x16x32_bf16 v[6:9], v[234:237], v[226:229], v[6:9]
	v_mfma_f32_16x16x32_bf16 v[2:5], v[242:245], v[226:229], v[2:5]
	s_barrier
	s_add_i32 s62, s62, 2
	s_add_u32 s60, s60, 0x100
	s_addc_u32 s61, s61, 0
	s_add_u32 s42, s42, 0x100
	s_addc_u32 s43, s43, 0
	s_cmp_gt_u32 s62, 13
	s_cbranch_scc0 .LBB0_360
	v_lshl_or_b32 v180, s0, 8, v207
	v_ashrrev_i32_e32 v181, 31, v180
	v_mov_b32_e32 v86, 0
	v_cndmask_b32_e64 v0, 0, 1, s[26:27]
	v_lshl_add_u64 v[176:177], v[180:181], 2, s[22:23]
	v_cmp_ne_u32_e64 s[0:1], 1, v0
	s_andn2_b64 vcc, exec, s[26:27]
	v_mov_b32_e32 v94, 0
	v_mov_b32_e32 v95, v86
	v_mov_b32_e32 v96, 0
	v_mov_b32_e32 v97, 0
	s_cbranch_vccnz .LBB0_363
	global_load_dwordx4 v[94:97], v[176:177], off

.LBB0_585:
	s_ashr_i32 s9, s8, 31
	v_cmp_lt_i64_e32 vcc, s[16:17], v[160:161]
	s_lshl_b64 s[16:17], s[8:9], 19
	s_add_u32 s16, s12, s16
	s_addc_u32 s17, s13, s17
	s_and_b64 s[18:19], vcc, exec
	s_cselect_b32 s9, s17, s21
	s_cselect_b32 s43, s16, s20
	s_ashr_i32 s1, s0, 31
	s_lshl_b64 s[18:19], s[0:1], 19
	s_add_u32 s18, s27, s18
	s_addc_u32 s19, s28, s19
	s_and_b64 s[24:25], vcc, exec
	s_cselect_b32 s1, s19, s23
	s_cselect_b32 s44, s18, s22
	s_add_u32 s20, s20, 0x40080
	s_addc_u32 s21, s21, 0
	s_add_u32 s45, s22, 0x100
	s_addc_u32 s46, s23, 0
	s_mov_b32 s47, -2
	v_mov_b64_e32 v[82:83], 0
	v_mov_b64_e32 v[84:85], 0
	s_nop 1
	v_mfma_f32_32x32x16_bf16 v[2:17], v[82:85], v[82:85], 0
	v_mov_b64_e32 v[114:115], 0
	v_mov_b64_e32 v[116:117], 0
	v_mov_b64_e32 v[118:119], 0
	v_mov_b64_e32 v[120:121], 0
	v_mov_b64_e32 v[122:123], 0
	v_mfma_f32_32x32x16_bf16 v[18:33], v[82:85], v[82:85], 0
	v_mov_b64_e32 v[124:125], 0
	v_mov_b64_e32 v[126:127], 0
	v_mov_b64_e32 v[128:129], 0
	v_mov_b64_e32 v[98:99], 0
	v_mov_b64_e32 v[100:101], 0
	v_mfma_f32_32x32x16_bf16 v[34:49], v[82:85], v[82:85], 0
	v_mov_b64_e32 v[102:103], 0
	v_mov_b64_e32 v[104:105], 0
	v_mov_b64_e32 v[106:107], 0
	v_mov_b64_e32 v[108:109], 0
	v_mov_b64_e32 v[110:111], 0
	v_mfma_f32_32x32x16_bf16 v[50:65], v[82:85], v[82:85], 0
	v_mov_b64_e32 v[112:113], 0
	v_mov_b64_e32 v[86:87], 0
	v_mov_b64_e32 v[88:89], 0
	v_mov_b64_e32 v[90:91], 0
	v_mov_b64_e32 v[92:93], 0
	v_mfma_f32_32x32x16_bf16 v[66:81], v[82:85], v[82:85], 0
	v_mov_b64_e32 v[94:95], 0
	v_mov_b64_e32 v[96:97], 0
.LBB0_586:
	s_add_u32 s22, s20, 0xfffc0080
	s_addc_u32 s23, s21, -1
	s_add_i32 s48, 0, 0x10000
	v_add_u32_e32 v140, s48, v143
	ds_read_b128 v[162:165], v140
	ds_read_b128 v[166:169], v140 offset:1024
	ds_read_b128 v[170:173], v140 offset:2048
	ds_read_b128 v[174:177], v140 offset:3072
	s_cmp_eq_u32 s47, 12
	s_cselect_b32 s25, s9, s23
	s_cselect_b32 s24, s43, s22
	s_cselect_b32 s23, s1, s46
	s_cselect_b32 s22, s44, s45
	v_lshl_add_u64 v[140:141], s[20:21], 0, v[136:137]
	s_add_i32 m0, s3, 0xc000
	ds_read_b128 v[178:181], v145
	ds_read_b128 v[182:185], v145 offset:1024
	ds_read_b128 v[206:209], v145 offset:2048
	ds_read_b128 v[210:213], v145 offset:3072
	ds_read_b128 v[214:217], v145 offset:4096
	ds_read_b128 v[218:221], v145 offset:5120
	ds_read_b128 v[222:225], v145 offset:6144
	ds_read_b128 v[226:229], v145 offset:7168
	global_load_lds_dwordx4 v[140:141], off
	v_lshl_add_u64 v[140:141], s[20:21], 0, v[138:139]
	s_add_i32 m0, s3, 0xe000
	s_nop 0
	global_load_lds_dwordx4 v[140:141], off
	s_waitcnt lgkmcnt(8)
	s_barrier
	s_waitcnt lgkmcnt(0)
	v_mfma_f32_16x16x32_bf16 v[122:125], v[162:165], v[178:181], v[122:125]
	v_mfma_f32_16x16x32_bf16 v[114:117], v[170:173], v[178:181], v[114:117]
	v_mfma_f32_16x16x32_bf16 v[106:109], v[162:165], v[206:209], v[106:109]
	v_mfma_f32_16x16x32_bf16 v[98:101], v[170:173], v[206:209], v[98:101]
	v_mfma_f32_16x16x32_bf16 v[90:93], v[162:165], v[214:217], v[90:93]
	v_mfma_f32_16x16x32_bf16 v[82:85], v[170:173], v[214:217], v[82:85]
	v_mfma_f32_16x16x32_bf16 v[74:77], v[162:165], v[222:225], v[74:77]
	v_mfma_f32_16x16x32_bf16 v[66:69], v[170:173], v[222:225], v[66:69]
	v_mfma_f32_16x16x32_bf16 v[122:125], v[166:169], v[182:185], v[122:125]
	v_mfma_f32_16x16x32_bf16 v[114:117], v[174:177], v[182:185], v[114:117]
	v_mfma_f32_16x16x32_bf16 v[106:109], v[166:169], v[210:213], v[106:109]
	v_mfma_f32_16x16x32_bf16 v[98:101], v[174:177], v[210:213], v[98:101]
	v_mfma_f32_16x16x32_bf16 v[90:93], v[166:169], v[218:221], v[90:93]
	v_mfma_f32_16x16x32_bf16 v[82:85], v[174:177], v[218:221], v[82:85]
	v_mfma_f32_16x16x32_bf16 v[74:77], v[166:169], v[226:229], v[74:77]
	v_mfma_f32_16x16x32_bf16 v[66:69], v[174:177], v[226:229], v[66:69]
	s_barrier
	s_add_i32 s50, 0, 0x14000
	v_add_u32_e32 v140, s50, v143
	s_add_i32 s48, s48, s29
	ds_read_b128 v[230:233], v140
	ds_read_b128 v[234:237], v140 offset:1024
	ds_read_b128 v[238:241], v140 offset:2048
	ds_read_b128 v[242:245], v140 offset:3072
	v_lshl_add_u64 v[140:141], s[22:23], 0, v[0:1]
	s_mov_b32 m0, s48
	v_lshl_add_u64 v[186:187], s[22:23], 0, v[130:131]
	global_load_lds_dwordx4 v[140:141], off
	s_add_i32 m0, s48, 0x2000
	s_nop 0
	global_load_lds_dwordx4 v[186:187], off
	s_barrier
	s_waitcnt lgkmcnt(0)
	v_mfma_f32_16x16x32_bf16 v[126:129], v[230:233], v[178:181], v[126:129]
	v_mfma_f32_16x16x32_bf16 v[118:121], v[238:241], v[178:181], v[118:121]
	v_mfma_f32_16x16x32_bf16 v[110:113], v[230:233], v[206:209], v[110:113]
	v_mfma_f32_16x16x32_bf16 v[102:105], v[238:241], v[206:209], v[102:105]
	v_mfma_f32_16x16x32_bf16 v[94:97], v[230:233], v[214:217], v[94:97]
	v_mfma_f32_16x16x32_bf16 v[86:89], v[238:241], v[214:217], v[86:89]
	v_mfma_f32_16x16x32_bf16 v[78:81], v[230:233], v[222:225], v[78:81]
	v_mfma_f32_16x16x32_bf16 v[70:73], v[238:241], v[222:225], v[70:73]
	v_mfma_f32_16x16x32_bf16 v[126:129], v[234:237], v[182:185], v[126:129]
	v_mfma_f32_16x16x32_bf16 v[118:121], v[242:245], v[182:185], v[118:121]
	v_mfma_f32_16x16x32_bf16 v[110:113], v[234:237], v[210:213], v[110:113]
	v_mfma_f32_16x16x32_bf16 v[102:105], v[242:245], v[210:213], v[102:105]
	v_mfma_f32_16x16x32_bf16 v[94:97], v[234:237], v[218:221], v[94:97]
	v_mfma_f32_16x16x32_bf16 v[86:89], v[242:245], v[218:221], v[86:89]
	v_mfma_f32_16x16x32_bf16 v[78:81], v[234:237], v[226:229], v[78:81]
	v_mfma_f32_16x16x32_bf16 v[70:73], v[242:245], v[226:229], v[70:73]
	s_barrier
	s_mov_b32 m0, s3
	v_lshl_add_u64 v[246:247], s[24:25], 0, v[134:135]
	ds_read_b128 v[178:181], v145 offset:16384
	ds_read_b128 v[182:185], v145 offset:17408
	ds_read_b128 v[206:209], v145 offset:18432
	ds_read_b128 v[210:213], v145 offset:19456
	ds_read_b128 v[214:217], v145 offset:20480
	ds_read_b128 v[218:221], v145 offset:21504
	ds_read_b128 v[222:225], v145 offset:22528
	ds_read_b128 v[226:229], v145 offset:23552
	global_load_lds_dwordx4 v[246:247], off
	v_lshl_add_u64 v[248:249], s[24:25], 0, v[132:133]
	s_mov_b32 m0, s31
	s_nop 0
	global_load_lds_dwordx4 v[248:249], off
	s_barrier
	s_waitcnt lgkmcnt(0)
	v_mfma_f32_16x16x32_bf16 v[58:61], v[162:165], v[178:181], v[58:61]
	v_mfma_f32_16x16x32_bf16 v[50:53], v[170:173], v[178:181], v[50:53]
	v_mfma_f32_16x16x32_bf16 v[42:45], v[162:165], v[206:209], v[42:45]
	v_mfma_f32_16x16x32_bf16 v[34:37], v[170:173], v[206:209], v[34:37]
	v_mfma_f32_16x16x32_bf16 v[26:29], v[162:165], v[214:217], v[26:29]
	v_mfma_f32_16x16x32_bf16 v[18:21], v[170:173], v[214:217], v[18:21]
	v_mfma_f32_16x16x32_bf16 v[10:13], v[162:165], v[222:225], v[10:13]
	v_mfma_f32_16x16x32_bf16 v[6:9], v[170:173], v[222:225], v[6:9]
	v_mfma_f32_16x16x32_bf16 v[58:61], v[166:169], v[182:185], v[58:61]
	v_mfma_f32_16x16x32_bf16 v[50:53], v[174:177], v[182:185], v[50:53]
	v_mfma_f32_16x16x32_bf16 v[42:45], v[166:169], v[210:213], v[42:45]
	v_mfma_f32_16x16x32_bf16 v[34:37], v[174:177], v[210:213], v[34:37]
	v_mfma_f32_16x16x32_bf16 v[26:29], v[166:169], v[218:221], v[26:29]
	v_mfma_f32_16x16x32_bf16 v[18:21], v[174:177], v[218:221], v[18:21]
	v_mfma_f32_16x16x32_bf16 v[10:13], v[166:169], v[226:229], v[10:13]
	v_mfma_f32_16x16x32_bf16 v[6:9], v[174:177], v[226:229], v[6:9]
	s_barrier
	s_add_u32 s48, s22, 0x40000
	s_addc_u32 s49, s23, 0
	s_add_i32 s50, s50, s29
	v_lshl_add_u64 v[162:163], s[48:49], 0, v[0:1]
	s_mov_b32 m0, s50
	s_nop 0
	global_load_lds_dwordx4 v[162:163], off
	v_lshl_add_u64 v[162:163], s[48:49], 0, v[130:131]
	s_add_i32 m0, s50, 0x2000
	s_nop 0
	global_load_lds_dwordx4 v[162:163], off
	s_waitcnt vmcnt(6)
	s_barrier
	v_mfma_f32_16x16x32_bf16 v[62:65], v[230:233], v[178:181], v[62:65]
	v_mfma_f32_16x16x32_bf16 v[54:57], v[238:241], v[178:181], v[54:57]
	v_mfma_f32_16x16x32_bf16 v[46:49], v[230:233], v[206:209], v[46:49]
	v_mfma_f32_16x16x32_bf16 v[38:41], v[238:241], v[206:209], v[38:41]
	v_mfma_f32_16x16x32_bf16 v[30:33], v[230:233], v[214:217], v[30:33]
	v_mfma_f32_16x16x32_bf16 v[22:25], v[238:241], v[214:217], v[22:25]
	v_mfma_f32_16x16x32_bf16 v[14:17], v[230:233], v[222:225], v[14:17]
	v_mfma_f32_16x16x32_bf16 v[2:5], v[238:241], v[222:225], v[2:5]
	v_mfma_f32_16x16x32_bf16 v[62:65], v[234:237], v[182:185], v[62:65]
	v_mfma_f32_16x16x32_bf16 v[54:57], v[242:245], v[182:185], v[54:57]
	v_mfma_f32_16x16x32_bf16 v[46:49], v[234:237], v[210:213], v[46:49]
	v_mfma_f32_16x16x32_bf16 v[38:41], v[242:245], v[210:213], v[38:41]
	v_mfma_f32_16x16x32_bf16 v[30:33], v[234:237], v[218:221], v[30:33]
	v_mfma_f32_16x16x32_bf16 v[22:25], v[242:245], v[218:221], v[22:25]
	v_mfma_f32_16x16x32_bf16 v[14:17], v[234:237], v[226:229], v[14:17]
	v_mfma_f32_16x16x32_bf16 v[2:5], v[242:245], v[226:229], v[2:5]
	s_barrier
	s_add_i32 s48, 0, 0x18000
	v_add_u32_e32 v174, s48, v143
	ds_read_b128 v[162:165], v174
	ds_read_b128 v[166:169], v174 offset:1024
	ds_read_b128 v[170:173], v174 offset:2048
	ds_read_b128 v[174:177], v174 offset:3072
	s_add_u32 s24, s24, 0x40000
	s_addc_u32 s25, s25, 0
	s_mov_b32 m0, s34
	v_lshl_add_u64 v[230:231], s[24:25], 0, v[134:135]
	ds_read_b128 v[178:181], v145 offset:32768
	ds_read_b128 v[182:185], v145 offset:33792
	ds_read_b128 v[206:209], v145 offset:34816
	ds_read_b128 v[210:213], v145 offset:35840
	ds_read_b128 v[214:217], v145 offset:36864
	ds_read_b128 v[218:221], v145 offset:37888
	ds_read_b128 v[222:225], v145 offset:38912
	ds_read_b128 v[226:229], v145 offset:39936
	global_load_lds_dwordx4 v[230:231], off
	v_lshl_add_u64 v[230:231], s[24:25], 0, v[132:133]
	s_mov_b32 m0, s35
	s_nop 0
	global_load_lds_dwordx4 v[230:231], off
	s_waitcnt lgkmcnt(8)
	s_barrier
	s_waitcnt lgkmcnt(0)
	v_mfma_f32_16x16x32_bf16 v[122:125], v[162:165], v[178:181], v[122:125]
	v_mfma_f32_16x16x32_bf16 v[114:117], v[170:173], v[178:181], v[114:117]
	v_mfma_f32_16x16x32_bf16 v[106:109], v[162:165], v[206:209], v[106:109]
	v_mfma_f32_16x16x32_bf16 v[98:101], v[170:173], v[206:209], v[98:101]
	v_mfma_f32_16x16x32_bf16 v[90:93], v[162:165], v[214:217], v[90:93]
	v_mfma_f32_16x16x32_bf16 v[82:85], v[170:173], v[214:217], v[82:85]
	v_mfma_f32_16x16x32_bf16 v[74:77], v[162:165], v[222:225], v[74:77]
	v_mfma_f32_16x16x32_bf16 v[66:69], v[170:173], v[222:225], v[66:69]
	v_mfma_f32_16x16x32_bf16 v[122:125], v[166:169], v[182:185], v[122:125]
	v_mfma_f32_16x16x32_bf16 v[114:117], v[174:177], v[182:185], v[114:117]
	v_mfma_f32_16x16x32_bf16 v[106:109], v[166:169], v[210:213], v[106:109]
	v_mfma_f32_16x16x32_bf16 v[98:101], v[174:177], v[210:213], v[98:101]
	v_mfma_f32_16x16x32_bf16 v[90:93], v[166:169], v[218:221], v[90:93]
	v_mfma_f32_16x16x32_bf16 v[82:85], v[174:177], v[218:221], v[82:85]
	v_mfma_f32_16x16x32_bf16 v[74:77], v[166:169], v[226:229], v[74:77]
	v_mfma_f32_16x16x32_bf16 v[66:69], v[174:177], v[226:229], v[66:69]
	s_barrier
	s_add_i32 s24, 0, 0x1c000
	s_add_i32 s25, s48, s29
	v_add_u32_e32 v205, s24, v143
	v_lshl_add_u64 v[140:141], v[140:141], 0, s[94:95]
	s_mov_b32 m0, s25
	ds_read_b128 v[230:233], v205
	ds_read_b128 v[234:237], v205 offset:1024
	ds_read_b128 v[238:241], v205 offset:2048
	ds_read_b128 v[242:245], v205 offset:3072
	global_load_lds_dwordx4 v[140:141], off
	v_lshl_add_u64 v[140:141], v[186:187], 0, s[94:95]
	s_add_i32 m0, s25, 0x2000
	s_nop 0
	global_load_lds_dwordx4 v[140:141], off
	s_barrier
	s_waitcnt lgkmcnt(0)
	v_mfma_f32_16x16x32_bf16 v[126:129], v[230:233], v[178:181], v[126:129]
	v_mfma_f32_16x16x32_bf16 v[118:121], v[238:241], v[178:181], v[118:121]
	v_mfma_f32_16x16x32_bf16 v[110:113], v[230:233], v[206:209], v[110:113]
	v_mfma_f32_16x16x32_bf16 v[102:105], v[238:241], v[206:209], v[102:105]
	v_mfma_f32_16x16x32_bf16 v[94:97], v[230:233], v[214:217], v[94:97]
	v_mfma_f32_16x16x32_bf16 v[86:89], v[238:241], v[214:217], v[86:89]
	v_mfma_f32_16x16x32_bf16 v[78:81], v[230:233], v[222:225], v[78:81]
	v_mfma_f32_16x16x32_bf16 v[70:73], v[238:241], v[222:225], v[70:73]
	v_mfma_f32_16x16x32_bf16 v[126:129], v[234:237], v[182:185], v[126:129]
	v_mfma_f32_16x16x32_bf16 v[118:121], v[242:245], v[182:185], v[118:121]
	v_mfma_f32_16x16x32_bf16 v[110:113], v[234:237], v[210:213], v[110:113]
	v_mfma_f32_16x16x32_bf16 v[102:105], v[242:245], v[210:213], v[102:105]
	v_mfma_f32_16x16x32_bf16 v[94:97], v[234:237], v[218:221], v[94:97]
	v_mfma_f32_16x16x32_bf16 v[86:89], v[242:245], v[218:221], v[86:89]
	v_mfma_f32_16x16x32_bf16 v[78:81], v[234:237], v[226:229], v[78:81]
	v_mfma_f32_16x16x32_bf16 v[70:73], v[242:245], v[226:229], v[70:73]
	s_barrier
	s_mov_b32 m0, s37
	v_lshl_add_u64 v[140:141], v[246:247], 0, s[94:95]
	ds_read_b128 v[178:181], v145 offset:49152
	ds_read_b128 v[182:185], v145 offset:50176
	ds_read_b128 v[206:209], v145 offset:51200
	ds_read_b128 v[210:213], v145 offset:52224
	ds_read_b128 v[214:217], v145 offset:53248
	ds_read_b128 v[218:221], v145 offset:54272
	ds_read_b128 v[222:225], v145 offset:55296
	ds_read_b128 v[226:229], v145 offset:56320
	global_load_lds_dwordx4 v[140:141], off
	v_lshl_add_u64 v[140:141], v[248:249], 0, s[94:95]
	s_mov_b32 m0, s40
	s_nop 0
	global_load_lds_dwordx4 v[140:141], off
	s_barrier
	s_waitcnt lgkmcnt(0)
	v_mfma_f32_16x16x32_bf16 v[58:61], v[162:165], v[178:181], v[58:61]
	v_mfma_f32_16x16x32_bf16 v[50:53], v[170:173], v[178:181], v[50:53]
	v_mfma_f32_16x16x32_bf16 v[42:45], v[162:165], v[206:209], v[42:45]
	v_mfma_f32_16x16x32_bf16 v[34:37], v[170:173], v[206:209], v[34:37]
	v_mfma_f32_16x16x32_bf16 v[26:29], v[162:165], v[214:217], v[26:29]
	v_mfma_f32_16x16x32_bf16 v[18:21], v[170:173], v[214:217], v[18:21]
	v_mfma_f32_16x16x32_bf16 v[10:13], v[162:165], v[222:225], v[10:13]
	v_mfma_f32_16x16x32_bf16 v[6:9], v[170:173], v[222:225], v[6:9]
	v_mfma_f32_16x16x32_bf16 v[58:61], v[166:169], v[182:185], v[58:61]
	v_mfma_f32_16x16x32_bf16 v[50:53], v[174:177], v[182:185], v[50:53]
	v_mfma_f32_16x16x32_bf16 v[42:45], v[166:169], v[210:213], v[42:45]
	v_mfma_f32_16x16x32_bf16 v[34:37], v[174:177], v[210:213], v[34:37]
	v_mfma_f32_16x16x32_bf16 v[26:29], v[166:169], v[218:221], v[26:29]
	v_mfma_f32_16x16x32_bf16 v[18:21], v[174:177], v[218:221], v[18:21]
	v_mfma_f32_16x16x32_bf16 v[10:13], v[166:169], v[226:229], v[10:13]
	v_mfma_f32_16x16x32_bf16 v[6:9], v[174:177], v[226:229], v[6:9]
	s_barrier
	s_add_u32 s22, s22, 0x40080
	s_addc_u32 s23, s23, 0
	s_add_i32 s24, s24, s29
	v_lshl_add_u64 v[140:141], s[22:23], 0, v[0:1]
	s_mov_b32 m0, s24
	s_nop 0
	global_load_lds_dwordx4 v[140:141], off
	v_lshl_add_u64 v[140:141], s[22:23], 0, v[130:131]
	s_add_i32 m0, s24, 0x2000
	s_nop 0
	global_load_lds_dwordx4 v[140:141], off
	s_waitcnt vmcnt(6)
	s_barrier
	v_mfma_f32_16x16x32_bf16 v[62:65], v[230:233], v[178:181], v[62:65]
	v_mfma_f32_16x16x32_bf16 v[54:57], v[238:241], v[178:181], v[54:57]
	v_mfma_f32_16x16x32_bf16 v[46:49], v[230:233], v[206:209], v[46:49]
	v_mfma_f32_16x16x32_bf16 v[38:41], v[238:241], v[206:209], v[38:41]
	v_mfma_f32_16x16x32_bf16 v[30:33], v[230:233], v[214:217], v[30:33]
	v_mfma_f32_16x16x32_bf16 v[22:25], v[238:241], v[214:217], v[22:25]
	v_mfma_f32_16x16x32_bf16 v[14:17], v[230:233], v[222:225], v[14:17]
	v_mfma_f32_16x16x32_bf16 v[2:5], v[238:241], v[222:225], v[2:5]
	v_mfma_f32_16x16x32_bf16 v[62:65], v[234:237], v[182:185], v[62:65]
	v_mfma_f32_16x16x32_bf16 v[54:57], v[242:245], v[182:185], v[54:57]
	v_mfma_f32_16x16x32_bf16 v[46:49], v[234:237], v[210:213], v[46:49]
	v_mfma_f32_16x16x32_bf16 v[38:41], v[242:245], v[210:213], v[38:41]
	v_mfma_f32_16x16x32_bf16 v[30:33], v[234:237], v[218:221], v[30:33]
	v_mfma_f32_16x16x32_bf16 v[22:25], v[242:245], v[218:221], v[22:25]
	v_mfma_f32_16x16x32_bf16 v[14:17], v[234:237], v[226:229], v[14:17]
	v_mfma_f32_16x16x32_bf16 v[2:5], v[242:245], v[226:229], v[2:5]
	s_barrier
	s_add_i32 s47, s47, 2
	s_add_u32 s20, s20, 0x100
	s_addc_u32 s21, s21, 0
	s_add_u32 s45, s45, 0x100
	s_addc_u32 s46, s46, 0
	s_cmp_gt_u32 s47, 13
	s_cbranch_scc0 .LBB0_586
	v_pk_mul_f32 v[164:165], v[122:123], s[4:5] op_sel_hi:[1,0]
	v_pk_mul_f32 v[122:123], v[122:123], v[126:127]
	v_pk_mul_f32 v[126:127], v[114:115], s[4:5] op_sel_hi:[1,0]
	v_pk_mul_f32 v[114:115], v[114:115], v[118:119]
	v_exp_f32_e32 v126, v126
	v_exp_f32_e32 v127, v127
	v_pk_mul_f32 v[128:129], v[124:125], v[128:129]
	v_pk_mul_f32 v[124:125], v[124:125], s[4:5] op_sel_hi:[1,0]
	v_exp_f32_e32 v164, v164
	v_pk_add_f32 v[126:127], v[126:127], 1.0 op_sel_hi:[1,0]
	v_exp_f32_e32 v165, v165
	v_rcp_f32_e32 v126, v126
	v_rcp_f32_e32 v127, v127
	v_exp_f32_e32 v124, v124
	v_exp_f32_e32 v125, v125
	v_pk_add_f32 v[164:165], v[164:165], 1.0 op_sel_hi:[1,0]
	v_pk_mul_f32 v[118:119], v[126:127], v[114:115]
	v_pk_mul_f32 v[114:115], v[116:117], s[4:5] op_sel_hi:[1,0]
	v_pk_add_f32 v[124:125], v[124:125], 1.0 op_sel_hi:[1,0]
	v_exp_f32_e32 v114, v114
	v_exp_f32_e32 v115, v115
	v_rcp_f32_e32 v164, v164
	v_rcp_f32_e32 v165, v165
	v_rcp_f32_e32 v124, v124
	v_pk_add_f32 v[114:115], v[114:115], 1.0 op_sel_hi:[1,0]
	v_rcp_f32_e32 v125, v125
	v_rcp_f32_e32 v114, v114
	v_rcp_f32_e32 v115, v115
	v_lshl_or_b32 v140, s42, 7, v144
	v_ashrrev_i32_e32 v141, 31, v140
	v_lshl_add_u32 v162, s2, 8, v142
	v_lshl_add_u64 v[140:141], v[140:141], 1, s[14:15]
	v_pk_mul_f32 v[120:121], v[116:117], v[120:121]
	v_pk_mul_f32 v[122:123], v[164:165], v[122:123]
	v_pk_mul_f32 v[124:125], v[124:125], v[128:129]
	v_pk_mul_f32 v[120:121], v[114:115], v[120:121]
	v_mad_i64_i32 v[126:127], s[20:21], v162, s91, v[140:141]
	v_cvt_pk_bf16_f32 v114, v122, v123
	v_cvt_pk_bf16_f32 v115, v124, v125
	v_cvt_pk_bf16_f32 v116, v118, v119
	v_cvt_pk_bf16_f32 v117, v120, v121
	global_store_dwordx4 v[126:127], v[114:117], off
	v_pk_mul_f32 v[112:113], v[108:109], v[112:113]
	v_pk_mul_f32 v[108:109], v[108:109], s[4:5] op_sel_hi:[1,0]
	v_pk_mul_f32 v[114:115], v[106:107], s[4:5] op_sel_hi:[1,0]
	v_pk_mul_f32 v[106:107], v[106:107], v[110:111]
	v_pk_mul_f32 v[110:111], v[98:99], s[4:5] op_sel_hi:[1,0]
	v_pk_mul_f32 v[98:99], v[98:99], v[102:103]
	v_exp_f32_e32 v110, v110
	v_exp_f32_e32 v111, v111
	v_exp_f32_e32 v114, v114
	v_exp_f32_e32 v115, v115
	v_exp_f32_e32 v108, v108
	v_pk_add_f32 v[110:111], v[110:111], 1.0 op_sel_hi:[1,0]
	v_exp_f32_e32 v109, v109
	v_rcp_f32_e32 v110, v110
	v_rcp_f32_e32 v111, v111
	v_pk_add_f32 v[114:115], v[114:115], 1.0 op_sel_hi:[1,0]
	v_pk_add_f32 v[108:109], v[108:109], 1.0 op_sel_hi:[1,0]
	v_rcp_f32_e32 v114, v114
	v_pk_mul_f32 v[102:103], v[110:111], v[98:99]
	v_pk_mul_f32 v[98:99], v[100:101], s[4:5] op_sel_hi:[1,0]
	v_rcp_f32_e32 v115, v115
	v_exp_f32_e32 v98, v98
	v_exp_f32_e32 v99, v99
	v_rcp_f32_e32 v108, v108
	v_rcp_f32_e32 v109, v109
	v_or_b32_e32 v116, 16, v162
	v_pk_add_f32 v[98:99], v[98:99], 1.0 op_sel_hi:[1,0]
	v_pk_mul_f32 v[104:105], v[100:101], v[104:105]
	v_rcp_f32_e32 v98, v98
	v_rcp_f32_e32 v99, v99
	v_pk_mul_f32 v[106:107], v[114:115], v[106:107]
	v_pk_mul_f32 v[108:109], v[108:109], v[112:113]
	v_mad_i64_i32 v[110:111], s[20:21], v116, s91, v[140:141]
	v_pk_mul_f32 v[104:105], v[98:99], v[104:105]
	v_cvt_pk_bf16_f32 v98, v106, v107
	v_cvt_pk_bf16_f32 v99, v108, v109
	v_cvt_pk_bf16_f32 v100, v102, v103
	v_pk_mul_f32 v[96:97], v[92:93], v[96:97]
	v_cvt_pk_bf16_f32 v101, v104, v105
	global_store_dwordx4 v[110:111], v[98:101], off
	v_pk_mul_f32 v[92:93], v[92:93], s[4:5] op_sel_hi:[1,0]
	v_pk_mul_f32 v[88:89], v[84:85], v[88:89]
	v_pk_mul_f32 v[98:99], v[90:91], s[4:5] op_sel_hi:[1,0]
	v_pk_mul_f32 v[90:91], v[90:91], v[94:95]
	v_pk_mul_f32 v[94:95], v[82:83], s[4:5] op_sel_hi:[1,0]
	v_pk_mul_f32 v[82:83], v[82:83], v[86:87]
	v_exp_f32_e32 v94, v94
	v_exp_f32_e32 v95, v95
	v_exp_f32_e32 v98, v98
	v_exp_f32_e32 v99, v99
	v_exp_f32_e32 v92, v92
	v_pk_add_f32 v[94:95], v[94:95], 1.0 op_sel_hi:[1,0]
	v_exp_f32_e32 v93, v93
	v_rcp_f32_e32 v94, v94
	v_rcp_f32_e32 v95, v95
	v_pk_add_f32 v[98:99], v[98:99], 1.0 op_sel_hi:[1,0]
	v_pk_add_f32 v[92:93], v[92:93], 1.0 op_sel_hi:[1,0]
	v_rcp_f32_e32 v98, v98
	v_pk_mul_f32 v[86:87], v[94:95], v[82:83]
	v_pk_mul_f32 v[82:83], v[84:85], s[4:5] op_sel_hi:[1,0]
	v_rcp_f32_e32 v99, v99
	v_exp_f32_e32 v82, v82
	v_exp_f32_e32 v83, v83
	v_rcp_f32_e32 v92, v92
	v_rcp_f32_e32 v93, v93
	v_or_b32_e32 v100, 32, v162
	v_pk_add_f32 v[82:83], v[82:83], 1.0 op_sel_hi:[1,0]
	v_pk_mul_f32 v[90:91], v[98:99], v[90:91]
	v_rcp_f32_e32 v82, v82
	v_rcp_f32_e32 v83, v83
	v_pk_mul_f32 v[92:93], v[92:93], v[96:97]
	v_mad_i64_i32 v[94:95], s[20:21], v100, s91, v[140:141]
	v_pk_mul_f32 v[88:89], v[82:83], v[88:89]
	v_cvt_pk_bf16_f32 v82, v90, v91
	v_cvt_pk_bf16_f32 v83, v92, v93
	v_cvt_pk_bf16_f32 v84, v86, v87
	v_pk_mul_f32 v[80:81], v[76:77], v[80:81]
	v_cvt_pk_bf16_f32 v85, v88, v89
	global_store_dwordx4 v[94:95], v[82:85], off
	v_pk_mul_f32 v[76:77], v[76:77], s[4:5] op_sel_hi:[1,0]
	v_pk_mul_f32 v[72:73], v[68:69], v[72:73]
	v_pk_mul_f32 v[82:83], v[74:75], s[4:5] op_sel_hi:[1,0]
	v_pk_mul_f32 v[74:75], v[74:75], v[78:79]
	v_pk_mul_f32 v[78:79], v[66:67], s[4:5] op_sel_hi:[1,0]
	v_pk_mul_f32 v[66:67], v[66:67], v[70:71]
	v_exp_f32_e32 v78, v78
	v_exp_f32_e32 v79, v79
	v_exp_f32_e32 v82, v82
	v_exp_f32_e32 v83, v83
	v_exp_f32_e32 v76, v76
	v_pk_add_f32 v[78:79], v[78:79], 1.0 op_sel_hi:[1,0]
	v_exp_f32_e32 v77, v77
	v_rcp_f32_e32 v78, v78
	v_rcp_f32_e32 v79, v79
	v_pk_add_f32 v[82:83], v[82:83], 1.0 op_sel_hi:[1,0]
	v_pk_add_f32 v[76:77], v[76:77], 1.0 op_sel_hi:[1,0]
	v_rcp_f32_e32 v82, v82
	v_pk_mul_f32 v[70:71], v[78:79], v[66:67]
	v_pk_mul_f32 v[66:67], v[68:69], s[4:5] op_sel_hi:[1,0]
	v_rcp_f32_e32 v83, v83
	v_exp_f32_e32 v66, v66
	v_exp_f32_e32 v67, v67
	v_rcp_f32_e32 v76, v76
	v_rcp_f32_e32 v77, v77
	v_or_b32_e32 v84, 48, v162
	v_pk_add_f32 v[66:67], v[66:67], 1.0 op_sel_hi:[1,0]
	v_pk_mul_f32 v[74:75], v[82:83], v[74:75]
	v_rcp_f32_e32 v66, v66
	v_rcp_f32_e32 v67, v67
	v_pk_mul_f32 v[76:77], v[76:77], v[80:81]
	v_mad_i64_i32 v[78:79], s[20:21], v84, s91, v[140:141]
	v_pk_mul_f32 v[72:73], v[66:67], v[72:73]
	v_cvt_pk_bf16_f32 v66, v74, v75
	v_cvt_pk_bf16_f32 v67, v76, v77
	v_cvt_pk_bf16_f32 v68, v70, v71
	v_pk_mul_f32 v[64:65], v[60:61], v[64:65]
	v_cvt_pk_bf16_f32 v69, v72, v73
	global_store_dwordx4 v[78:79], v[66:69], off
	v_pk_mul_f32 v[60:61], v[60:61], s[4:5] op_sel_hi:[1,0]
	v_pk_mul_f32 v[56:57], v[52:53], v[56:57]
	v_pk_mul_f32 v[66:67], v[58:59], s[4:5] op_sel_hi:[1,0]
	v_pk_mul_f32 v[58:59], v[58:59], v[62:63]
	v_pk_mul_f32 v[62:63], v[50:51], s[4:5] op_sel_hi:[1,0]
	v_pk_mul_f32 v[50:51], v[50:51], v[54:55]
	v_exp_f32_e32 v62, v62
	v_exp_f32_e32 v63, v63
	v_exp_f32_e32 v66, v66
	v_exp_f32_e32 v67, v67
	v_exp_f32_e32 v60, v60
	v_pk_add_f32 v[62:63], v[62:63], 1.0 op_sel_hi:[1,0]
	v_exp_f32_e32 v61, v61
	v_rcp_f32_e32 v62, v62
	v_rcp_f32_e32 v63, v63
	v_pk_add_f32 v[66:67], v[66:67], 1.0 op_sel_hi:[1,0]
	v_pk_add_f32 v[60:61], v[60:61], 1.0 op_sel_hi:[1,0]
	v_rcp_f32_e32 v66, v66
	v_pk_mul_f32 v[54:55], v[62:63], v[50:51]
	v_pk_mul_f32 v[50:51], v[52:53], s[4:5] op_sel_hi:[1,0]
	v_rcp_f32_e32 v67, v67
	v_exp_f32_e32 v50, v50
	v_exp_f32_e32 v51, v51
	v_rcp_f32_e32 v60, v60
	v_rcp_f32_e32 v61, v61
	v_add_u32_e32 v68, 0x80, v162
	v_pk_add_f32 v[50:51], v[50:51], 1.0 op_sel_hi:[1,0]
	v_pk_mul_f32 v[58:59], v[66:67], v[58:59]
	v_rcp_f32_e32 v50, v50
	v_rcp_f32_e32 v51, v51
	v_pk_mul_f32 v[60:61], v[60:61], v[64:65]
	v_mad_i64_i32 v[62:63], s[20:21], v68, s91, v[140:141]
	v_pk_mul_f32 v[56:57], v[50:51], v[56:57]
	v_cvt_pk_bf16_f32 v50, v58, v59
	v_cvt_pk_bf16_f32 v51, v60, v61
	v_cvt_pk_bf16_f32 v52, v54, v55
	v_pk_mul_f32 v[48:49], v[44:45], v[48:49]
	v_cvt_pk_bf16_f32 v53, v56, v57
	global_store_dwordx4 v[62:63], v[50:53], off
	v_pk_mul_f32 v[44:45], v[44:45], s[4:5] op_sel_hi:[1,0]
	v_pk_mul_f32 v[40:41], v[36:37], v[40:41]
	v_pk_mul_f32 v[50:51], v[42:43], s[4:5] op_sel_hi:[1,0]
	v_pk_mul_f32 v[42:43], v[42:43], v[46:47]
	v_pk_mul_f32 v[46:47], v[34:35], s[4:5] op_sel_hi:[1,0]
	v_pk_mul_f32 v[34:35], v[34:35], v[38:39]
	v_exp_f32_e32 v46, v46
	v_exp_f32_e32 v47, v47
	v_exp_f32_e32 v50, v50
	v_exp_f32_e32 v51, v51
	v_exp_f32_e32 v44, v44
	v_pk_add_f32 v[46:47], v[46:47], 1.0 op_sel_hi:[1,0]
	v_exp_f32_e32 v45, v45
	v_rcp_f32_e32 v46, v46
	v_rcp_f32_e32 v47, v47
	v_pk_add_f32 v[50:51], v[50:51], 1.0 op_sel_hi:[1,0]
	v_pk_add_f32 v[44:45], v[44:45], 1.0 op_sel_hi:[1,0]
	v_rcp_f32_e32 v50, v50
	v_pk_mul_f32 v[38:39], v[46:47], v[34:35]
	v_pk_mul_f32 v[34:35], v[36:37], s[4:5] op_sel_hi:[1,0]
	v_rcp_f32_e32 v51, v51
	v_exp_f32_e32 v34, v34
	v_exp_f32_e32 v35, v35
	v_rcp_f32_e32 v44, v44
	v_rcp_f32_e32 v45, v45
	v_add_u32_e32 v52, 0x90, v162
	v_pk_add_f32 v[34:35], v[34:35], 1.0 op_sel_hi:[1,0]
	v_pk_mul_f32 v[42:43], v[50:51], v[42:43]
	v_rcp_f32_e32 v34, v34
	v_rcp_f32_e32 v35, v35
	v_pk_mul_f32 v[44:45], v[44:45], v[48:49]
	v_mad_i64_i32 v[46:47], s[20:21], v52, s91, v[140:141]
	v_pk_mul_f32 v[40:41], v[34:35], v[40:41]
	v_cvt_pk_bf16_f32 v34, v42, v43
	v_cvt_pk_bf16_f32 v35, v44, v45
	v_cvt_pk_bf16_f32 v36, v38, v39
	v_pk_mul_f32 v[32:33], v[28:29], v[32:33]
	v_cvt_pk_bf16_f32 v37, v40, v41
	global_store_dwordx4 v[46:47], v[34:37], off
	v_pk_mul_f32 v[28:29], v[28:29], s[4:5] op_sel_hi:[1,0]
	v_pk_mul_f32 v[24:25], v[20:21], v[24:25]
	v_pk_mul_f32 v[34:35], v[26:27], s[4:5] op_sel_hi:[1,0]
	v_pk_mul_f32 v[26:27], v[26:27], v[30:31]
	v_pk_mul_f32 v[30:31], v[18:19], s[4:5] op_sel_hi:[1,0]
	v_pk_mul_f32 v[18:19], v[18:19], v[22:23]
	v_exp_f32_e32 v30, v30
	v_exp_f32_e32 v31, v31
	v_exp_f32_e32 v34, v34
	v_exp_f32_e32 v35, v35
	v_exp_f32_e32 v28, v28
	v_pk_add_f32 v[30:31], v[30:31], 1.0 op_sel_hi:[1,0]
	v_exp_f32_e32 v29, v29
	v_rcp_f32_e32 v30, v30
	v_rcp_f32_e32 v31, v31
	v_pk_add_f32 v[34:35], v[34:35], 1.0 op_sel_hi:[1,0]
	v_pk_add_f32 v[28:29], v[28:29], 1.0 op_sel_hi:[1,0]
	v_rcp_f32_e32 v34, v34
	v_pk_mul_f32 v[22:23], v[30:31], v[18:19]
	v_pk_mul_f32 v[18:19], v[20:21], s[4:5] op_sel_hi:[1,0]
	v_rcp_f32_e32 v35, v35
	v_exp_f32_e32 v18, v18
	v_exp_f32_e32 v19, v19
	v_rcp_f32_e32 v28, v28
	v_rcp_f32_e32 v29, v29
	v_add_u32_e32 v36, 0xa0, v162
	v_pk_add_f32 v[18:19], v[18:19], 1.0 op_sel_hi:[1,0]
	v_pk_mul_f32 v[26:27], v[34:35], v[26:27]
	v_rcp_f32_e32 v18, v18
	v_rcp_f32_e32 v19, v19
	v_pk_mul_f32 v[28:29], v[28:29], v[32:33]
	v_mad_i64_i32 v[30:31], s[20:21], v36, s91, v[140:141]
	v_pk_mul_f32 v[24:25], v[18:19], v[24:25]
	v_cvt_pk_bf16_f32 v18, v26, v27
	v_cvt_pk_bf16_f32 v19, v28, v29
	v_cvt_pk_bf16_f32 v20, v22, v23
	v_pk_mul_f32 v[2:3], v[6:7], v[2:3]
	v_cvt_pk_bf16_f32 v21, v24, v25
	global_store_dwordx4 v[30:31], v[18:21], off
	v_pk_mul_f32 v[16:17], v[12:13], v[16:17]
	v_pk_mul_f32 v[12:13], v[12:13], s[4:5] op_sel_hi:[1,0]
	v_pk_mul_f32 v[18:19], v[10:11], s[4:5] op_sel_hi:[1,0]
	v_pk_mul_f32 v[10:11], v[10:11], v[14:15]
	v_pk_mul_f32 v[14:15], v[6:7], s[4:5] op_sel_hi:[1,0]
	v_exp_f32_e32 v18, v18
	v_exp_f32_e32 v14, v14
	v_exp_f32_e32 v15, v15
	v_exp_f32_e32 v19, v19
	v_exp_f32_e32 v12, v12
	v_exp_f32_e32 v13, v13
	v_pk_add_f32 v[14:15], v[14:15], 1.0 op_sel_hi:[1,0]
	v_pk_add_f32 v[18:19], v[18:19], 1.0 op_sel_hi:[1,0]
	v_rcp_f32_e32 v14, v14
	v_rcp_f32_e32 v15, v15
	v_pk_add_f32 v[12:13], v[12:13], 1.0 op_sel_hi:[1,0]
	v_rcp_f32_e32 v18, v18
	v_rcp_f32_e32 v19, v19
	v_pk_mul_f32 v[6:7], v[14:15], v[2:3]
	v_pk_mul_f32 v[2:3], v[8:9], s[4:5] op_sel_hi:[1,0]
	v_rcp_f32_e32 v12, v12
	v_exp_f32_e32 v2, v2
	v_exp_f32_e32 v3, v3
	v_rcp_f32_e32 v13, v13
	v_add_u32_e32 v20, 0xb0, v162
	v_mad_i64_i32 v[14:15], s[20:21], v20, s91, v[140:141]
	v_pk_add_f32 v[2:3], v[2:3], 1.0 op_sel_hi:[1,0]
	v_pk_mul_f32 v[4:5], v[8:9], v[4:5]
	v_rcp_f32_e32 v2, v2
	v_rcp_f32_e32 v3, v3
	s_and_b64 vcc, exec, s[38:39]
	s_mov_b32 s42, s0
	s_mov_b32 s2, s8
	s_mov_b64 s[22:23], s[18:19]
	s_mov_b64 s[20:21], s[16:17]
	v_pk_mul_f32 v[10:11], v[18:19], v[10:11]
	v_pk_mul_f32 v[12:13], v[12:13], v[16:17]
	v_pk_mul_f32 v[8:9], v[2:3], v[4:5]
	v_cvt_pk_bf16_f32 v2, v10, v11
	v_cvt_pk_bf16_f32 v3, v12, v13
	v_cvt_pk_bf16_f32 v4, v6, v7
	s_nop 0
	v_cvt_pk_bf16_f32 v5, v8, v9
	global_store_dwordx4 v[14:15], v[2:5], off
	s_cbranch_vccz .LBB0_579
	s_waitcnt vmcnt(0)
	s_cmpk_gt_u32 s26, 0xff
	s_cbranch_scc1 .LBB0_590
	s_barrier
